# pair-order MFMAs + mid setprio/lgkmcnt stripped + barrier before last 2 MFMAs at prio 3
# speedup vs baseline: 1.0129x; 1.0064x over previous
.LBB0_120:
	ds_read_b128 v[128:131], v178
	ds_read_b128 v[132:135], v178 offset:1024
	ds_read_b128 v[154:157], v178 offset:2048
	ds_read_b128 v[158:161], v178 offset:3072
	ds_read_b128 v[162:165], v179
	ds_read_b128 v[166:169], v179 offset:1024
	ds_read_b128 v[182:185], v179 offset:2048
	ds_read_b128 v[186:189], v179 offset:3072
	s_add_u32 s67, s88, 0xfffc0080
	s_addc_u32 s68, s89, -1
	s_cmp_eq_u32 s66, 12
	s_cselect_b32 s93, s52, s68
	s_cselect_b32 s92, s53, s67
	s_cselect_b32 s91, s56, s59
	s_cselect_b32 s90, s57, s58
	v_lshl_add_u64 v[170:171], s[88:89], 0, v[144:145]
	s_add_i32 m0, s17, 0xc000
	ds_read_b128 v[190:193], v180
	ds_read_b128 v[194:197], v180 offset:1024
	ds_read_b128 v[198:201], v180 offset:2048
	ds_read_b128 v[202:205], v180 offset:3072
	ds_read_b128 v[206:209], v180 offset:4096
	ds_read_b128 v[210:213], v180 offset:5120
	ds_read_b128 v[214:217], v180 offset:6144
	ds_read_b128 v[218:221], v180 offset:7168
	global_load_lds_dwordx4 v[170:171], off
	v_lshl_add_u64 v[170:171], s[88:89], 0, v[148:149]
	s_add_i32 m0, s17, 0xe000
	s_nop 0
	global_load_lds_dwordx4 v[170:171], off
	s_waitcnt vmcnt(8)
	s_waitcnt lgkmcnt(0)
	s_barrier
	s_setprio 1
	v_mfma_f32_16x16x32_bf16 v[124:127], v[128:131], v[190:193], v[124:127]
	v_mfma_f32_16x16x32_bf16 v[124:127], v[132:135], v[194:197], v[124:127]
	v_mfma_f32_16x16x32_bf16 v[116:119], v[154:157], v[190:193], v[116:119]
	v_mfma_f32_16x16x32_bf16 v[116:119], v[158:161], v[194:197], v[116:119]
	v_mfma_f32_16x16x32_bf16 v[108:111], v[128:131], v[198:201], v[108:111]
	v_mfma_f32_16x16x32_bf16 v[108:111], v[132:135], v[202:205], v[108:111]
	v_mfma_f32_16x16x32_bf16 v[100:103], v[154:157], v[198:201], v[100:103]
	v_mfma_f32_16x16x32_bf16 v[100:103], v[158:161], v[202:205], v[100:103]
	v_mfma_f32_16x16x32_bf16 v[92:95], v[128:131], v[206:209], v[92:95]
	v_mfma_f32_16x16x32_bf16 v[92:95], v[132:135], v[210:213], v[92:95]
	v_mfma_f32_16x16x32_bf16 v[84:87], v[154:157], v[206:209], v[84:87]
	v_mfma_f32_16x16x32_bf16 v[84:87], v[158:161], v[210:213], v[84:87]
	v_mfma_f32_16x16x32_bf16 v[76:79], v[128:131], v[214:217], v[76:79]
	v_mfma_f32_16x16x32_bf16 v[76:79], v[132:135], v[218:221], v[76:79]
	v_mfma_f32_16x16x32_bf16 v[68:71], v[154:157], v[214:217], v[68:71]
	v_mfma_f32_16x16x32_bf16 v[68:71], v[158:161], v[218:221], v[68:71]
	v_mfma_f32_16x16x32_bf16 v[120:123], v[162:165], v[190:193], v[120:123]
	v_mfma_f32_16x16x32_bf16 v[120:123], v[166:169], v[194:197], v[120:123]
	v_mfma_f32_16x16x32_bf16 v[112:115], v[182:185], v[190:193], v[112:115]
	v_mfma_f32_16x16x32_bf16 v[112:115], v[186:189], v[194:197], v[112:115]
	v_mfma_f32_16x16x32_bf16 v[104:107], v[162:165], v[198:201], v[104:107]
	v_mfma_f32_16x16x32_bf16 v[104:107], v[166:169], v[202:205], v[104:107]
	v_mfma_f32_16x16x32_bf16 v[96:99], v[182:185], v[198:201], v[96:99]
	v_mfma_f32_16x16x32_bf16 v[96:99], v[186:189], v[202:205], v[96:99]
	v_mfma_f32_16x16x32_bf16 v[88:91], v[162:165], v[206:209], v[88:91]
	v_mfma_f32_16x16x32_bf16 v[88:91], v[166:169], v[210:213], v[88:91]
	v_mfma_f32_16x16x32_bf16 v[80:83], v[182:185], v[206:209], v[80:83]
	v_mfma_f32_16x16x32_bf16 v[80:83], v[186:189], v[210:213], v[80:83]
	v_mfma_f32_16x16x32_bf16 v[72:75], v[162:165], v[214:217], v[72:75]
	v_mfma_f32_16x16x32_bf16 v[72:75], v[166:169], v[218:221], v[72:75]
	s_setprio 3
	s_barrier
	v_mfma_f32_16x16x32_bf16 v[64:67], v[182:185], v[214:217], v[64:67]
	v_mfma_f32_16x16x32_bf16 v[64:67], v[186:189], v[218:221], v[64:67]
	s_setprio 0
	s_add_i32 s67, s25, s16
	v_lshl_add_u64 v[170:171], s[90:91], 0, v[140:141]
	s_mov_b32 m0, s67
	ds_read_b128 v[190:193], v180 offset:16384
	ds_read_b128 v[194:197], v180 offset:17408
	ds_read_b128 v[198:201], v180 offset:18432
	ds_read_b128 v[202:205], v180 offset:19456
	ds_read_b128 v[206:209], v180 offset:20480
	ds_read_b128 v[210:213], v180 offset:21504
	ds_read_b128 v[214:217], v180 offset:22528
	ds_read_b128 v[218:221], v180 offset:23552
	global_load_lds_dwordx4 v[170:171], off
	s_add_i32 m0, s67, 0x2000
	s_add_u32 s68, s90, 0x40000
	v_lshl_add_u64 v[222:223], s[90:91], 0, v[136:137]
	s_addc_u32 s69, s91, 0
	s_add_i32 s67, s26, s16
	global_load_lds_dwordx4 v[222:223], off
	v_lshl_add_u64 v[224:225], s[68:69], 0, v[140:141]
	s_mov_b32 m0, s67
	v_lshl_add_u64 v[226:227], s[92:93], 0, v[138:139]
	global_load_lds_dwordx4 v[224:225], off
	v_lshl_add_u64 v[224:225], s[68:69], 0, v[136:137]
	s_add_i32 m0, s67, 0x2000
	s_nop 0
	global_load_lds_dwordx4 v[224:225], off
	v_lshl_add_u64 v[224:225], s[92:93], 0, v[142:143]
	s_mov_b32 m0, s17
	s_nop 0
	global_load_lds_dwordx4 v[224:225], off
	s_mov_b32 m0, s18
	s_nop 0
	global_load_lds_dwordx4 v[226:227], off
	s_waitcnt vmcnt(8)
	s_waitcnt lgkmcnt(0)
	s_barrier
	s_setprio 1
	v_mfma_f32_16x16x32_bf16 v[60:63], v[128:131], v[190:193], v[60:63]
	v_mfma_f32_16x16x32_bf16 v[60:63], v[132:135], v[194:197], v[60:63]
	v_mfma_f32_16x16x32_bf16 v[52:55], v[154:157], v[190:193], v[52:55]
	v_mfma_f32_16x16x32_bf16 v[52:55], v[158:161], v[194:197], v[52:55]
	v_mfma_f32_16x16x32_bf16 v[44:47], v[128:131], v[198:201], v[44:47]
	v_mfma_f32_16x16x32_bf16 v[44:47], v[132:135], v[202:205], v[44:47]
	v_mfma_f32_16x16x32_bf16 v[36:39], v[154:157], v[198:201], v[36:39]
	v_mfma_f32_16x16x32_bf16 v[36:39], v[158:161], v[202:205], v[36:39]
	v_mfma_f32_16x16x32_bf16 v[28:31], v[128:131], v[206:209], v[28:31]
	v_mfma_f32_16x16x32_bf16 v[28:31], v[132:135], v[210:213], v[28:31]
	v_mfma_f32_16x16x32_bf16 v[20:23], v[154:157], v[206:209], v[20:23]
	v_mfma_f32_16x16x32_bf16 v[20:23], v[158:161], v[210:213], v[20:23]
	v_mfma_f32_16x16x32_bf16 v[12:15], v[128:131], v[214:217], v[12:15]
	v_mfma_f32_16x16x32_bf16 v[12:15], v[132:135], v[218:221], v[12:15]
	v_mfma_f32_16x16x32_bf16 v[4:7], v[154:157], v[214:217], v[4:7]
	v_mfma_f32_16x16x32_bf16 v[4:7], v[158:161], v[218:221], v[4:7]
	v_mfma_f32_16x16x32_bf16 v[56:59], v[162:165], v[190:193], v[56:59]
	v_mfma_f32_16x16x32_bf16 v[56:59], v[166:169], v[194:197], v[56:59]
	v_mfma_f32_16x16x32_bf16 v[48:51], v[182:185], v[190:193], v[48:51]
	v_mfma_f32_16x16x32_bf16 v[48:51], v[186:189], v[194:197], v[48:51]
	v_mfma_f32_16x16x32_bf16 v[40:43], v[162:165], v[198:201], v[40:43]
	v_mfma_f32_16x16x32_bf16 v[40:43], v[166:169], v[202:205], v[40:43]
	v_mfma_f32_16x16x32_bf16 v[32:35], v[182:185], v[198:201], v[32:35]
	v_mfma_f32_16x16x32_bf16 v[32:35], v[186:189], v[202:205], v[32:35]
	v_mfma_f32_16x16x32_bf16 v[24:27], v[162:165], v[206:209], v[24:27]
	v_mfma_f32_16x16x32_bf16 v[24:27], v[166:169], v[210:213], v[24:27]
	v_mfma_f32_16x16x32_bf16 v[16:19], v[182:185], v[206:209], v[16:19]
	v_mfma_f32_16x16x32_bf16 v[16:19], v[186:189], v[210:213], v[16:19]
	v_mfma_f32_16x16x32_bf16 v[8:11], v[162:165], v[214:217], v[8:11]
	v_mfma_f32_16x16x32_bf16 v[8:11], v[166:169], v[218:221], v[8:11]
	s_setprio 3
	s_barrier
	v_mfma_f32_16x16x32_bf16 v[0:3], v[182:185], v[214:217], v[0:3]
	v_mfma_f32_16x16x32_bf16 v[0:3], v[186:189], v[218:221], v[0:3]
	s_setprio 0
	s_add_i32 s67, 0, 0x18000
	s_add_i32 s73, 0, 0x1c000
	v_add_u32_e32 v158, s67, v175
	v_add_u32_e32 v186, s73, v175
	ds_read_b128 v[128:131], v158
	ds_read_b128 v[132:135], v158 offset:1024
	ds_read_b128 v[154:157], v158 offset:2048
	ds_read_b128 v[158:161], v158 offset:3072
	ds_read_b128 v[162:165], v186
	ds_read_b128 v[166:169], v186 offset:1024
	ds_read_b128 v[182:185], v186 offset:2048
	ds_read_b128 v[186:189], v186 offset:3072
	s_add_u32 s68, s92, 0x40000
	s_addc_u32 s69, s93, 0
	s_mov_b32 m0, s19
	v_lshl_add_u64 v[228:229], s[68:69], 0, v[142:143]
	ds_read_b128 v[190:193], v180 offset:32768
	ds_read_b128 v[194:197], v180 offset:33792
	ds_read_b128 v[198:201], v180 offset:34816
	ds_read_b128 v[202:205], v180 offset:35840
	ds_read_b128 v[206:209], v180 offset:36864
	ds_read_b128 v[210:213], v180 offset:37888
	ds_read_b128 v[214:217], v180 offset:38912
	ds_read_b128 v[218:221], v180 offset:39936
	global_load_lds_dwordx4 v[228:229], off
	v_lshl_add_u64 v[228:229], s[68:69], 0, v[138:139]
	s_mov_b32 m0, s20
	s_nop 0
	global_load_lds_dwordx4 v[228:229], off
	s_waitcnt vmcnt(8)
	s_waitcnt lgkmcnt(0)
	s_barrier
	s_setprio 1
	v_mfma_f32_16x16x32_bf16 v[124:127], v[128:131], v[190:193], v[124:127]
	v_mfma_f32_16x16x32_bf16 v[124:127], v[132:135], v[194:197], v[124:127]
	v_mfma_f32_16x16x32_bf16 v[116:119], v[154:157], v[190:193], v[116:119]
	v_mfma_f32_16x16x32_bf16 v[116:119], v[158:161], v[194:197], v[116:119]
	v_mfma_f32_16x16x32_bf16 v[108:111], v[128:131], v[198:201], v[108:111]
	v_mfma_f32_16x16x32_bf16 v[108:111], v[132:135], v[202:205], v[108:111]
	v_mfma_f32_16x16x32_bf16 v[100:103], v[154:157], v[198:201], v[100:103]
	v_mfma_f32_16x16x32_bf16 v[100:103], v[158:161], v[202:205], v[100:103]
	v_mfma_f32_16x16x32_bf16 v[92:95], v[128:131], v[206:209], v[92:95]
	v_mfma_f32_16x16x32_bf16 v[92:95], v[132:135], v[210:213], v[92:95]
	v_mfma_f32_16x16x32_bf16 v[84:87], v[154:157], v[206:209], v[84:87]
	v_mfma_f32_16x16x32_bf16 v[84:87], v[158:161], v[210:213], v[84:87]
	v_mfma_f32_16x16x32_bf16 v[76:79], v[128:131], v[214:217], v[76:79]
	v_mfma_f32_16x16x32_bf16 v[76:79], v[132:135], v[218:221], v[76:79]
	v_mfma_f32_16x16x32_bf16 v[68:71], v[154:157], v[214:217], v[68:71]
	v_mfma_f32_16x16x32_bf16 v[68:71], v[158:161], v[218:221], v[68:71]
	v_mfma_f32_16x16x32_bf16 v[120:123], v[162:165], v[190:193], v[120:123]
	v_mfma_f32_16x16x32_bf16 v[120:123], v[166:169], v[194:197], v[120:123]
	v_mfma_f32_16x16x32_bf16 v[112:115], v[182:185], v[190:193], v[112:115]
	v_mfma_f32_16x16x32_bf16 v[112:115], v[186:189], v[194:197], v[112:115]
	v_mfma_f32_16x16x32_bf16 v[104:107], v[162:165], v[198:201], v[104:107]
	v_mfma_f32_16x16x32_bf16 v[104:107], v[166:169], v[202:205], v[104:107]
	v_mfma_f32_16x16x32_bf16 v[96:99], v[182:185], v[198:201], v[96:99]
	v_mfma_f32_16x16x32_bf16 v[96:99], v[186:189], v[202:205], v[96:99]
	v_mfma_f32_16x16x32_bf16 v[88:91], v[162:165], v[206:209], v[88:91]
	v_mfma_f32_16x16x32_bf16 v[88:91], v[166:169], v[210:213], v[88:91]
	v_mfma_f32_16x16x32_bf16 v[80:83], v[182:185], v[206:209], v[80:83]
	v_mfma_f32_16x16x32_bf16 v[80:83], v[186:189], v[210:213], v[80:83]
	v_mfma_f32_16x16x32_bf16 v[72:75], v[162:165], v[214:217], v[72:75]
	v_mfma_f32_16x16x32_bf16 v[72:75], v[166:169], v[218:221], v[72:75]
	s_setprio 3
	s_barrier
	v_mfma_f32_16x16x32_bf16 v[64:67], v[182:185], v[214:217], v[64:67]
	v_mfma_f32_16x16x32_bf16 v[64:67], v[186:189], v[218:221], v[64:67]
	s_setprio 0
	s_add_i32 s67, s67, s16
	v_lshl_add_u64 v[170:171], v[170:171], 0, s[74:75]
	s_mov_b32 m0, s67
	ds_read_b128 v[190:193], v180 offset:49152
	ds_read_b128 v[194:197], v180 offset:50176
	ds_read_b128 v[198:201], v180 offset:51200
	ds_read_b128 v[202:205], v180 offset:52224
	ds_read_b128 v[206:209], v180 offset:53248
	ds_read_b128 v[210:213], v180 offset:54272
	ds_read_b128 v[214:217], v180 offset:55296
	ds_read_b128 v[218:221], v180 offset:56320
	global_load_lds_dwordx4 v[170:171], off
	s_add_i32 m0, s67, 0x2000
	s_add_u32 s68, s90, 0x40080
	v_lshl_add_u64 v[170:171], v[222:223], 0, s[74:75]
	s_addc_u32 s69, s91, 0
	s_add_i32 s67, s73, s16
	global_load_lds_dwordx4 v[170:171], off
	v_lshl_add_u64 v[170:171], s[68:69], 0, v[140:141]
	s_mov_b32 m0, s67
	s_nop 0
	global_load_lds_dwordx4 v[170:171], off
	v_lshl_add_u64 v[170:171], s[68:69], 0, v[136:137]
	s_add_i32 m0, s67, 0x2000
	s_nop 0
	global_load_lds_dwordx4 v[170:171], off
	v_lshl_add_u64 v[170:171], v[224:225], 0, s[74:75]
	s_mov_b32 m0, s23
	s_nop 0
	global_load_lds_dwordx4 v[170:171], off
	v_lshl_add_u64 v[170:171], v[226:227], 0, s[74:75]
	s_mov_b32 m0, s24
	s_nop 0
	global_load_lds_dwordx4 v[170:171], off
	s_waitcnt vmcnt(8)
	s_waitcnt lgkmcnt(0)
	s_barrier
	s_setprio 1
	v_mfma_f32_16x16x32_bf16 v[60:63], v[128:131], v[190:193], v[60:63]
	v_mfma_f32_16x16x32_bf16 v[60:63], v[132:135], v[194:197], v[60:63]
	v_mfma_f32_16x16x32_bf16 v[52:55], v[154:157], v[190:193], v[52:55]
	v_mfma_f32_16x16x32_bf16 v[52:55], v[158:161], v[194:197], v[52:55]
	v_mfma_f32_16x16x32_bf16 v[44:47], v[128:131], v[198:201], v[44:47]
	v_mfma_f32_16x16x32_bf16 v[44:47], v[132:135], v[202:205], v[44:47]
	v_mfma_f32_16x16x32_bf16 v[36:39], v[154:157], v[198:201], v[36:39]
	v_mfma_f32_16x16x32_bf16 v[36:39], v[158:161], v[202:205], v[36:39]
	v_mfma_f32_16x16x32_bf16 v[28:31], v[128:131], v[206:209], v[28:31]
	v_mfma_f32_16x16x32_bf16 v[28:31], v[132:135], v[210:213], v[28:31]
	v_mfma_f32_16x16x32_bf16 v[20:23], v[154:157], v[206:209], v[20:23]
	v_mfma_f32_16x16x32_bf16 v[20:23], v[158:161], v[210:213], v[20:23]
	v_mfma_f32_16x16x32_bf16 v[12:15], v[128:131], v[214:217], v[12:15]
	v_mfma_f32_16x16x32_bf16 v[12:15], v[132:135], v[218:221], v[12:15]
	v_mfma_f32_16x16x32_bf16 v[4:7], v[154:157], v[214:217], v[4:7]
	v_mfma_f32_16x16x32_bf16 v[4:7], v[158:161], v[218:221], v[4:7]
	v_mfma_f32_16x16x32_bf16 v[56:59], v[162:165], v[190:193], v[56:59]
	v_mfma_f32_16x16x32_bf16 v[56:59], v[166:169], v[194:197], v[56:59]
	v_mfma_f32_16x16x32_bf16 v[48:51], v[182:185], v[190:193], v[48:51]
	v_mfma_f32_16x16x32_bf16 v[48:51], v[186:189], v[194:197], v[48:51]
	v_mfma_f32_16x16x32_bf16 v[40:43], v[162:165], v[198:201], v[40:43]
	v_mfma_f32_16x16x32_bf16 v[40:43], v[166:169], v[202:205], v[40:43]
	v_mfma_f32_16x16x32_bf16 v[32:35], v[182:185], v[198:201], v[32:35]
	v_mfma_f32_16x16x32_bf16 v[32:35], v[186:189], v[202:205], v[32:35]
	v_mfma_f32_16x16x32_bf16 v[24:27], v[162:165], v[206:209], v[24:27]
	v_mfma_f32_16x16x32_bf16 v[24:27], v[166:169], v[210:213], v[24:27]
	v_mfma_f32_16x16x32_bf16 v[16:19], v[182:185], v[206:209], v[16:19]
	v_mfma_f32_16x16x32_bf16 v[16:19], v[186:189], v[210:213], v[16:19]
	v_mfma_f32_16x16x32_bf16 v[8:11], v[162:165], v[214:217], v[8:11]
	v_mfma_f32_16x16x32_bf16 v[8:11], v[166:169], v[218:221], v[8:11]
	s_setprio 3
	s_barrier
	v_mfma_f32_16x16x32_bf16 v[0:3], v[182:185], v[214:217], v[0:3]
	v_mfma_f32_16x16x32_bf16 v[0:3], v[186:189], v[218:221], v[0:3]
	s_setprio 0
	s_add_i32 s66, s66, 2
	s_add_u32 s88, s88, 0x100
	s_addc_u32 s89, s89, 0
	s_add_u32 s58, s58, 0x100
	s_addc_u32 s59, s59, 0
	s_cmp_gt_u32 s66, 13
	s_cbranch_scc0 .LBB0_120
	s_and_b64 vcc, exec, s[76:77]
	s_cbranch_vccz .LBB0_123
	s_barrier

.LBB0_272:
	ds_read_b128 v[120:123], v245
	ds_read_b128 v[124:127], v245 offset:1024
	ds_read_b128 v[128:131], v245 offset:2048
	ds_read_b128 v[132:135], v245 offset:3072
	ds_read_b128 v[144:147], v246
	ds_read_b128 v[148:151], v246 offset:1024
	ds_read_b128 v[152:155], v246 offset:2048
	ds_read_b128 v[156:159], v246 offset:3072
	s_add_u32 s59, s86, 0xfff50080
	s_addc_u32 s66, s87, -1
	s_cmp_eq_u32 s58, 40
	s_cselect_b32 s91, s11, s66
	s_cselect_b32 s90, s10, s59
	s_cselect_b32 s89, s85, s57
	s_cselect_b32 s88, s84, s56
	v_lshl_add_u64 v[204:205], s[86:87], 0, v[200:201]
	s_add_i32 m0, s16, 0xc000
	ds_read_b128 v[160:163], v247
	ds_read_b128 v[164:167], v247 offset:1024
	ds_read_b128 v[168:171], v247 offset:2048
	ds_read_b128 v[172:175], v247 offset:3072
	ds_read_b128 v[176:179], v247 offset:4096
	ds_read_b128 v[180:183], v247 offset:5120
	ds_read_b128 v[184:187], v247 offset:6144
	ds_read_b128 v[188:191], v247 offset:7168
	global_load_lds_dwordx4 v[204:205], off
	v_lshl_add_u64 v[204:205], s[86:87], 0, v[202:203]
	s_add_i32 m0, s16, 0xe000
	s_nop 0
	global_load_lds_dwordx4 v[204:205], off
	s_waitcnt vmcnt(8)
	s_waitcnt lgkmcnt(0)
	s_barrier
	s_setprio 1
	v_mfma_f32_16x16x32_bf16 v[140:143], v[120:123], v[160:163], v[140:143]
	v_mfma_f32_16x16x32_bf16 v[140:143], v[124:127], v[164:167], v[140:143]
	v_mfma_f32_16x16x32_bf16 v[136:139], v[128:131], v[160:163], v[136:139]
	v_mfma_f32_16x16x32_bf16 v[136:139], v[132:135], v[164:167], v[136:139]
	v_mfma_f32_16x16x32_bf16 v[108:111], v[120:123], v[168:171], v[108:111]
	v_mfma_f32_16x16x32_bf16 v[108:111], v[124:127], v[172:175], v[108:111]
	v_mfma_f32_16x16x32_bf16 v[104:107], v[128:131], v[168:171], v[104:107]
	v_mfma_f32_16x16x32_bf16 v[104:107], v[132:135], v[172:175], v[104:107]
	v_mfma_f32_16x16x32_bf16 v[92:95], v[120:123], v[176:179], v[92:95]
	v_mfma_f32_16x16x32_bf16 v[92:95], v[124:127], v[180:183], v[92:95]
	v_mfma_f32_16x16x32_bf16 v[88:91], v[128:131], v[176:179], v[88:91]
	v_mfma_f32_16x16x32_bf16 v[88:91], v[132:135], v[180:183], v[88:91]
	v_mfma_f32_16x16x32_bf16 v[76:79], v[120:123], v[184:187], v[76:79]
	v_mfma_f32_16x16x32_bf16 v[76:79], v[124:127], v[188:191], v[76:79]
	v_mfma_f32_16x16x32_bf16 v[72:75], v[128:131], v[184:187], v[72:75]
	v_mfma_f32_16x16x32_bf16 v[72:75], v[132:135], v[188:191], v[72:75]
	v_mfma_f32_16x16x32_bf16 v[116:119], v[144:147], v[160:163], v[116:119]
	v_mfma_f32_16x16x32_bf16 v[116:119], v[148:151], v[164:167], v[116:119]
	v_mfma_f32_16x16x32_bf16 v[112:115], v[152:155], v[160:163], v[112:115]
	v_mfma_f32_16x16x32_bf16 v[112:115], v[156:159], v[164:167], v[112:115]
	v_mfma_f32_16x16x32_bf16 v[100:103], v[144:147], v[168:171], v[100:103]
	v_mfma_f32_16x16x32_bf16 v[100:103], v[148:151], v[172:175], v[100:103]
	v_mfma_f32_16x16x32_bf16 v[96:99], v[152:155], v[168:171], v[96:99]
	v_mfma_f32_16x16x32_bf16 v[96:99], v[156:159], v[172:175], v[96:99]
	v_mfma_f32_16x16x32_bf16 v[84:87], v[144:147], v[176:179], v[84:87]
	v_mfma_f32_16x16x32_bf16 v[84:87], v[148:151], v[180:183], v[84:87]
	v_mfma_f32_16x16x32_bf16 v[80:83], v[152:155], v[176:179], v[80:83]
	v_mfma_f32_16x16x32_bf16 v[80:83], v[156:159], v[180:183], v[80:83]
	v_mfma_f32_16x16x32_bf16 v[68:71], v[144:147], v[184:187], v[68:71]
	v_mfma_f32_16x16x32_bf16 v[68:71], v[148:151], v[188:191], v[68:71]
	s_setprio 3
	s_barrier
	v_mfma_f32_16x16x32_bf16 v[64:67], v[152:155], v[184:187], v[64:67]
	v_mfma_f32_16x16x32_bf16 v[64:67], v[156:159], v[188:191], v[64:67]
	s_setprio 0
	s_add_i32 s59, s26, s15
	v_lshl_add_u64 v[204:205], s[88:89], 0, v[194:195]
	s_mov_b32 m0, s59
	ds_read_b128 v[160:163], v247 offset:16384
	ds_read_b128 v[164:167], v247 offset:17408
	ds_read_b128 v[168:171], v247 offset:18432
	ds_read_b128 v[172:175], v247 offset:19456
	ds_read_b128 v[176:179], v247 offset:20480
	ds_read_b128 v[180:183], v247 offset:21504
	ds_read_b128 v[184:187], v247 offset:22528
	ds_read_b128 v[188:191], v247 offset:23552
	global_load_lds_dwordx4 v[204:205], off
	s_add_i32 m0, s59, 0x2000
	s_add_u32 s66, s88, 0xb0000
	v_lshl_add_u64 v[206:207], s[88:89], 0, v[198:199]
	s_addc_u32 s67, s89, 0
	s_add_i32 s59, s27, s15
	global_load_lds_dwordx4 v[206:207], off
	v_lshl_add_u64 v[208:209], s[66:67], 0, v[194:195]
	s_mov_b32 m0, s59
	v_lshl_add_u64 v[210:211], s[90:91], 0, v[196:197]
	global_load_lds_dwordx4 v[208:209], off
	v_lshl_add_u64 v[208:209], s[66:67], 0, v[198:199]
	s_add_i32 m0, s59, 0x2000
	s_nop 0
	global_load_lds_dwordx4 v[208:209], off
	v_lshl_add_u64 v[208:209], s[90:91], 0, v[192:193]
	s_mov_b32 m0, s16
	s_nop 0
	global_load_lds_dwordx4 v[208:209], off
	s_mov_b32 m0, s17
	s_nop 0
	global_load_lds_dwordx4 v[210:211], off
	s_waitcnt vmcnt(8)
	s_waitcnt lgkmcnt(0)
	s_barrier
	s_setprio 1
	v_mfma_f32_16x16x32_bf16 v[60:63], v[120:123], v[160:163], v[60:63]
	v_mfma_f32_16x16x32_bf16 v[60:63], v[124:127], v[164:167], v[60:63]
	v_mfma_f32_16x16x32_bf16 v[56:59], v[128:131], v[160:163], v[56:59]
	v_mfma_f32_16x16x32_bf16 v[56:59], v[132:135], v[164:167], v[56:59]
	v_mfma_f32_16x16x32_bf16 v[44:47], v[120:123], v[168:171], v[44:47]
	v_mfma_f32_16x16x32_bf16 v[44:47], v[124:127], v[172:175], v[44:47]
	v_mfma_f32_16x16x32_bf16 v[40:43], v[128:131], v[168:171], v[40:43]
	v_mfma_f32_16x16x32_bf16 v[40:43], v[132:135], v[172:175], v[40:43]
	v_mfma_f32_16x16x32_bf16 v[28:31], v[120:123], v[176:179], v[28:31]
	v_mfma_f32_16x16x32_bf16 v[28:31], v[124:127], v[180:183], v[28:31]
	v_mfma_f32_16x16x32_bf16 v[24:27], v[128:131], v[176:179], v[24:27]
	v_mfma_f32_16x16x32_bf16 v[24:27], v[132:135], v[180:183], v[24:27]
	v_mfma_f32_16x16x32_bf16 v[12:15], v[120:123], v[184:187], v[12:15]
	v_mfma_f32_16x16x32_bf16 v[12:15], v[124:127], v[188:191], v[12:15]
	v_mfma_f32_16x16x32_bf16 v[8:11], v[128:131], v[184:187], v[8:11]
	v_mfma_f32_16x16x32_bf16 v[8:11], v[132:135], v[188:191], v[8:11]
	v_mfma_f32_16x16x32_bf16 v[52:55], v[144:147], v[160:163], v[52:55]
	v_mfma_f32_16x16x32_bf16 v[52:55], v[148:151], v[164:167], v[52:55]
	v_mfma_f32_16x16x32_bf16 v[48:51], v[152:155], v[160:163], v[48:51]
	v_mfma_f32_16x16x32_bf16 v[48:51], v[156:159], v[164:167], v[48:51]
	v_mfma_f32_16x16x32_bf16 v[36:39], v[144:147], v[168:171], v[36:39]
	v_mfma_f32_16x16x32_bf16 v[36:39], v[148:151], v[172:175], v[36:39]
	v_mfma_f32_16x16x32_bf16 v[32:35], v[152:155], v[168:171], v[32:35]
	v_mfma_f32_16x16x32_bf16 v[32:35], v[156:159], v[172:175], v[32:35]
	v_mfma_f32_16x16x32_bf16 v[20:23], v[144:147], v[176:179], v[20:23]
	v_mfma_f32_16x16x32_bf16 v[20:23], v[148:151], v[180:183], v[20:23]
	v_mfma_f32_16x16x32_bf16 v[16:19], v[152:155], v[176:179], v[16:19]
	v_mfma_f32_16x16x32_bf16 v[16:19], v[156:159], v[180:183], v[16:19]
	v_mfma_f32_16x16x32_bf16 v[4:7], v[144:147], v[184:187], v[4:7]
	v_mfma_f32_16x16x32_bf16 v[4:7], v[148:151], v[188:191], v[4:7]
	s_setprio 3
	s_barrier
	v_mfma_f32_16x16x32_bf16 v[0:3], v[152:155], v[184:187], v[0:3]
	v_mfma_f32_16x16x32_bf16 v[0:3], v[156:159], v[188:191], v[0:3]
	s_setprio 0
	s_add_i32 s59, 0, 0x18000
	s_add_i32 s68, 0, 0x1c000
	v_add_u32_e32 v132, s59, v243
	v_add_u32_e32 v156, s68, v243
	ds_read_b128 v[120:123], v132
	ds_read_b128 v[124:127], v132 offset:1024
	ds_read_b128 v[128:131], v132 offset:2048
	ds_read_b128 v[132:135], v132 offset:3072
	ds_read_b128 v[144:147], v156
	ds_read_b128 v[148:151], v156 offset:1024
	ds_read_b128 v[152:155], v156 offset:2048
	ds_read_b128 v[156:159], v156 offset:3072
	s_add_u32 s66, s90, 0xb0000
	s_addc_u32 s67, s91, 0
	s_mov_b32 m0, s18
	v_lshl_add_u64 v[212:213], s[66:67], 0, v[192:193]
	ds_read_b128 v[160:163], v247 offset:32768
	ds_read_b128 v[164:167], v247 offset:33792
	ds_read_b128 v[168:171], v247 offset:34816
	ds_read_b128 v[172:175], v247 offset:35840
	ds_read_b128 v[176:179], v247 offset:36864
	ds_read_b128 v[180:183], v247 offset:37888
	ds_read_b128 v[184:187], v247 offset:38912
	ds_read_b128 v[188:191], v247 offset:39936
	global_load_lds_dwordx4 v[212:213], off
	v_lshl_add_u64 v[212:213], s[66:67], 0, v[196:197]
	s_mov_b32 m0, s19
	s_nop 0
	global_load_lds_dwordx4 v[212:213], off
	s_waitcnt vmcnt(8)
	s_waitcnt lgkmcnt(0)
	s_barrier
	s_setprio 1
	v_mfma_f32_16x16x32_bf16 v[140:143], v[120:123], v[160:163], v[140:143]
	v_mfma_f32_16x16x32_bf16 v[140:143], v[124:127], v[164:167], v[140:143]
	v_mfma_f32_16x16x32_bf16 v[136:139], v[128:131], v[160:163], v[136:139]
	v_mfma_f32_16x16x32_bf16 v[136:139], v[132:135], v[164:167], v[136:139]
	v_mfma_f32_16x16x32_bf16 v[108:111], v[120:123], v[168:171], v[108:111]
	v_mfma_f32_16x16x32_bf16 v[108:111], v[124:127], v[172:175], v[108:111]
	v_mfma_f32_16x16x32_bf16 v[104:107], v[128:131], v[168:171], v[104:107]
	v_mfma_f32_16x16x32_bf16 v[104:107], v[132:135], v[172:175], v[104:107]
	v_mfma_f32_16x16x32_bf16 v[92:95], v[120:123], v[176:179], v[92:95]
	v_mfma_f32_16x16x32_bf16 v[92:95], v[124:127], v[180:183], v[92:95]
	v_mfma_f32_16x16x32_bf16 v[88:91], v[128:131], v[176:179], v[88:91]
	v_mfma_f32_16x16x32_bf16 v[88:91], v[132:135], v[180:183], v[88:91]
	v_mfma_f32_16x16x32_bf16 v[76:79], v[120:123], v[184:187], v[76:79]
	v_mfma_f32_16x16x32_bf16 v[76:79], v[124:127], v[188:191], v[76:79]
	v_mfma_f32_16x16x32_bf16 v[72:75], v[128:131], v[184:187], v[72:75]
	v_mfma_f32_16x16x32_bf16 v[72:75], v[132:135], v[188:191], v[72:75]
	v_mfma_f32_16x16x32_bf16 v[116:119], v[144:147], v[160:163], v[116:119]
	v_mfma_f32_16x16x32_bf16 v[116:119], v[148:151], v[164:167], v[116:119]
	v_mfma_f32_16x16x32_bf16 v[112:115], v[152:155], v[160:163], v[112:115]
	v_mfma_f32_16x16x32_bf16 v[112:115], v[156:159], v[164:167], v[112:115]
	v_mfma_f32_16x16x32_bf16 v[100:103], v[144:147], v[168:171], v[100:103]
	v_mfma_f32_16x16x32_bf16 v[100:103], v[148:151], v[172:175], v[100:103]
	v_mfma_f32_16x16x32_bf16 v[96:99], v[152:155], v[168:171], v[96:99]
	v_mfma_f32_16x16x32_bf16 v[96:99], v[156:159], v[172:175], v[96:99]
	v_mfma_f32_16x16x32_bf16 v[84:87], v[144:147], v[176:179], v[84:87]
	v_mfma_f32_16x16x32_bf16 v[84:87], v[148:151], v[180:183], v[84:87]
	v_mfma_f32_16x16x32_bf16 v[80:83], v[152:155], v[176:179], v[80:83]
	v_mfma_f32_16x16x32_bf16 v[80:83], v[156:159], v[180:183], v[80:83]
	v_mfma_f32_16x16x32_bf16 v[68:71], v[144:147], v[184:187], v[68:71]
	v_mfma_f32_16x16x32_bf16 v[68:71], v[148:151], v[188:191], v[68:71]
	s_setprio 3
	s_barrier
	v_mfma_f32_16x16x32_bf16 v[64:67], v[152:155], v[184:187], v[64:67]
	v_mfma_f32_16x16x32_bf16 v[64:67], v[156:159], v[188:191], v[64:67]
	s_setprio 0
	s_add_i32 s59, s59, s15
	v_lshl_add_u64 v[204:205], v[204:205], 0, s[80:81]
	s_mov_b32 m0, s59
	ds_read_b128 v[160:163], v247 offset:49152
	ds_read_b128 v[164:167], v247 offset:50176
	ds_read_b128 v[168:171], v247 offset:51200
	ds_read_b128 v[172:175], v247 offset:52224
	ds_read_b128 v[176:179], v247 offset:53248
	ds_read_b128 v[180:183], v247 offset:54272
	ds_read_b128 v[184:187], v247 offset:55296
	ds_read_b128 v[188:191], v247 offset:56320
	global_load_lds_dwordx4 v[204:205], off
	s_add_i32 m0, s59, 0x2000
	s_add_u32 s66, s88, 0xb0080
	v_lshl_add_u64 v[204:205], v[206:207], 0, s[80:81]
	s_addc_u32 s67, s89, 0
	s_add_i32 s59, s68, s15
	global_load_lds_dwordx4 v[204:205], off
	v_lshl_add_u64 v[204:205], s[66:67], 0, v[194:195]
	s_mov_b32 m0, s59
	s_nop 0
	global_load_lds_dwordx4 v[204:205], off
	v_lshl_add_u64 v[204:205], s[66:67], 0, v[198:199]
	s_add_i32 m0, s59, 0x2000
	s_nop 0
	global_load_lds_dwordx4 v[204:205], off
	v_lshl_add_u64 v[204:205], v[208:209], 0, s[80:81]
	s_mov_b32 m0, s21
	s_nop 0
	global_load_lds_dwordx4 v[204:205], off
	v_lshl_add_u64 v[204:205], v[210:211], 0, s[80:81]
	s_mov_b32 m0, s22
	s_nop 0
	global_load_lds_dwordx4 v[204:205], off
	s_waitcnt vmcnt(8)
	s_waitcnt lgkmcnt(0)
	s_barrier
	s_setprio 1
	v_mfma_f32_16x16x32_bf16 v[60:63], v[120:123], v[160:163], v[60:63]
	v_mfma_f32_16x16x32_bf16 v[60:63], v[124:127], v[164:167], v[60:63]
	v_mfma_f32_16x16x32_bf16 v[56:59], v[128:131], v[160:163], v[56:59]
	v_mfma_f32_16x16x32_bf16 v[56:59], v[132:135], v[164:167], v[56:59]
	v_mfma_f32_16x16x32_bf16 v[44:47], v[120:123], v[168:171], v[44:47]
	v_mfma_f32_16x16x32_bf16 v[44:47], v[124:127], v[172:175], v[44:47]
	v_mfma_f32_16x16x32_bf16 v[40:43], v[128:131], v[168:171], v[40:43]
	v_mfma_f32_16x16x32_bf16 v[40:43], v[132:135], v[172:175], v[40:43]
	v_mfma_f32_16x16x32_bf16 v[28:31], v[120:123], v[176:179], v[28:31]
	v_mfma_f32_16x16x32_bf16 v[28:31], v[124:127], v[180:183], v[28:31]
	v_mfma_f32_16x16x32_bf16 v[24:27], v[128:131], v[176:179], v[24:27]
	v_mfma_f32_16x16x32_bf16 v[24:27], v[132:135], v[180:183], v[24:27]
	v_mfma_f32_16x16x32_bf16 v[12:15], v[120:123], v[184:187], v[12:15]
	v_mfma_f32_16x16x32_bf16 v[12:15], v[124:127], v[188:191], v[12:15]
	v_mfma_f32_16x16x32_bf16 v[8:11], v[128:131], v[184:187], v[8:11]
	v_mfma_f32_16x16x32_bf16 v[8:11], v[132:135], v[188:191], v[8:11]
	v_mfma_f32_16x16x32_bf16 v[52:55], v[144:147], v[160:163], v[52:55]
	v_mfma_f32_16x16x32_bf16 v[52:55], v[148:151], v[164:167], v[52:55]
	v_mfma_f32_16x16x32_bf16 v[48:51], v[152:155], v[160:163], v[48:51]
	v_mfma_f32_16x16x32_bf16 v[48:51], v[156:159], v[164:167], v[48:51]
	v_mfma_f32_16x16x32_bf16 v[36:39], v[144:147], v[168:171], v[36:39]
	v_mfma_f32_16x16x32_bf16 v[36:39], v[148:151], v[172:175], v[36:39]
	v_mfma_f32_16x16x32_bf16 v[32:35], v[152:155], v[168:171], v[32:35]
	v_mfma_f32_16x16x32_bf16 v[32:35], v[156:159], v[172:175], v[32:35]
	v_mfma_f32_16x16x32_bf16 v[20:23], v[144:147], v[176:179], v[20:23]
	v_mfma_f32_16x16x32_bf16 v[20:23], v[148:151], v[180:183], v[20:23]
	v_mfma_f32_16x16x32_bf16 v[16:19], v[152:155], v[176:179], v[16:19]
	v_mfma_f32_16x16x32_bf16 v[16:19], v[156:159], v[180:183], v[16:19]
	v_mfma_f32_16x16x32_bf16 v[4:7], v[144:147], v[184:187], v[4:7]
	v_mfma_f32_16x16x32_bf16 v[4:7], v[148:151], v[188:191], v[4:7]
	s_setprio 3
	s_barrier
	v_mfma_f32_16x16x32_bf16 v[0:3], v[152:155], v[184:187], v[0:3]
	v_mfma_f32_16x16x32_bf16 v[0:3], v[156:159], v[188:191], v[0:3]
	s_setprio 0
	s_add_i32 s58, s58, 2
	s_add_u32 s86, s86, 0x100
	s_addc_u32 s87, s87, 0
	s_add_u32 s56, s56, 0x100
	s_addc_u32 s57, s57, 0
	s_cmp_gt_u32 s58, 41
	s_cbranch_scc0 .LBB0_272
	s_and_b64 vcc, exec, s[82:83]
	s_cbranch_vccz .LBB0_275
	s_barrier

.LBB0_429:
	ds_read_b128 v[128:131], v203
	ds_read_b128 v[132:135], v203 offset:1024
	ds_read_b128 v[136:139], v203 offset:2048
	ds_read_b128 v[164:167], v203 offset:3072
	ds_read_b128 v[168:171], v204
	ds_read_b128 v[172:175], v204 offset:1024
	ds_read_b128 v[176:179], v204 offset:2048
	ds_read_b128 v[180:183], v204 offset:3072
	s_add_u32 s6, s88, 0xfffc0080
	s_addc_u32 s7, s89, -1
	s_cmp_eq_u32 s21, 12
	s_cselect_b32 vcc_hi, s15, s7
	s_cselect_b32 vcc_lo, s16, s6
	s_cselect_b32 s7, s17, s20
	s_cselect_b32 s6, s18, s19
	v_lshl_add_u64 v[196:197], s[88:89], 0, v[156:157]
	s_add_i32 m0, s58, 0xc000
	ds_read_b128 v[184:187], v205
	ds_read_b128 v[188:191], v205 offset:1024
	ds_read_b128 v[192:195], v205 offset:2048
	ds_read_b128 v[212:215], v205 offset:3072
	ds_read_b128 v[216:219], v205 offset:4096
	ds_read_b128 v[220:223], v205 offset:5120
	ds_read_b128 v[224:227], v205 offset:6144
	ds_read_b128 v[228:231], v205 offset:7168
	global_load_lds_dwordx4 v[196:197], off
	v_lshl_add_u64 v[196:197], s[88:89], 0, v[158:159]
	s_add_i32 m0, s58, 0xe000
	s_nop 0
	global_load_lds_dwordx4 v[196:197], off
	s_waitcnt vmcnt(8)
	s_waitcnt lgkmcnt(0)
	s_barrier
	s_setprio 1
	v_mfma_f32_16x16x32_bf16 v[124:127], v[128:131], v[184:187], v[124:127]
	v_mfma_f32_16x16x32_bf16 v[124:127], v[132:135], v[188:191], v[124:127]
	v_mfma_f32_16x16x32_bf16 v[116:119], v[136:139], v[184:187], v[116:119]
	v_mfma_f32_16x16x32_bf16 v[116:119], v[164:167], v[188:191], v[116:119]
	v_mfma_f32_16x16x32_bf16 v[108:111], v[128:131], v[192:195], v[108:111]
	v_mfma_f32_16x16x32_bf16 v[108:111], v[132:135], v[212:215], v[108:111]
	v_mfma_f32_16x16x32_bf16 v[100:103], v[136:139], v[192:195], v[100:103]
	v_mfma_f32_16x16x32_bf16 v[100:103], v[164:167], v[212:215], v[100:103]
	v_mfma_f32_16x16x32_bf16 v[92:95], v[128:131], v[216:219], v[92:95]
	v_mfma_f32_16x16x32_bf16 v[92:95], v[132:135], v[220:223], v[92:95]
	v_mfma_f32_16x16x32_bf16 v[84:87], v[136:139], v[216:219], v[84:87]
	v_mfma_f32_16x16x32_bf16 v[84:87], v[164:167], v[220:223], v[84:87]
	v_mfma_f32_16x16x32_bf16 v[76:79], v[128:131], v[224:227], v[76:79]
	v_mfma_f32_16x16x32_bf16 v[76:79], v[132:135], v[228:231], v[76:79]
	v_mfma_f32_16x16x32_bf16 v[68:71], v[136:139], v[224:227], v[68:71]
	v_mfma_f32_16x16x32_bf16 v[68:71], v[164:167], v[228:231], v[68:71]
	v_mfma_f32_16x16x32_bf16 v[120:123], v[168:171], v[184:187], v[120:123]
	v_mfma_f32_16x16x32_bf16 v[120:123], v[172:175], v[188:191], v[120:123]
	v_mfma_f32_16x16x32_bf16 v[112:115], v[176:179], v[184:187], v[112:115]
	v_mfma_f32_16x16x32_bf16 v[112:115], v[180:183], v[188:191], v[112:115]
	v_mfma_f32_16x16x32_bf16 v[104:107], v[168:171], v[192:195], v[104:107]
	v_mfma_f32_16x16x32_bf16 v[104:107], v[172:175], v[212:215], v[104:107]
	v_mfma_f32_16x16x32_bf16 v[96:99], v[176:179], v[192:195], v[96:99]
	v_mfma_f32_16x16x32_bf16 v[96:99], v[180:183], v[212:215], v[96:99]
	v_mfma_f32_16x16x32_bf16 v[88:91], v[168:171], v[216:219], v[88:91]
	v_mfma_f32_16x16x32_bf16 v[88:91], v[172:175], v[220:223], v[88:91]
	v_mfma_f32_16x16x32_bf16 v[80:83], v[176:179], v[216:219], v[80:83]
	v_mfma_f32_16x16x32_bf16 v[80:83], v[180:183], v[220:223], v[80:83]
	v_mfma_f32_16x16x32_bf16 v[72:75], v[168:171], v[224:227], v[72:75]
	v_mfma_f32_16x16x32_bf16 v[72:75], v[172:175], v[228:231], v[72:75]
	s_setprio 3
	s_barrier
	v_mfma_f32_16x16x32_bf16 v[64:67], v[176:179], v[224:227], v[64:67]
	v_mfma_f32_16x16x32_bf16 v[64:67], v[180:183], v[228:231], v[64:67]
	s_setprio 0
	s_add_i32 s22, s76, s57
	v_lshl_add_u64 v[196:197], s[6:7], 0, v[142:143]
	s_mov_b32 m0, s22
	ds_read_b128 v[184:187], v205 offset:16384
	ds_read_b128 v[188:191], v205 offset:17408
	ds_read_b128 v[192:195], v205 offset:18432
	ds_read_b128 v[212:215], v205 offset:19456
	ds_read_b128 v[216:219], v205 offset:20480
	ds_read_b128 v[220:223], v205 offset:21504
	ds_read_b128 v[224:227], v205 offset:22528
	ds_read_b128 v[228:231], v205 offset:23552
	global_load_lds_dwordx4 v[196:197], off
	s_add_i32 m0, s22, 0x2000
	s_add_u32 s22, s6, 0x40000
	v_lshl_add_u64 v[232:233], s[6:7], 0, v[146:147]
	s_addc_u32 s23, s7, 0
	s_add_i32 s24, s77, s57
	global_load_lds_dwordx4 v[232:233], off
	v_lshl_add_u64 v[234:235], s[22:23], 0, v[142:143]
	s_mov_b32 m0, s24
	v_lshl_add_u64 v[236:237], vcc, 0, v[144:145]
	global_load_lds_dwordx4 v[234:235], off
	v_lshl_add_u64 v[234:235], s[22:23], 0, v[146:147]
	s_add_i32 m0, s24, 0x2000
	s_nop 0
	global_load_lds_dwordx4 v[234:235], off
	v_lshl_add_u64 v[234:235], vcc, 0, v[140:141]
	s_mov_b32 m0, s58
	s_nop 0
	global_load_lds_dwordx4 v[234:235], off
	s_mov_b32 m0, s59
	s_nop 0
	global_load_lds_dwordx4 v[236:237], off
	s_waitcnt vmcnt(8)
	s_waitcnt lgkmcnt(0)
	s_barrier
	s_setprio 1
	v_mfma_f32_16x16x32_bf16 v[60:63], v[128:131], v[184:187], v[60:63]
	v_mfma_f32_16x16x32_bf16 v[60:63], v[132:135], v[188:191], v[60:63]
	v_mfma_f32_16x16x32_bf16 v[52:55], v[136:139], v[184:187], v[52:55]
	v_mfma_f32_16x16x32_bf16 v[52:55], v[164:167], v[188:191], v[52:55]
	v_mfma_f32_16x16x32_bf16 v[44:47], v[128:131], v[192:195], v[44:47]
	v_mfma_f32_16x16x32_bf16 v[44:47], v[132:135], v[212:215], v[44:47]
	v_mfma_f32_16x16x32_bf16 v[36:39], v[136:139], v[192:195], v[36:39]
	v_mfma_f32_16x16x32_bf16 v[36:39], v[164:167], v[212:215], v[36:39]
	v_mfma_f32_16x16x32_bf16 v[28:31], v[128:131], v[216:219], v[28:31]
	v_mfma_f32_16x16x32_bf16 v[28:31], v[132:135], v[220:223], v[28:31]
	v_mfma_f32_16x16x32_bf16 v[20:23], v[136:139], v[216:219], v[20:23]
	v_mfma_f32_16x16x32_bf16 v[20:23], v[164:167], v[220:223], v[20:23]
	v_mfma_f32_16x16x32_bf16 v[12:15], v[128:131], v[224:227], v[12:15]
	v_mfma_f32_16x16x32_bf16 v[12:15], v[132:135], v[228:231], v[12:15]
	v_mfma_f32_16x16x32_bf16 v[4:7], v[136:139], v[224:227], v[4:7]
	v_mfma_f32_16x16x32_bf16 v[4:7], v[164:167], v[228:231], v[4:7]
	v_mfma_f32_16x16x32_bf16 v[56:59], v[168:171], v[184:187], v[56:59]
	v_mfma_f32_16x16x32_bf16 v[56:59], v[172:175], v[188:191], v[56:59]
	v_mfma_f32_16x16x32_bf16 v[48:51], v[176:179], v[184:187], v[48:51]
	v_mfma_f32_16x16x32_bf16 v[48:51], v[180:183], v[188:191], v[48:51]
	v_mfma_f32_16x16x32_bf16 v[40:43], v[168:171], v[192:195], v[40:43]
	v_mfma_f32_16x16x32_bf16 v[40:43], v[172:175], v[212:215], v[40:43]
	v_mfma_f32_16x16x32_bf16 v[32:35], v[176:179], v[192:195], v[32:35]
	v_mfma_f32_16x16x32_bf16 v[32:35], v[180:183], v[212:215], v[32:35]
	v_mfma_f32_16x16x32_bf16 v[24:27], v[168:171], v[216:219], v[24:27]
	v_mfma_f32_16x16x32_bf16 v[24:27], v[172:175], v[220:223], v[24:27]
	v_mfma_f32_16x16x32_bf16 v[16:19], v[176:179], v[216:219], v[16:19]
	v_mfma_f32_16x16x32_bf16 v[16:19], v[180:183], v[220:223], v[16:19]
	v_mfma_f32_16x16x32_bf16 v[8:11], v[168:171], v[224:227], v[8:11]
	v_mfma_f32_16x16x32_bf16 v[8:11], v[172:175], v[228:231], v[8:11]
	s_setprio 3
	s_barrier
	v_mfma_f32_16x16x32_bf16 v[0:3], v[176:179], v[224:227], v[0:3]
	v_mfma_f32_16x16x32_bf16 v[0:3], v[180:183], v[228:231], v[0:3]
	s_setprio 0
	s_add_i32 s24, 0, 0x18000
	v_add_u32_e32 v150, s24, v200
	s_add_i32 s25, 0, 0x1c000
	ds_read_b128 v[128:131], v150
	ds_read_b128 v[132:135], v150 offset:1024
	ds_read_b128 v[136:139], v150 offset:2048
	ds_read_b128 v[164:167], v150 offset:3072
	v_add_u32_e32 v150, s25, v200
	ds_read_b128 v[168:171], v150
	ds_read_b128 v[172:175], v150 offset:1024
	ds_read_b128 v[176:179], v150 offset:2048
	ds_read_b128 v[180:183], v150 offset:3072
	s_add_u32 s22, vcc_lo, 0x40000
	s_addc_u32 s23, vcc_hi, 0
	s_mov_b32 m0, s66
	v_lshl_add_u64 v[238:239], s[22:23], 0, v[140:141]
	ds_read_b128 v[184:187], v205 offset:32768
	ds_read_b128 v[188:191], v205 offset:33792
	ds_read_b128 v[192:195], v205 offset:34816
	ds_read_b128 v[212:215], v205 offset:35840
	ds_read_b128 v[216:219], v205 offset:36864
	ds_read_b128 v[220:223], v205 offset:37888
	ds_read_b128 v[224:227], v205 offset:38912
	ds_read_b128 v[228:231], v205 offset:39936
	global_load_lds_dwordx4 v[238:239], off
	v_lshl_add_u64 v[238:239], s[22:23], 0, v[144:145]
	s_mov_b32 m0, s67
	s_nop 0
	global_load_lds_dwordx4 v[238:239], off
	s_waitcnt vmcnt(8)
	s_waitcnt lgkmcnt(0)
	s_barrier
	s_setprio 1
	v_mfma_f32_16x16x32_bf16 v[124:127], v[128:131], v[184:187], v[124:127]
	v_mfma_f32_16x16x32_bf16 v[124:127], v[132:135], v[188:191], v[124:127]
	v_mfma_f32_16x16x32_bf16 v[116:119], v[136:139], v[184:187], v[116:119]
	v_mfma_f32_16x16x32_bf16 v[116:119], v[164:167], v[188:191], v[116:119]
	v_mfma_f32_16x16x32_bf16 v[108:111], v[128:131], v[192:195], v[108:111]
	v_mfma_f32_16x16x32_bf16 v[108:111], v[132:135], v[212:215], v[108:111]
	v_mfma_f32_16x16x32_bf16 v[100:103], v[136:139], v[192:195], v[100:103]
	v_mfma_f32_16x16x32_bf16 v[100:103], v[164:167], v[212:215], v[100:103]
	v_mfma_f32_16x16x32_bf16 v[92:95], v[128:131], v[216:219], v[92:95]
	v_mfma_f32_16x16x32_bf16 v[92:95], v[132:135], v[220:223], v[92:95]
	v_mfma_f32_16x16x32_bf16 v[84:87], v[136:139], v[216:219], v[84:87]
	v_mfma_f32_16x16x32_bf16 v[84:87], v[164:167], v[220:223], v[84:87]
	v_mfma_f32_16x16x32_bf16 v[76:79], v[128:131], v[224:227], v[76:79]
	v_mfma_f32_16x16x32_bf16 v[76:79], v[132:135], v[228:231], v[76:79]
	v_mfma_f32_16x16x32_bf16 v[68:71], v[136:139], v[224:227], v[68:71]
	v_mfma_f32_16x16x32_bf16 v[68:71], v[164:167], v[228:231], v[68:71]
	v_mfma_f32_16x16x32_bf16 v[120:123], v[168:171], v[184:187], v[120:123]
	v_mfma_f32_16x16x32_bf16 v[120:123], v[172:175], v[188:191], v[120:123]
	v_mfma_f32_16x16x32_bf16 v[112:115], v[176:179], v[184:187], v[112:115]
	v_mfma_f32_16x16x32_bf16 v[112:115], v[180:183], v[188:191], v[112:115]
	v_mfma_f32_16x16x32_bf16 v[104:107], v[168:171], v[192:195], v[104:107]
	v_mfma_f32_16x16x32_bf16 v[104:107], v[172:175], v[212:215], v[104:107]
	v_mfma_f32_16x16x32_bf16 v[96:99], v[176:179], v[192:195], v[96:99]
	v_mfma_f32_16x16x32_bf16 v[96:99], v[180:183], v[212:215], v[96:99]
	v_mfma_f32_16x16x32_bf16 v[88:91], v[168:171], v[216:219], v[88:91]
	v_mfma_f32_16x16x32_bf16 v[88:91], v[172:175], v[220:223], v[88:91]
	v_mfma_f32_16x16x32_bf16 v[80:83], v[176:179], v[216:219], v[80:83]
	v_mfma_f32_16x16x32_bf16 v[80:83], v[180:183], v[220:223], v[80:83]
	v_mfma_f32_16x16x32_bf16 v[72:75], v[168:171], v[224:227], v[72:75]
	v_mfma_f32_16x16x32_bf16 v[72:75], v[172:175], v[228:231], v[72:75]
	s_setprio 3
	s_barrier
	v_mfma_f32_16x16x32_bf16 v[64:67], v[176:179], v[224:227], v[64:67]
	v_mfma_f32_16x16x32_bf16 v[64:67], v[180:183], v[228:231], v[64:67]
	s_setprio 0
	s_add_i32 s22, s24, s57
	v_lshl_add_u64 v[196:197], v[196:197], 0, s[80:81]
	s_mov_b32 m0, s22
	ds_read_b128 v[184:187], v205 offset:49152
	ds_read_b128 v[188:191], v205 offset:50176
	ds_read_b128 v[192:195], v205 offset:51200
	ds_read_b128 v[212:215], v205 offset:52224
	ds_read_b128 v[216:219], v205 offset:53248
	ds_read_b128 v[220:223], v205 offset:54272
	ds_read_b128 v[224:227], v205 offset:55296
	ds_read_b128 v[228:231], v205 offset:56320
	global_load_lds_dwordx4 v[196:197], off
	s_add_i32 m0, s22, 0x2000
	s_add_u32 s6, s6, 0x40080
	v_lshl_add_u64 v[196:197], v[232:233], 0, s[80:81]
	s_addc_u32 s7, s7, 0
	s_add_i32 s22, s25, s57
	global_load_lds_dwordx4 v[196:197], off
	v_lshl_add_u64 v[196:197], s[6:7], 0, v[142:143]
	s_mov_b32 m0, s22
	s_nop 0
	global_load_lds_dwordx4 v[196:197], off
	v_lshl_add_u64 v[196:197], s[6:7], 0, v[146:147]
	s_add_i32 m0, s22, 0x2000
	s_nop 0
	global_load_lds_dwordx4 v[196:197], off
	v_lshl_add_u64 v[196:197], v[234:235], 0, s[80:81]
	s_mov_b32 m0, s93
	s_nop 0
	global_load_lds_dwordx4 v[196:197], off
	v_lshl_add_u64 v[196:197], v[236:237], 0, s[80:81]
	s_mov_b32 m0, s69
	s_nop 0
	global_load_lds_dwordx4 v[196:197], off
	s_waitcnt vmcnt(8)
	s_waitcnt lgkmcnt(0)
	s_barrier
	s_setprio 1
	v_mfma_f32_16x16x32_bf16 v[60:63], v[128:131], v[184:187], v[60:63]
	v_mfma_f32_16x16x32_bf16 v[60:63], v[132:135], v[188:191], v[60:63]
	v_mfma_f32_16x16x32_bf16 v[52:55], v[136:139], v[184:187], v[52:55]
	v_mfma_f32_16x16x32_bf16 v[52:55], v[164:167], v[188:191], v[52:55]
	v_mfma_f32_16x16x32_bf16 v[44:47], v[128:131], v[192:195], v[44:47]
	v_mfma_f32_16x16x32_bf16 v[44:47], v[132:135], v[212:215], v[44:47]
	v_mfma_f32_16x16x32_bf16 v[36:39], v[136:139], v[192:195], v[36:39]
	v_mfma_f32_16x16x32_bf16 v[36:39], v[164:167], v[212:215], v[36:39]
	v_mfma_f32_16x16x32_bf16 v[28:31], v[128:131], v[216:219], v[28:31]
	v_mfma_f32_16x16x32_bf16 v[28:31], v[132:135], v[220:223], v[28:31]
	v_mfma_f32_16x16x32_bf16 v[20:23], v[136:139], v[216:219], v[20:23]
	v_mfma_f32_16x16x32_bf16 v[20:23], v[164:167], v[220:223], v[20:23]
	v_mfma_f32_16x16x32_bf16 v[12:15], v[128:131], v[224:227], v[12:15]
	v_mfma_f32_16x16x32_bf16 v[12:15], v[132:135], v[228:231], v[12:15]
	v_mfma_f32_16x16x32_bf16 v[4:7], v[136:139], v[224:227], v[4:7]
	v_mfma_f32_16x16x32_bf16 v[4:7], v[164:167], v[228:231], v[4:7]
	v_mfma_f32_16x16x32_bf16 v[56:59], v[168:171], v[184:187], v[56:59]
	v_mfma_f32_16x16x32_bf16 v[56:59], v[172:175], v[188:191], v[56:59]
	v_mfma_f32_16x16x32_bf16 v[48:51], v[176:179], v[184:187], v[48:51]
	v_mfma_f32_16x16x32_bf16 v[48:51], v[180:183], v[188:191], v[48:51]
	v_mfma_f32_16x16x32_bf16 v[40:43], v[168:171], v[192:195], v[40:43]
	v_mfma_f32_16x16x32_bf16 v[40:43], v[172:175], v[212:215], v[40:43]
	v_mfma_f32_16x16x32_bf16 v[32:35], v[176:179], v[192:195], v[32:35]
	v_mfma_f32_16x16x32_bf16 v[32:35], v[180:183], v[212:215], v[32:35]
	v_mfma_f32_16x16x32_bf16 v[24:27], v[168:171], v[216:219], v[24:27]
	v_mfma_f32_16x16x32_bf16 v[24:27], v[172:175], v[220:223], v[24:27]
	v_mfma_f32_16x16x32_bf16 v[16:19], v[176:179], v[216:219], v[16:19]
	v_mfma_f32_16x16x32_bf16 v[16:19], v[180:183], v[220:223], v[16:19]
	v_mfma_f32_16x16x32_bf16 v[8:11], v[168:171], v[224:227], v[8:11]
	v_mfma_f32_16x16x32_bf16 v[8:11], v[172:175], v[228:231], v[8:11]
	s_setprio 3
	s_barrier
	v_mfma_f32_16x16x32_bf16 v[0:3], v[176:179], v[224:227], v[0:3]
	v_mfma_f32_16x16x32_bf16 v[0:3], v[180:183], v[228:231], v[0:3]
	s_setprio 0
	s_add_i32 s21, s21, 2
	s_add_u32 s88, s88, 0x100
	s_addc_u32 s89, s89, 0
	s_add_u32 s19, s19, 0x100
	s_addc_u32 s20, s20, 0
	s_cmp_gt_u32 s21, 13
	s_cbranch_scc0 .LBB0_429
	s_and_b64 vcc, exec, s[82:83]
	s_cbranch_vccz .LBB0_432
	s_barrier

.LBB0_993:
	ds_read_b128 v[120:123], v245
	ds_read_b128 v[124:127], v245 offset:1024
	ds_read_b128 v[128:131], v245 offset:2048
	ds_read_b128 v[132:135], v245 offset:3072
	ds_read_b128 v[144:147], v246
	ds_read_b128 v[148:151], v246 offset:1024
	ds_read_b128 v[152:155], v246 offset:2048
	ds_read_b128 v[156:159], v246 offset:3072
	s_add_u32 s59, s82, 0xfffc0080
	s_addc_u32 s66, s83, -1
	s_cmp_eq_u32 s58, 12
	s_cselect_b32 s87, s53, s66
	s_cselect_b32 s86, s54, s59
	s_cselect_b32 s85, s51, s57
	s_cselect_b32 s84, s55, s56
	v_lshl_add_u64 v[204:205], s[82:83], 0, v[200:201]
	s_add_i32 m0, s16, 0xc000
	ds_read_b128 v[160:163], v247
	ds_read_b128 v[164:167], v247 offset:1024
	ds_read_b128 v[168:171], v247 offset:2048
	ds_read_b128 v[172:175], v247 offset:3072
	ds_read_b128 v[176:179], v247 offset:4096
	ds_read_b128 v[180:183], v247 offset:5120
	ds_read_b128 v[184:187], v247 offset:6144
	ds_read_b128 v[188:191], v247 offset:7168
	global_load_lds_dwordx4 v[204:205], off
	v_lshl_add_u64 v[204:205], s[82:83], 0, v[202:203]
	s_add_i32 m0, s16, 0xe000
	s_nop 0
	global_load_lds_dwordx4 v[204:205], off
	s_waitcnt vmcnt(8)
	s_waitcnt lgkmcnt(0)
	s_barrier
	s_setprio 1
	v_mfma_f32_16x16x32_bf16 v[140:143], v[120:123], v[160:163], v[140:143]
	v_mfma_f32_16x16x32_bf16 v[140:143], v[124:127], v[164:167], v[140:143]
	v_mfma_f32_16x16x32_bf16 v[136:139], v[128:131], v[160:163], v[136:139]
	v_mfma_f32_16x16x32_bf16 v[136:139], v[132:135], v[164:167], v[136:139]
	v_mfma_f32_16x16x32_bf16 v[108:111], v[120:123], v[168:171], v[108:111]
	v_mfma_f32_16x16x32_bf16 v[108:111], v[124:127], v[172:175], v[108:111]
	v_mfma_f32_16x16x32_bf16 v[104:107], v[128:131], v[168:171], v[104:107]
	v_mfma_f32_16x16x32_bf16 v[104:107], v[132:135], v[172:175], v[104:107]
	v_mfma_f32_16x16x32_bf16 v[92:95], v[120:123], v[176:179], v[92:95]
	v_mfma_f32_16x16x32_bf16 v[92:95], v[124:127], v[180:183], v[92:95]
	v_mfma_f32_16x16x32_bf16 v[88:91], v[128:131], v[176:179], v[88:91]
	v_mfma_f32_16x16x32_bf16 v[88:91], v[132:135], v[180:183], v[88:91]
	v_mfma_f32_16x16x32_bf16 v[76:79], v[120:123], v[184:187], v[76:79]
	v_mfma_f32_16x16x32_bf16 v[76:79], v[124:127], v[188:191], v[76:79]
	v_mfma_f32_16x16x32_bf16 v[72:75], v[128:131], v[184:187], v[72:75]
	v_mfma_f32_16x16x32_bf16 v[72:75], v[132:135], v[188:191], v[72:75]
	v_mfma_f32_16x16x32_bf16 v[116:119], v[144:147], v[160:163], v[116:119]
	v_mfma_f32_16x16x32_bf16 v[116:119], v[148:151], v[164:167], v[116:119]
	v_mfma_f32_16x16x32_bf16 v[112:115], v[152:155], v[160:163], v[112:115]
	v_mfma_f32_16x16x32_bf16 v[112:115], v[156:159], v[164:167], v[112:115]
	v_mfma_f32_16x16x32_bf16 v[100:103], v[144:147], v[168:171], v[100:103]
	v_mfma_f32_16x16x32_bf16 v[100:103], v[148:151], v[172:175], v[100:103]
	v_mfma_f32_16x16x32_bf16 v[96:99], v[152:155], v[168:171], v[96:99]
	v_mfma_f32_16x16x32_bf16 v[96:99], v[156:159], v[172:175], v[96:99]
	v_mfma_f32_16x16x32_bf16 v[84:87], v[144:147], v[176:179], v[84:87]
	v_mfma_f32_16x16x32_bf16 v[84:87], v[148:151], v[180:183], v[84:87]
	v_mfma_f32_16x16x32_bf16 v[80:83], v[152:155], v[176:179], v[80:83]
	v_mfma_f32_16x16x32_bf16 v[80:83], v[156:159], v[180:183], v[80:83]
	v_mfma_f32_16x16x32_bf16 v[68:71], v[144:147], v[184:187], v[68:71]
	v_mfma_f32_16x16x32_bf16 v[68:71], v[148:151], v[188:191], v[68:71]
	s_setprio 3
	s_barrier
	v_mfma_f32_16x16x32_bf16 v[64:67], v[152:155], v[184:187], v[64:67]
	v_mfma_f32_16x16x32_bf16 v[64:67], v[156:159], v[188:191], v[64:67]
	s_setprio 0
	s_add_i32 s59, s26, s15
	v_lshl_add_u64 v[204:205], s[84:85], 0, v[194:195]
	s_mov_b32 m0, s59
	ds_read_b128 v[160:163], v247 offset:16384
	ds_read_b128 v[164:167], v247 offset:17408
	ds_read_b128 v[168:171], v247 offset:18432
	ds_read_b128 v[172:175], v247 offset:19456
	ds_read_b128 v[176:179], v247 offset:20480
	ds_read_b128 v[180:183], v247 offset:21504
	ds_read_b128 v[184:187], v247 offset:22528
	ds_read_b128 v[188:191], v247 offset:23552
	global_load_lds_dwordx4 v[204:205], off
	s_add_i32 m0, s59, 0x2000
	s_add_u32 s66, s84, 0x40000
	v_lshl_add_u64 v[206:207], s[84:85], 0, v[198:199]
	s_addc_u32 s67, s85, 0
	s_add_i32 s59, s27, s15
	global_load_lds_dwordx4 v[206:207], off
	v_lshl_add_u64 v[208:209], s[66:67], 0, v[194:195]
	s_mov_b32 m0, s59
	v_lshl_add_u64 v[210:211], s[86:87], 0, v[196:197]
	global_load_lds_dwordx4 v[208:209], off
	v_lshl_add_u64 v[208:209], s[66:67], 0, v[198:199]
	s_add_i32 m0, s59, 0x2000
	s_nop 0
	global_load_lds_dwordx4 v[208:209], off
	v_lshl_add_u64 v[208:209], s[86:87], 0, v[192:193]
	s_mov_b32 m0, s16
	s_nop 0
	global_load_lds_dwordx4 v[208:209], off
	s_mov_b32 m0, s17
	s_nop 0
	global_load_lds_dwordx4 v[210:211], off
	s_waitcnt vmcnt(8)
	s_waitcnt lgkmcnt(0)
	s_barrier
	s_setprio 1
	v_mfma_f32_16x16x32_bf16 v[60:63], v[120:123], v[160:163], v[60:63]
	v_mfma_f32_16x16x32_bf16 v[60:63], v[124:127], v[164:167], v[60:63]
	v_mfma_f32_16x16x32_bf16 v[56:59], v[128:131], v[160:163], v[56:59]
	v_mfma_f32_16x16x32_bf16 v[56:59], v[132:135], v[164:167], v[56:59]
	v_mfma_f32_16x16x32_bf16 v[44:47], v[120:123], v[168:171], v[44:47]
	v_mfma_f32_16x16x32_bf16 v[44:47], v[124:127], v[172:175], v[44:47]
	v_mfma_f32_16x16x32_bf16 v[40:43], v[128:131], v[168:171], v[40:43]
	v_mfma_f32_16x16x32_bf16 v[40:43], v[132:135], v[172:175], v[40:43]
	v_mfma_f32_16x16x32_bf16 v[28:31], v[120:123], v[176:179], v[28:31]
	v_mfma_f32_16x16x32_bf16 v[28:31], v[124:127], v[180:183], v[28:31]
	v_mfma_f32_16x16x32_bf16 v[24:27], v[128:131], v[176:179], v[24:27]
	v_mfma_f32_16x16x32_bf16 v[24:27], v[132:135], v[180:183], v[24:27]
	v_mfma_f32_16x16x32_bf16 v[12:15], v[120:123], v[184:187], v[12:15]
	v_mfma_f32_16x16x32_bf16 v[12:15], v[124:127], v[188:191], v[12:15]
	v_mfma_f32_16x16x32_bf16 v[8:11], v[128:131], v[184:187], v[8:11]
	v_mfma_f32_16x16x32_bf16 v[8:11], v[132:135], v[188:191], v[8:11]
	v_mfma_f32_16x16x32_bf16 v[52:55], v[144:147], v[160:163], v[52:55]
	v_mfma_f32_16x16x32_bf16 v[52:55], v[148:151], v[164:167], v[52:55]
	v_mfma_f32_16x16x32_bf16 v[48:51], v[152:155], v[160:163], v[48:51]
	v_mfma_f32_16x16x32_bf16 v[48:51], v[156:159], v[164:167], v[48:51]
	v_mfma_f32_16x16x32_bf16 v[36:39], v[144:147], v[168:171], v[36:39]
	v_mfma_f32_16x16x32_bf16 v[36:39], v[148:151], v[172:175], v[36:39]
	v_mfma_f32_16x16x32_bf16 v[32:35], v[152:155], v[168:171], v[32:35]
	v_mfma_f32_16x16x32_bf16 v[32:35], v[156:159], v[172:175], v[32:35]
	v_mfma_f32_16x16x32_bf16 v[20:23], v[144:147], v[176:179], v[20:23]
	v_mfma_f32_16x16x32_bf16 v[20:23], v[148:151], v[180:183], v[20:23]
	v_mfma_f32_16x16x32_bf16 v[16:19], v[152:155], v[176:179], v[16:19]
	v_mfma_f32_16x16x32_bf16 v[16:19], v[156:159], v[180:183], v[16:19]
	v_mfma_f32_16x16x32_bf16 v[4:7], v[144:147], v[184:187], v[4:7]
	v_mfma_f32_16x16x32_bf16 v[4:7], v[148:151], v[188:191], v[4:7]
	s_setprio 3
	s_barrier
	v_mfma_f32_16x16x32_bf16 v[0:3], v[152:155], v[184:187], v[0:3]
	v_mfma_f32_16x16x32_bf16 v[0:3], v[156:159], v[188:191], v[0:3]
	s_setprio 0
	s_add_i32 s59, 0, 0x18000
	s_add_i32 s68, 0, 0x1c000
	v_add_u32_e32 v132, s59, v243
	v_add_u32_e32 v156, s68, v243
	ds_read_b128 v[120:123], v132
	ds_read_b128 v[124:127], v132 offset:1024
	ds_read_b128 v[128:131], v132 offset:2048
	ds_read_b128 v[132:135], v132 offset:3072
	ds_read_b128 v[144:147], v156
	ds_read_b128 v[148:151], v156 offset:1024
	ds_read_b128 v[152:155], v156 offset:2048
	ds_read_b128 v[156:159], v156 offset:3072
	s_add_u32 s66, s86, 0x40000
	s_addc_u32 s67, s87, 0
	s_mov_b32 m0, s18
	v_lshl_add_u64 v[212:213], s[66:67], 0, v[192:193]
	ds_read_b128 v[160:163], v247 offset:32768
	ds_read_b128 v[164:167], v247 offset:33792
	ds_read_b128 v[168:171], v247 offset:34816
	ds_read_b128 v[172:175], v247 offset:35840
	ds_read_b128 v[176:179], v247 offset:36864
	ds_read_b128 v[180:183], v247 offset:37888
	ds_read_b128 v[184:187], v247 offset:38912
	ds_read_b128 v[188:191], v247 offset:39936
	global_load_lds_dwordx4 v[212:213], off
	v_lshl_add_u64 v[212:213], s[66:67], 0, v[196:197]
	s_mov_b32 m0, s19
	s_nop 0
	global_load_lds_dwordx4 v[212:213], off
	s_waitcnt vmcnt(8)
	s_waitcnt lgkmcnt(0)
	s_barrier
	s_setprio 1
	v_mfma_f32_16x16x32_bf16 v[140:143], v[120:123], v[160:163], v[140:143]
	v_mfma_f32_16x16x32_bf16 v[140:143], v[124:127], v[164:167], v[140:143]
	v_mfma_f32_16x16x32_bf16 v[136:139], v[128:131], v[160:163], v[136:139]
	v_mfma_f32_16x16x32_bf16 v[136:139], v[132:135], v[164:167], v[136:139]
	v_mfma_f32_16x16x32_bf16 v[108:111], v[120:123], v[168:171], v[108:111]
	v_mfma_f32_16x16x32_bf16 v[108:111], v[124:127], v[172:175], v[108:111]
	v_mfma_f32_16x16x32_bf16 v[104:107], v[128:131], v[168:171], v[104:107]
	v_mfma_f32_16x16x32_bf16 v[104:107], v[132:135], v[172:175], v[104:107]
	v_mfma_f32_16x16x32_bf16 v[92:95], v[120:123], v[176:179], v[92:95]
	v_mfma_f32_16x16x32_bf16 v[92:95], v[124:127], v[180:183], v[92:95]
	v_mfma_f32_16x16x32_bf16 v[88:91], v[128:131], v[176:179], v[88:91]
	v_mfma_f32_16x16x32_bf16 v[88:91], v[132:135], v[180:183], v[88:91]
	v_mfma_f32_16x16x32_bf16 v[76:79], v[120:123], v[184:187], v[76:79]
	v_mfma_f32_16x16x32_bf16 v[76:79], v[124:127], v[188:191], v[76:79]
	v_mfma_f32_16x16x32_bf16 v[72:75], v[128:131], v[184:187], v[72:75]
	v_mfma_f32_16x16x32_bf16 v[72:75], v[132:135], v[188:191], v[72:75]
	v_mfma_f32_16x16x32_bf16 v[116:119], v[144:147], v[160:163], v[116:119]
	v_mfma_f32_16x16x32_bf16 v[116:119], v[148:151], v[164:167], v[116:119]
	v_mfma_f32_16x16x32_bf16 v[112:115], v[152:155], v[160:163], v[112:115]
	v_mfma_f32_16x16x32_bf16 v[112:115], v[156:159], v[164:167], v[112:115]
	v_mfma_f32_16x16x32_bf16 v[100:103], v[144:147], v[168:171], v[100:103]
	v_mfma_f32_16x16x32_bf16 v[100:103], v[148:151], v[172:175], v[100:103]
	v_mfma_f32_16x16x32_bf16 v[96:99], v[152:155], v[168:171], v[96:99]
	v_mfma_f32_16x16x32_bf16 v[96:99], v[156:159], v[172:175], v[96:99]
	v_mfma_f32_16x16x32_bf16 v[84:87], v[144:147], v[176:179], v[84:87]
	v_mfma_f32_16x16x32_bf16 v[84:87], v[148:151], v[180:183], v[84:87]
	v_mfma_f32_16x16x32_bf16 v[80:83], v[152:155], v[176:179], v[80:83]
	v_mfma_f32_16x16x32_bf16 v[80:83], v[156:159], v[180:183], v[80:83]
	v_mfma_f32_16x16x32_bf16 v[68:71], v[144:147], v[184:187], v[68:71]
	v_mfma_f32_16x16x32_bf16 v[68:71], v[148:151], v[188:191], v[68:71]
	s_setprio 3
	s_barrier
	v_mfma_f32_16x16x32_bf16 v[64:67], v[152:155], v[184:187], v[64:67]
	v_mfma_f32_16x16x32_bf16 v[64:67], v[156:159], v[188:191], v[64:67]
	s_setprio 0
	s_add_i32 s59, s59, s15
	v_lshl_add_u64 v[204:205], v[204:205], 0, s[46:47]
	s_mov_b32 m0, s59
	ds_read_b128 v[160:163], v247 offset:49152
	ds_read_b128 v[164:167], v247 offset:50176
	ds_read_b128 v[168:171], v247 offset:51200
	ds_read_b128 v[172:175], v247 offset:52224
	ds_read_b128 v[176:179], v247 offset:53248
	ds_read_b128 v[180:183], v247 offset:54272
	ds_read_b128 v[184:187], v247 offset:55296
	ds_read_b128 v[188:191], v247 offset:56320
	global_load_lds_dwordx4 v[204:205], off
	s_add_i32 m0, s59, 0x2000
	s_add_u32 s66, s84, 0x40080
	v_lshl_add_u64 v[204:205], v[206:207], 0, s[46:47]
	s_addc_u32 s67, s85, 0
	s_add_i32 s59, s68, s15
	global_load_lds_dwordx4 v[204:205], off
	v_lshl_add_u64 v[204:205], s[66:67], 0, v[194:195]
	s_mov_b32 m0, s59
	s_nop 0
	global_load_lds_dwordx4 v[204:205], off
	v_lshl_add_u64 v[204:205], s[66:67], 0, v[198:199]
	s_add_i32 m0, s59, 0x2000
	s_nop 0
	global_load_lds_dwordx4 v[204:205], off
	v_lshl_add_u64 v[204:205], v[208:209], 0, s[46:47]
	s_mov_b32 m0, s21
	s_nop 0
	global_load_lds_dwordx4 v[204:205], off
	v_lshl_add_u64 v[204:205], v[210:211], 0, s[46:47]
	s_mov_b32 m0, s22
	s_nop 0
	global_load_lds_dwordx4 v[204:205], off
	s_waitcnt vmcnt(8)
	s_waitcnt lgkmcnt(0)
	s_barrier
	s_setprio 1
	v_mfma_f32_16x16x32_bf16 v[60:63], v[120:123], v[160:163], v[60:63]
	v_mfma_f32_16x16x32_bf16 v[60:63], v[124:127], v[164:167], v[60:63]
	v_mfma_f32_16x16x32_bf16 v[56:59], v[128:131], v[160:163], v[56:59]
	v_mfma_f32_16x16x32_bf16 v[56:59], v[132:135], v[164:167], v[56:59]
	v_mfma_f32_16x16x32_bf16 v[44:47], v[120:123], v[168:171], v[44:47]
	v_mfma_f32_16x16x32_bf16 v[44:47], v[124:127], v[172:175], v[44:47]
	v_mfma_f32_16x16x32_bf16 v[40:43], v[128:131], v[168:171], v[40:43]
	v_mfma_f32_16x16x32_bf16 v[40:43], v[132:135], v[172:175], v[40:43]
	v_mfma_f32_16x16x32_bf16 v[28:31], v[120:123], v[176:179], v[28:31]
	v_mfma_f32_16x16x32_bf16 v[28:31], v[124:127], v[180:183], v[28:31]
	v_mfma_f32_16x16x32_bf16 v[24:27], v[128:131], v[176:179], v[24:27]
	v_mfma_f32_16x16x32_bf16 v[24:27], v[132:135], v[180:183], v[24:27]
	v_mfma_f32_16x16x32_bf16 v[12:15], v[120:123], v[184:187], v[12:15]
	v_mfma_f32_16x16x32_bf16 v[12:15], v[124:127], v[188:191], v[12:15]
	v_mfma_f32_16x16x32_bf16 v[8:11], v[128:131], v[184:187], v[8:11]
	v_mfma_f32_16x16x32_bf16 v[8:11], v[132:135], v[188:191], v[8:11]
	v_mfma_f32_16x16x32_bf16 v[52:55], v[144:147], v[160:163], v[52:55]
	v_mfma_f32_16x16x32_bf16 v[52:55], v[148:151], v[164:167], v[52:55]
	v_mfma_f32_16x16x32_bf16 v[48:51], v[152:155], v[160:163], v[48:51]
	v_mfma_f32_16x16x32_bf16 v[48:51], v[156:159], v[164:167], v[48:51]
	v_mfma_f32_16x16x32_bf16 v[36:39], v[144:147], v[168:171], v[36:39]
	v_mfma_f32_16x16x32_bf16 v[36:39], v[148:151], v[172:175], v[36:39]
	v_mfma_f32_16x16x32_bf16 v[32:35], v[152:155], v[168:171], v[32:35]
	v_mfma_f32_16x16x32_bf16 v[32:35], v[156:159], v[172:175], v[32:35]
	v_mfma_f32_16x16x32_bf16 v[20:23], v[144:147], v[176:179], v[20:23]
	v_mfma_f32_16x16x32_bf16 v[20:23], v[148:151], v[180:183], v[20:23]
	v_mfma_f32_16x16x32_bf16 v[16:19], v[152:155], v[176:179], v[16:19]
	v_mfma_f32_16x16x32_bf16 v[16:19], v[156:159], v[180:183], v[16:19]
	v_mfma_f32_16x16x32_bf16 v[4:7], v[144:147], v[184:187], v[4:7]
	v_mfma_f32_16x16x32_bf16 v[4:7], v[148:151], v[188:191], v[4:7]
	s_setprio 3
	s_barrier
	v_mfma_f32_16x16x32_bf16 v[0:3], v[152:155], v[184:187], v[0:3]
	v_mfma_f32_16x16x32_bf16 v[0:3], v[156:159], v[188:191], v[0:3]
	s_setprio 0
	s_add_i32 s58, s58, 2
	s_add_u32 s82, s82, 0x100
	s_addc_u32 s83, s83, 0
	s_add_u32 s56, s56, 0x100
	s_addc_u32 s57, s57, 0
	s_cmp_gt_u32 s58, 13
	s_cbranch_scc0 .LBB0_993
	s_and_b64 vcc, exec, s[48:49]
	s_cbranch_vccz .LBB0_996
	s_barrier

.LBB0_1148:
	ds_read_b128 v[146:149], v174
	ds_read_b128 v[150:153], v174 offset:1024
	ds_read_b128 v[154:157], v174 offset:2048
	ds_read_b128 v[158:161], v174 offset:3072
	ds_read_b128 v[162:165], v175
	ds_read_b128 v[178:181], v175 offset:1024
	ds_read_b128 v[182:185], v175 offset:2048
	ds_read_b128 v[186:189], v175 offset:3072
	s_add_u32 s67, s78, 0xfffc0080
	s_addc_u32 s68, s79, -1
	s_cmp_eq_u32 s66, 12
	s_cselect_b32 s83, s49, s68
	s_cselect_b32 s82, s54, s67
	s_cselect_b32 s81, s47, s59
	s_cselect_b32 s80, s55, s58
	v_lshl_add_u64 v[166:167], s[78:79], 0, v[136:137]
	s_add_i32 m0, s17, 0xc000
	ds_read_b128 v[190:193], v176
	ds_read_b128 v[194:197], v176 offset:1024
	ds_read_b128 v[198:201], v176 offset:2048
	ds_read_b128 v[202:205], v176 offset:3072
	ds_read_b128 v[206:209], v176 offset:4096
	ds_read_b128 v[210:213], v176 offset:5120
	ds_read_b128 v[214:217], v176 offset:6144
	ds_read_b128 v[218:221], v176 offset:7168
	global_load_lds_dwordx4 v[166:167], off
	v_lshl_add_u64 v[166:167], s[78:79], 0, v[140:141]
	s_add_i32 m0, s17, 0xe000
	s_nop 0
	global_load_lds_dwordx4 v[166:167], off
	s_waitcnt vmcnt(8)
	s_waitcnt lgkmcnt(0)
	s_barrier
	s_setprio 1
	v_mfma_f32_16x16x32_bf16 v[124:127], v[146:149], v[190:193], v[124:127]
	v_mfma_f32_16x16x32_bf16 v[124:127], v[150:153], v[194:197], v[124:127]
	v_mfma_f32_16x16x32_bf16 v[116:119], v[154:157], v[190:193], v[116:119]
	v_mfma_f32_16x16x32_bf16 v[116:119], v[158:161], v[194:197], v[116:119]
	v_mfma_f32_16x16x32_bf16 v[108:111], v[146:149], v[198:201], v[108:111]
	v_mfma_f32_16x16x32_bf16 v[108:111], v[150:153], v[202:205], v[108:111]
	v_mfma_f32_16x16x32_bf16 v[100:103], v[154:157], v[198:201], v[100:103]
	v_mfma_f32_16x16x32_bf16 v[100:103], v[158:161], v[202:205], v[100:103]
	v_mfma_f32_16x16x32_bf16 v[92:95], v[146:149], v[206:209], v[92:95]
	v_mfma_f32_16x16x32_bf16 v[92:95], v[150:153], v[210:213], v[92:95]
	v_mfma_f32_16x16x32_bf16 v[84:87], v[154:157], v[206:209], v[84:87]
	v_mfma_f32_16x16x32_bf16 v[84:87], v[158:161], v[210:213], v[84:87]
	v_mfma_f32_16x16x32_bf16 v[76:79], v[146:149], v[214:217], v[76:79]
	v_mfma_f32_16x16x32_bf16 v[76:79], v[150:153], v[218:221], v[76:79]
	v_mfma_f32_16x16x32_bf16 v[68:71], v[154:157], v[214:217], v[68:71]
	v_mfma_f32_16x16x32_bf16 v[68:71], v[158:161], v[218:221], v[68:71]
	v_mfma_f32_16x16x32_bf16 v[120:123], v[162:165], v[190:193], v[120:123]
	v_mfma_f32_16x16x32_bf16 v[120:123], v[178:181], v[194:197], v[120:123]
	v_mfma_f32_16x16x32_bf16 v[112:115], v[182:185], v[190:193], v[112:115]
	v_mfma_f32_16x16x32_bf16 v[112:115], v[186:189], v[194:197], v[112:115]
	v_mfma_f32_16x16x32_bf16 v[104:107], v[162:165], v[198:201], v[104:107]
	v_mfma_f32_16x16x32_bf16 v[104:107], v[178:181], v[202:205], v[104:107]
	v_mfma_f32_16x16x32_bf16 v[96:99], v[182:185], v[198:201], v[96:99]
	v_mfma_f32_16x16x32_bf16 v[96:99], v[186:189], v[202:205], v[96:99]
	v_mfma_f32_16x16x32_bf16 v[88:91], v[162:165], v[206:209], v[88:91]
	v_mfma_f32_16x16x32_bf16 v[88:91], v[178:181], v[210:213], v[88:91]
	v_mfma_f32_16x16x32_bf16 v[80:83], v[182:185], v[206:209], v[80:83]
	v_mfma_f32_16x16x32_bf16 v[80:83], v[186:189], v[210:213], v[80:83]
	v_mfma_f32_16x16x32_bf16 v[72:75], v[162:165], v[214:217], v[72:75]
	v_mfma_f32_16x16x32_bf16 v[72:75], v[178:181], v[218:221], v[72:75]
	s_setprio 3
	s_barrier
	v_mfma_f32_16x16x32_bf16 v[64:67], v[182:185], v[214:217], v[64:67]
	v_mfma_f32_16x16x32_bf16 v[64:67], v[186:189], v[218:221], v[64:67]
	s_setprio 0
	s_add_i32 s67, s25, s16
	v_lshl_add_u64 v[166:167], s[80:81], 0, v[132:133]
	s_mov_b32 m0, s67
	ds_read_b128 v[190:193], v176 offset:16384
	ds_read_b128 v[194:197], v176 offset:17408
	ds_read_b128 v[198:201], v176 offset:18432
	ds_read_b128 v[202:205], v176 offset:19456
	ds_read_b128 v[206:209], v176 offset:20480
	ds_read_b128 v[210:213], v176 offset:21504
	ds_read_b128 v[214:217], v176 offset:22528
	ds_read_b128 v[218:221], v176 offset:23552
	global_load_lds_dwordx4 v[166:167], off
	s_add_i32 m0, s67, 0x2000
	s_add_u32 s68, s80, 0x40000
	v_lshl_add_u64 v[222:223], s[80:81], 0, v[128:129]
	s_addc_u32 s69, s81, 0
	s_add_i32 s67, s26, s16
	global_load_lds_dwordx4 v[222:223], off
	v_lshl_add_u64 v[224:225], s[68:69], 0, v[132:133]
	s_mov_b32 m0, s67
	v_lshl_add_u64 v[226:227], s[82:83], 0, v[130:131]
	global_load_lds_dwordx4 v[224:225], off
	v_lshl_add_u64 v[224:225], s[68:69], 0, v[128:129]
	s_add_i32 m0, s67, 0x2000
	s_nop 0
	global_load_lds_dwordx4 v[224:225], off
	v_lshl_add_u64 v[224:225], s[82:83], 0, v[134:135]
	s_mov_b32 m0, s17
	s_nop 0
	global_load_lds_dwordx4 v[224:225], off
	s_mov_b32 m0, s18
	s_nop 0
	global_load_lds_dwordx4 v[226:227], off
	s_waitcnt vmcnt(8)
	s_waitcnt lgkmcnt(0)
	s_barrier
	s_setprio 1
	v_mfma_f32_16x16x32_bf16 v[60:63], v[146:149], v[190:193], v[60:63]
	v_mfma_f32_16x16x32_bf16 v[60:63], v[150:153], v[194:197], v[60:63]
	v_mfma_f32_16x16x32_bf16 v[52:55], v[154:157], v[190:193], v[52:55]
	v_mfma_f32_16x16x32_bf16 v[52:55], v[158:161], v[194:197], v[52:55]
	v_mfma_f32_16x16x32_bf16 v[44:47], v[146:149], v[198:201], v[44:47]
	v_mfma_f32_16x16x32_bf16 v[44:47], v[150:153], v[202:205], v[44:47]
	v_mfma_f32_16x16x32_bf16 v[36:39], v[154:157], v[198:201], v[36:39]
	v_mfma_f32_16x16x32_bf16 v[36:39], v[158:161], v[202:205], v[36:39]
	v_mfma_f32_16x16x32_bf16 v[28:31], v[146:149], v[206:209], v[28:31]
	v_mfma_f32_16x16x32_bf16 v[28:31], v[150:153], v[210:213], v[28:31]
	v_mfma_f32_16x16x32_bf16 v[20:23], v[154:157], v[206:209], v[20:23]
	v_mfma_f32_16x16x32_bf16 v[20:23], v[158:161], v[210:213], v[20:23]
	v_mfma_f32_16x16x32_bf16 v[12:15], v[146:149], v[214:217], v[12:15]
	v_mfma_f32_16x16x32_bf16 v[12:15], v[150:153], v[218:221], v[12:15]
	v_mfma_f32_16x16x32_bf16 v[4:7], v[154:157], v[214:217], v[4:7]
	v_mfma_f32_16x16x32_bf16 v[4:7], v[158:161], v[218:221], v[4:7]
	v_mfma_f32_16x16x32_bf16 v[56:59], v[162:165], v[190:193], v[56:59]
	v_mfma_f32_16x16x32_bf16 v[56:59], v[178:181], v[194:197], v[56:59]
	v_mfma_f32_16x16x32_bf16 v[48:51], v[182:185], v[190:193], v[48:51]
	v_mfma_f32_16x16x32_bf16 v[48:51], v[186:189], v[194:197], v[48:51]
	v_mfma_f32_16x16x32_bf16 v[40:43], v[162:165], v[198:201], v[40:43]
	v_mfma_f32_16x16x32_bf16 v[40:43], v[178:181], v[202:205], v[40:43]
	v_mfma_f32_16x16x32_bf16 v[32:35], v[182:185], v[198:201], v[32:35]
	v_mfma_f32_16x16x32_bf16 v[32:35], v[186:189], v[202:205], v[32:35]
	v_mfma_f32_16x16x32_bf16 v[24:27], v[162:165], v[206:209], v[24:27]
	v_mfma_f32_16x16x32_bf16 v[24:27], v[178:181], v[210:213], v[24:27]
	v_mfma_f32_16x16x32_bf16 v[16:19], v[182:185], v[206:209], v[16:19]
	v_mfma_f32_16x16x32_bf16 v[16:19], v[186:189], v[210:213], v[16:19]
	v_mfma_f32_16x16x32_bf16 v[8:11], v[162:165], v[214:217], v[8:11]
	v_mfma_f32_16x16x32_bf16 v[8:11], v[178:181], v[218:221], v[8:11]
	s_setprio 3
	s_barrier
	v_mfma_f32_16x16x32_bf16 v[0:3], v[182:185], v[214:217], v[0:3]
	v_mfma_f32_16x16x32_bf16 v[0:3], v[186:189], v[218:221], v[0:3]
	s_setprio 0
	s_add_i32 s67, 0, 0x18000
	s_add_i32 s73, 0, 0x1c000
	v_add_u32_e32 v158, s67, v171
	v_add_u32_e32 v186, s73, v171
	ds_read_b128 v[146:149], v158
	ds_read_b128 v[150:153], v158 offset:1024
	ds_read_b128 v[154:157], v158 offset:2048
	ds_read_b128 v[158:161], v158 offset:3072
	ds_read_b128 v[162:165], v186
	ds_read_b128 v[178:181], v186 offset:1024
	ds_read_b128 v[182:185], v186 offset:2048
	ds_read_b128 v[186:189], v186 offset:3072
	s_add_u32 s68, s82, 0x40000
	s_addc_u32 s69, s83, 0
	s_mov_b32 m0, s19
	v_lshl_add_u64 v[228:229], s[68:69], 0, v[134:135]
	ds_read_b128 v[190:193], v176 offset:32768
	ds_read_b128 v[194:197], v176 offset:33792
	ds_read_b128 v[198:201], v176 offset:34816
	ds_read_b128 v[202:205], v176 offset:35840
	ds_read_b128 v[206:209], v176 offset:36864
	ds_read_b128 v[210:213], v176 offset:37888
	ds_read_b128 v[214:217], v176 offset:38912
	ds_read_b128 v[218:221], v176 offset:39936
	global_load_lds_dwordx4 v[228:229], off
	v_lshl_add_u64 v[228:229], s[68:69], 0, v[130:131]
	s_mov_b32 m0, s20
	s_nop 0
	global_load_lds_dwordx4 v[228:229], off
	s_waitcnt vmcnt(8)
	s_waitcnt lgkmcnt(0)
	s_barrier
	s_setprio 1
	v_mfma_f32_16x16x32_bf16 v[124:127], v[146:149], v[190:193], v[124:127]
	v_mfma_f32_16x16x32_bf16 v[124:127], v[150:153], v[194:197], v[124:127]
	v_mfma_f32_16x16x32_bf16 v[116:119], v[154:157], v[190:193], v[116:119]
	v_mfma_f32_16x16x32_bf16 v[116:119], v[158:161], v[194:197], v[116:119]
	v_mfma_f32_16x16x32_bf16 v[108:111], v[146:149], v[198:201], v[108:111]
	v_mfma_f32_16x16x32_bf16 v[108:111], v[150:153], v[202:205], v[108:111]
	v_mfma_f32_16x16x32_bf16 v[100:103], v[154:157], v[198:201], v[100:103]
	v_mfma_f32_16x16x32_bf16 v[100:103], v[158:161], v[202:205], v[100:103]
	v_mfma_f32_16x16x32_bf16 v[92:95], v[146:149], v[206:209], v[92:95]
	v_mfma_f32_16x16x32_bf16 v[92:95], v[150:153], v[210:213], v[92:95]
	v_mfma_f32_16x16x32_bf16 v[84:87], v[154:157], v[206:209], v[84:87]
	v_mfma_f32_16x16x32_bf16 v[84:87], v[158:161], v[210:213], v[84:87]
	v_mfma_f32_16x16x32_bf16 v[76:79], v[146:149], v[214:217], v[76:79]
	v_mfma_f32_16x16x32_bf16 v[76:79], v[150:153], v[218:221], v[76:79]
	v_mfma_f32_16x16x32_bf16 v[68:71], v[154:157], v[214:217], v[68:71]
	v_mfma_f32_16x16x32_bf16 v[68:71], v[158:161], v[218:221], v[68:71]
	v_mfma_f32_16x16x32_bf16 v[120:123], v[162:165], v[190:193], v[120:123]
	v_mfma_f32_16x16x32_bf16 v[120:123], v[178:181], v[194:197], v[120:123]
	v_mfma_f32_16x16x32_bf16 v[112:115], v[182:185], v[190:193], v[112:115]
	v_mfma_f32_16x16x32_bf16 v[112:115], v[186:189], v[194:197], v[112:115]
	v_mfma_f32_16x16x32_bf16 v[104:107], v[162:165], v[198:201], v[104:107]
	v_mfma_f32_16x16x32_bf16 v[104:107], v[178:181], v[202:205], v[104:107]
	v_mfma_f32_16x16x32_bf16 v[96:99], v[182:185], v[198:201], v[96:99]
	v_mfma_f32_16x16x32_bf16 v[96:99], v[186:189], v[202:205], v[96:99]
	v_mfma_f32_16x16x32_bf16 v[88:91], v[162:165], v[206:209], v[88:91]
	v_mfma_f32_16x16x32_bf16 v[88:91], v[178:181], v[210:213], v[88:91]
	v_mfma_f32_16x16x32_bf16 v[80:83], v[182:185], v[206:209], v[80:83]
	v_mfma_f32_16x16x32_bf16 v[80:83], v[186:189], v[210:213], v[80:83]
	v_mfma_f32_16x16x32_bf16 v[72:75], v[162:165], v[214:217], v[72:75]
	v_mfma_f32_16x16x32_bf16 v[72:75], v[178:181], v[218:221], v[72:75]
	s_setprio 3
	s_barrier
	v_mfma_f32_16x16x32_bf16 v[64:67], v[182:185], v[214:217], v[64:67]
	v_mfma_f32_16x16x32_bf16 v[64:67], v[186:189], v[218:221], v[64:67]
	s_setprio 0
	s_add_i32 s67, s67, s16
	v_lshl_add_u64 v[166:167], v[166:167], 0, s[10:11]
	s_mov_b32 m0, s67
	ds_read_b128 v[190:193], v176 offset:49152
	ds_read_b128 v[194:197], v176 offset:50176
	ds_read_b128 v[198:201], v176 offset:51200
	ds_read_b128 v[202:205], v176 offset:52224
	ds_read_b128 v[206:209], v176 offset:53248
	ds_read_b128 v[210:213], v176 offset:54272
	ds_read_b128 v[214:217], v176 offset:55296
	ds_read_b128 v[218:221], v176 offset:56320
	global_load_lds_dwordx4 v[166:167], off
	s_add_i32 m0, s67, 0x2000
	s_add_u32 s68, s80, 0x40080
	v_lshl_add_u64 v[166:167], v[222:223], 0, s[10:11]
	s_addc_u32 s69, s81, 0
	s_add_i32 s67, s73, s16
	global_load_lds_dwordx4 v[166:167], off
	v_lshl_add_u64 v[166:167], s[68:69], 0, v[132:133]
	s_mov_b32 m0, s67
	s_nop 0
	global_load_lds_dwordx4 v[166:167], off
	v_lshl_add_u64 v[166:167], s[68:69], 0, v[128:129]
	s_add_i32 m0, s67, 0x2000
	s_nop 0
	global_load_lds_dwordx4 v[166:167], off
	v_lshl_add_u64 v[166:167], v[224:225], 0, s[10:11]
	s_mov_b32 m0, s23
	s_nop 0
	global_load_lds_dwordx4 v[166:167], off
	v_lshl_add_u64 v[166:167], v[226:227], 0, s[10:11]
	s_mov_b32 m0, s24
	s_nop 0
	global_load_lds_dwordx4 v[166:167], off
	s_waitcnt vmcnt(8)
	s_waitcnt lgkmcnt(0)
	s_barrier
	s_setprio 1
	v_mfma_f32_16x16x32_bf16 v[60:63], v[146:149], v[190:193], v[60:63]
	v_mfma_f32_16x16x32_bf16 v[60:63], v[150:153], v[194:197], v[60:63]
	v_mfma_f32_16x16x32_bf16 v[52:55], v[154:157], v[190:193], v[52:55]
	v_mfma_f32_16x16x32_bf16 v[52:55], v[158:161], v[194:197], v[52:55]
	v_mfma_f32_16x16x32_bf16 v[44:47], v[146:149], v[198:201], v[44:47]
	v_mfma_f32_16x16x32_bf16 v[44:47], v[150:153], v[202:205], v[44:47]
	v_mfma_f32_16x16x32_bf16 v[36:39], v[154:157], v[198:201], v[36:39]
	v_mfma_f32_16x16x32_bf16 v[36:39], v[158:161], v[202:205], v[36:39]
	v_mfma_f32_16x16x32_bf16 v[28:31], v[146:149], v[206:209], v[28:31]
	v_mfma_f32_16x16x32_bf16 v[28:31], v[150:153], v[210:213], v[28:31]
	v_mfma_f32_16x16x32_bf16 v[20:23], v[154:157], v[206:209], v[20:23]
	v_mfma_f32_16x16x32_bf16 v[20:23], v[158:161], v[210:213], v[20:23]
	v_mfma_f32_16x16x32_bf16 v[12:15], v[146:149], v[214:217], v[12:15]
	v_mfma_f32_16x16x32_bf16 v[12:15], v[150:153], v[218:221], v[12:15]
	v_mfma_f32_16x16x32_bf16 v[4:7], v[154:157], v[214:217], v[4:7]
	v_mfma_f32_16x16x32_bf16 v[4:7], v[158:161], v[218:221], v[4:7]
	v_mfma_f32_16x16x32_bf16 v[56:59], v[162:165], v[190:193], v[56:59]
	v_mfma_f32_16x16x32_bf16 v[56:59], v[178:181], v[194:197], v[56:59]
	v_mfma_f32_16x16x32_bf16 v[48:51], v[182:185], v[190:193], v[48:51]
	v_mfma_f32_16x16x32_bf16 v[48:51], v[186:189], v[194:197], v[48:51]
	v_mfma_f32_16x16x32_bf16 v[40:43], v[162:165], v[198:201], v[40:43]
	v_mfma_f32_16x16x32_bf16 v[40:43], v[178:181], v[202:205], v[40:43]
	v_mfma_f32_16x16x32_bf16 v[32:35], v[182:185], v[198:201], v[32:35]
	v_mfma_f32_16x16x32_bf16 v[32:35], v[186:189], v[202:205], v[32:35]
	v_mfma_f32_16x16x32_bf16 v[24:27], v[162:165], v[206:209], v[24:27]
	v_mfma_f32_16x16x32_bf16 v[24:27], v[178:181], v[210:213], v[24:27]
	v_mfma_f32_16x16x32_bf16 v[16:19], v[182:185], v[206:209], v[16:19]
	v_mfma_f32_16x16x32_bf16 v[16:19], v[186:189], v[210:213], v[16:19]
	v_mfma_f32_16x16x32_bf16 v[8:11], v[162:165], v[214:217], v[8:11]
	v_mfma_f32_16x16x32_bf16 v[8:11], v[178:181], v[218:221], v[8:11]
	s_setprio 3
	s_barrier
	v_mfma_f32_16x16x32_bf16 v[0:3], v[182:185], v[214:217], v[0:3]
	v_mfma_f32_16x16x32_bf16 v[0:3], v[186:189], v[218:221], v[0:3]
	s_setprio 0
	s_add_i32 s66, s66, 2
	s_add_u32 s78, s78, 0x100
	s_addc_u32 s79, s79, 0
	s_add_u32 s58, s58, 0x100
	s_addc_u32 s59, s59, 0
	s_cmp_gt_u32 s66, 13
	s_cbranch_scc0 .LBB0_1148
	s_and_b64 vcc, exec, s[44:45]
	s_cbranch_vccz .LBB0_1151
	s_barrier

.LBB0_1299:
	ds_read_b128 v[120:123], v245
	ds_read_b128 v[124:127], v245 offset:1024
	ds_read_b128 v[128:131], v245 offset:2048
	ds_read_b128 v[132:135], v245 offset:3072
	ds_read_b128 v[144:147], v246
	ds_read_b128 v[148:151], v246 offset:1024
	ds_read_b128 v[152:155], v246 offset:2048
	ds_read_b128 v[156:159], v246 offset:3072
	s_add_u32 s66, s76, 0xfff50080
	s_addc_u32 s67, s77, -1
	s_cmp_eq_u32 s59, 40
	s_cselect_b32 s81, s9, s67
	s_cselect_b32 s80, s8, s66
	s_cselect_b32 s79, s53, s58
	s_cselect_b32 s78, s52, s55
	v_lshl_add_u64 v[204:205], s[76:77], 0, v[200:201]
	s_add_i32 m0, s16, 0xc000
	ds_read_b128 v[160:163], v247
	ds_read_b128 v[164:167], v247 offset:1024
	ds_read_b128 v[168:171], v247 offset:2048
	ds_read_b128 v[172:175], v247 offset:3072
	ds_read_b128 v[176:179], v247 offset:4096
	ds_read_b128 v[180:183], v247 offset:5120
	ds_read_b128 v[184:187], v247 offset:6144
	ds_read_b128 v[188:191], v247 offset:7168
	global_load_lds_dwordx4 v[204:205], off
	v_lshl_add_u64 v[204:205], s[76:77], 0, v[202:203]
	s_add_i32 m0, s16, 0xe000
	s_nop 0
	global_load_lds_dwordx4 v[204:205], off
	s_waitcnt vmcnt(8)
	s_waitcnt lgkmcnt(0)
	s_barrier
	s_setprio 1
	v_mfma_f32_16x16x32_bf16 v[140:143], v[120:123], v[160:163], v[140:143]
	v_mfma_f32_16x16x32_bf16 v[140:143], v[124:127], v[164:167], v[140:143]
	v_mfma_f32_16x16x32_bf16 v[136:139], v[128:131], v[160:163], v[136:139]
	v_mfma_f32_16x16x32_bf16 v[136:139], v[132:135], v[164:167], v[136:139]
	v_mfma_f32_16x16x32_bf16 v[108:111], v[120:123], v[168:171], v[108:111]
	v_mfma_f32_16x16x32_bf16 v[108:111], v[124:127], v[172:175], v[108:111]
	v_mfma_f32_16x16x32_bf16 v[104:107], v[128:131], v[168:171], v[104:107]
	v_mfma_f32_16x16x32_bf16 v[104:107], v[132:135], v[172:175], v[104:107]
	v_mfma_f32_16x16x32_bf16 v[92:95], v[120:123], v[176:179], v[92:95]
	v_mfma_f32_16x16x32_bf16 v[92:95], v[124:127], v[180:183], v[92:95]
	v_mfma_f32_16x16x32_bf16 v[88:91], v[128:131], v[176:179], v[88:91]
	v_mfma_f32_16x16x32_bf16 v[88:91], v[132:135], v[180:183], v[88:91]
	v_mfma_f32_16x16x32_bf16 v[76:79], v[120:123], v[184:187], v[76:79]
	v_mfma_f32_16x16x32_bf16 v[76:79], v[124:127], v[188:191], v[76:79]
	v_mfma_f32_16x16x32_bf16 v[72:75], v[128:131], v[184:187], v[72:75]
	v_mfma_f32_16x16x32_bf16 v[72:75], v[132:135], v[188:191], v[72:75]
	v_mfma_f32_16x16x32_bf16 v[116:119], v[144:147], v[160:163], v[116:119]
	v_mfma_f32_16x16x32_bf16 v[116:119], v[148:151], v[164:167], v[116:119]
	v_mfma_f32_16x16x32_bf16 v[112:115], v[152:155], v[160:163], v[112:115]
	v_mfma_f32_16x16x32_bf16 v[112:115], v[156:159], v[164:167], v[112:115]
	v_mfma_f32_16x16x32_bf16 v[100:103], v[144:147], v[168:171], v[100:103]
	v_mfma_f32_16x16x32_bf16 v[100:103], v[148:151], v[172:175], v[100:103]
	v_mfma_f32_16x16x32_bf16 v[96:99], v[152:155], v[168:171], v[96:99]
	v_mfma_f32_16x16x32_bf16 v[96:99], v[156:159], v[172:175], v[96:99]
	v_mfma_f32_16x16x32_bf16 v[84:87], v[144:147], v[176:179], v[84:87]
	v_mfma_f32_16x16x32_bf16 v[84:87], v[148:151], v[180:183], v[84:87]
	v_mfma_f32_16x16x32_bf16 v[80:83], v[152:155], v[176:179], v[80:83]
	v_mfma_f32_16x16x32_bf16 v[80:83], v[156:159], v[180:183], v[80:83]
	v_mfma_f32_16x16x32_bf16 v[68:71], v[144:147], v[184:187], v[68:71]
	v_mfma_f32_16x16x32_bf16 v[68:71], v[148:151], v[188:191], v[68:71]
	s_setprio 3
	s_barrier
	v_mfma_f32_16x16x32_bf16 v[64:67], v[152:155], v[184:187], v[64:67]
	v_mfma_f32_16x16x32_bf16 v[64:67], v[156:159], v[188:191], v[64:67]
	s_setprio 0
	s_add_i32 s66, s26, s15
	v_lshl_add_u64 v[204:205], s[78:79], 0, v[194:195]
	s_mov_b32 m0, s66
	ds_read_b128 v[160:163], v247 offset:16384
	ds_read_b128 v[164:167], v247 offset:17408
	ds_read_b128 v[168:171], v247 offset:18432
	ds_read_b128 v[172:175], v247 offset:19456
	ds_read_b128 v[176:179], v247 offset:20480
	ds_read_b128 v[180:183], v247 offset:21504
	ds_read_b128 v[184:187], v247 offset:22528
	ds_read_b128 v[188:191], v247 offset:23552
	global_load_lds_dwordx4 v[204:205], off
	s_add_i32 m0, s66, 0x2000
	s_add_u32 s66, s78, 0xb0000
	v_lshl_add_u64 v[206:207], s[78:79], 0, v[198:199]
	s_addc_u32 s67, s79, 0
	s_add_i32 s68, s27, s15
	global_load_lds_dwordx4 v[206:207], off
	v_lshl_add_u64 v[208:209], s[66:67], 0, v[194:195]
	s_mov_b32 m0, s68
	v_lshl_add_u64 v[210:211], s[80:81], 0, v[196:197]
	global_load_lds_dwordx4 v[208:209], off
	v_lshl_add_u64 v[208:209], s[66:67], 0, v[198:199]
	s_add_i32 m0, s68, 0x2000
	s_nop 0
	global_load_lds_dwordx4 v[208:209], off
	v_lshl_add_u64 v[208:209], s[80:81], 0, v[192:193]
	s_mov_b32 m0, s16
	s_nop 0
	global_load_lds_dwordx4 v[208:209], off
	s_mov_b32 m0, s17
	s_nop 0
	global_load_lds_dwordx4 v[210:211], off
	s_waitcnt vmcnt(8)
	s_waitcnt lgkmcnt(0)
	s_barrier
	s_setprio 1
	v_mfma_f32_16x16x32_bf16 v[60:63], v[120:123], v[160:163], v[60:63]
	v_mfma_f32_16x16x32_bf16 v[60:63], v[124:127], v[164:167], v[60:63]
	v_mfma_f32_16x16x32_bf16 v[56:59], v[128:131], v[160:163], v[56:59]
	v_mfma_f32_16x16x32_bf16 v[56:59], v[132:135], v[164:167], v[56:59]
	v_mfma_f32_16x16x32_bf16 v[44:47], v[120:123], v[168:171], v[44:47]
	v_mfma_f32_16x16x32_bf16 v[44:47], v[124:127], v[172:175], v[44:47]
	v_mfma_f32_16x16x32_bf16 v[40:43], v[128:131], v[168:171], v[40:43]
	v_mfma_f32_16x16x32_bf16 v[40:43], v[132:135], v[172:175], v[40:43]
	v_mfma_f32_16x16x32_bf16 v[28:31], v[120:123], v[176:179], v[28:31]
	v_mfma_f32_16x16x32_bf16 v[28:31], v[124:127], v[180:183], v[28:31]
	v_mfma_f32_16x16x32_bf16 v[24:27], v[128:131], v[176:179], v[24:27]
	v_mfma_f32_16x16x32_bf16 v[24:27], v[132:135], v[180:183], v[24:27]
	v_mfma_f32_16x16x32_bf16 v[12:15], v[120:123], v[184:187], v[12:15]
	v_mfma_f32_16x16x32_bf16 v[12:15], v[124:127], v[188:191], v[12:15]
	v_mfma_f32_16x16x32_bf16 v[8:11], v[128:131], v[184:187], v[8:11]
	v_mfma_f32_16x16x32_bf16 v[8:11], v[132:135], v[188:191], v[8:11]
	v_mfma_f32_16x16x32_bf16 v[52:55], v[144:147], v[160:163], v[52:55]
	v_mfma_f32_16x16x32_bf16 v[52:55], v[148:151], v[164:167], v[52:55]
	v_mfma_f32_16x16x32_bf16 v[48:51], v[152:155], v[160:163], v[48:51]
	v_mfma_f32_16x16x32_bf16 v[48:51], v[156:159], v[164:167], v[48:51]
	v_mfma_f32_16x16x32_bf16 v[36:39], v[144:147], v[168:171], v[36:39]
	v_mfma_f32_16x16x32_bf16 v[36:39], v[148:151], v[172:175], v[36:39]
	v_mfma_f32_16x16x32_bf16 v[32:35], v[152:155], v[168:171], v[32:35]
	v_mfma_f32_16x16x32_bf16 v[32:35], v[156:159], v[172:175], v[32:35]
	v_mfma_f32_16x16x32_bf16 v[20:23], v[144:147], v[176:179], v[20:23]
	v_mfma_f32_16x16x32_bf16 v[20:23], v[148:151], v[180:183], v[20:23]
	v_mfma_f32_16x16x32_bf16 v[16:19], v[152:155], v[176:179], v[16:19]
	v_mfma_f32_16x16x32_bf16 v[16:19], v[156:159], v[180:183], v[16:19]
	v_mfma_f32_16x16x32_bf16 v[4:7], v[144:147], v[184:187], v[4:7]
	v_mfma_f32_16x16x32_bf16 v[4:7], v[148:151], v[188:191], v[4:7]
	s_setprio 3
	s_barrier
	v_mfma_f32_16x16x32_bf16 v[0:3], v[152:155], v[184:187], v[0:3]
	v_mfma_f32_16x16x32_bf16 v[0:3], v[156:159], v[188:191], v[0:3]
	s_setprio 0
	s_add_i32 s68, 0, 0x18000
	s_add_i32 s69, 0, 0x1c000
	v_add_u32_e32 v132, s68, v243
	v_add_u32_e32 v156, s69, v243
	ds_read_b128 v[120:123], v132
	ds_read_b128 v[124:127], v132 offset:1024
	ds_read_b128 v[128:131], v132 offset:2048
	ds_read_b128 v[132:135], v132 offset:3072
	ds_read_b128 v[144:147], v156
	ds_read_b128 v[148:151], v156 offset:1024
	ds_read_b128 v[152:155], v156 offset:2048
	ds_read_b128 v[156:159], v156 offset:3072
	s_add_u32 s66, s80, 0xb0000
	s_addc_u32 s67, s81, 0
	s_mov_b32 m0, s18
	v_lshl_add_u64 v[212:213], s[66:67], 0, v[192:193]
	ds_read_b128 v[160:163], v247 offset:32768
	ds_read_b128 v[164:167], v247 offset:33792
	ds_read_b128 v[168:171], v247 offset:34816
	ds_read_b128 v[172:175], v247 offset:35840
	ds_read_b128 v[176:179], v247 offset:36864
	ds_read_b128 v[180:183], v247 offset:37888
	ds_read_b128 v[184:187], v247 offset:38912
	ds_read_b128 v[188:191], v247 offset:39936
	global_load_lds_dwordx4 v[212:213], off
	v_lshl_add_u64 v[212:213], s[66:67], 0, v[196:197]
	s_mov_b32 m0, s19
	s_nop 0
	global_load_lds_dwordx4 v[212:213], off
	s_waitcnt vmcnt(8)
	s_waitcnt lgkmcnt(0)
	s_barrier
	s_setprio 1
	v_mfma_f32_16x16x32_bf16 v[140:143], v[120:123], v[160:163], v[140:143]
	v_mfma_f32_16x16x32_bf16 v[140:143], v[124:127], v[164:167], v[140:143]
	v_mfma_f32_16x16x32_bf16 v[136:139], v[128:131], v[160:163], v[136:139]
	v_mfma_f32_16x16x32_bf16 v[136:139], v[132:135], v[164:167], v[136:139]
	v_mfma_f32_16x16x32_bf16 v[108:111], v[120:123], v[168:171], v[108:111]
	v_mfma_f32_16x16x32_bf16 v[108:111], v[124:127], v[172:175], v[108:111]
	v_mfma_f32_16x16x32_bf16 v[104:107], v[128:131], v[168:171], v[104:107]
	v_mfma_f32_16x16x32_bf16 v[104:107], v[132:135], v[172:175], v[104:107]
	v_mfma_f32_16x16x32_bf16 v[92:95], v[120:123], v[176:179], v[92:95]
	v_mfma_f32_16x16x32_bf16 v[92:95], v[124:127], v[180:183], v[92:95]
	v_mfma_f32_16x16x32_bf16 v[88:91], v[128:131], v[176:179], v[88:91]
	v_mfma_f32_16x16x32_bf16 v[88:91], v[132:135], v[180:183], v[88:91]
	v_mfma_f32_16x16x32_bf16 v[76:79], v[120:123], v[184:187], v[76:79]
	v_mfma_f32_16x16x32_bf16 v[76:79], v[124:127], v[188:191], v[76:79]
	v_mfma_f32_16x16x32_bf16 v[72:75], v[128:131], v[184:187], v[72:75]
	v_mfma_f32_16x16x32_bf16 v[72:75], v[132:135], v[188:191], v[72:75]
	v_mfma_f32_16x16x32_bf16 v[116:119], v[144:147], v[160:163], v[116:119]
	v_mfma_f32_16x16x32_bf16 v[116:119], v[148:151], v[164:167], v[116:119]
	v_mfma_f32_16x16x32_bf16 v[112:115], v[152:155], v[160:163], v[112:115]
	v_mfma_f32_16x16x32_bf16 v[112:115], v[156:159], v[164:167], v[112:115]
	v_mfma_f32_16x16x32_bf16 v[100:103], v[144:147], v[168:171], v[100:103]
	v_mfma_f32_16x16x32_bf16 v[100:103], v[148:151], v[172:175], v[100:103]
	v_mfma_f32_16x16x32_bf16 v[96:99], v[152:155], v[168:171], v[96:99]
	v_mfma_f32_16x16x32_bf16 v[96:99], v[156:159], v[172:175], v[96:99]
	v_mfma_f32_16x16x32_bf16 v[84:87], v[144:147], v[176:179], v[84:87]
	v_mfma_f32_16x16x32_bf16 v[84:87], v[148:151], v[180:183], v[84:87]
	v_mfma_f32_16x16x32_bf16 v[80:83], v[152:155], v[176:179], v[80:83]
	v_mfma_f32_16x16x32_bf16 v[80:83], v[156:159], v[180:183], v[80:83]
	v_mfma_f32_16x16x32_bf16 v[68:71], v[144:147], v[184:187], v[68:71]
	v_mfma_f32_16x16x32_bf16 v[68:71], v[148:151], v[188:191], v[68:71]
	s_setprio 3
	s_barrier
	v_mfma_f32_16x16x32_bf16 v[64:67], v[152:155], v[184:187], v[64:67]
	v_mfma_f32_16x16x32_bf16 v[64:67], v[156:159], v[188:191], v[64:67]
	s_setprio 0
	s_add_i32 s66, s68, s15
	v_lshl_add_u64 v[204:205], v[204:205], 0, s[48:49]
	s_mov_b32 m0, s66
	ds_read_b128 v[160:163], v247 offset:49152
	ds_read_b128 v[164:167], v247 offset:50176
	ds_read_b128 v[168:171], v247 offset:51200
	ds_read_b128 v[172:175], v247 offset:52224
	ds_read_b128 v[176:179], v247 offset:53248
	ds_read_b128 v[180:183], v247 offset:54272
	ds_read_b128 v[184:187], v247 offset:55296
	ds_read_b128 v[188:191], v247 offset:56320
	global_load_lds_dwordx4 v[204:205], off
	s_add_i32 m0, s66, 0x2000
	s_add_u32 s66, s78, 0xb0080
	v_lshl_add_u64 v[204:205], v[206:207], 0, s[48:49]
	s_addc_u32 s67, s79, 0
	s_add_i32 s68, s69, s15
	global_load_lds_dwordx4 v[204:205], off
	v_lshl_add_u64 v[204:205], s[66:67], 0, v[194:195]
	s_mov_b32 m0, s68
	s_nop 0
	global_load_lds_dwordx4 v[204:205], off
	v_lshl_add_u64 v[204:205], s[66:67], 0, v[198:199]
	s_add_i32 m0, s68, 0x2000
	s_nop 0
	global_load_lds_dwordx4 v[204:205], off
	v_lshl_add_u64 v[204:205], v[208:209], 0, s[48:49]
	s_mov_b32 m0, s21
	s_nop 0
	global_load_lds_dwordx4 v[204:205], off
	v_lshl_add_u64 v[204:205], v[210:211], 0, s[48:49]
	s_mov_b32 m0, s22
	s_nop 0
	global_load_lds_dwordx4 v[204:205], off
	s_waitcnt vmcnt(8)
	s_waitcnt lgkmcnt(0)
	s_barrier
	s_setprio 1
	v_mfma_f32_16x16x32_bf16 v[60:63], v[120:123], v[160:163], v[60:63]
	v_mfma_f32_16x16x32_bf16 v[60:63], v[124:127], v[164:167], v[60:63]
	v_mfma_f32_16x16x32_bf16 v[56:59], v[128:131], v[160:163], v[56:59]
	v_mfma_f32_16x16x32_bf16 v[56:59], v[132:135], v[164:167], v[56:59]
	v_mfma_f32_16x16x32_bf16 v[44:47], v[120:123], v[168:171], v[44:47]
	v_mfma_f32_16x16x32_bf16 v[44:47], v[124:127], v[172:175], v[44:47]
	v_mfma_f32_16x16x32_bf16 v[40:43], v[128:131], v[168:171], v[40:43]
	v_mfma_f32_16x16x32_bf16 v[40:43], v[132:135], v[172:175], v[40:43]
	v_mfma_f32_16x16x32_bf16 v[28:31], v[120:123], v[176:179], v[28:31]
	v_mfma_f32_16x16x32_bf16 v[28:31], v[124:127], v[180:183], v[28:31]
	v_mfma_f32_16x16x32_bf16 v[24:27], v[128:131], v[176:179], v[24:27]
	v_mfma_f32_16x16x32_bf16 v[24:27], v[132:135], v[180:183], v[24:27]
	v_mfma_f32_16x16x32_bf16 v[12:15], v[120:123], v[184:187], v[12:15]
	v_mfma_f32_16x16x32_bf16 v[12:15], v[124:127], v[188:191], v[12:15]
	v_mfma_f32_16x16x32_bf16 v[8:11], v[128:131], v[184:187], v[8:11]
	v_mfma_f32_16x16x32_bf16 v[8:11], v[132:135], v[188:191], v[8:11]
	v_mfma_f32_16x16x32_bf16 v[52:55], v[144:147], v[160:163], v[52:55]
	v_mfma_f32_16x16x32_bf16 v[52:55], v[148:151], v[164:167], v[52:55]
	v_mfma_f32_16x16x32_bf16 v[48:51], v[152:155], v[160:163], v[48:51]
	v_mfma_f32_16x16x32_bf16 v[48:51], v[156:159], v[164:167], v[48:51]
	v_mfma_f32_16x16x32_bf16 v[36:39], v[144:147], v[168:171], v[36:39]
	v_mfma_f32_16x16x32_bf16 v[36:39], v[148:151], v[172:175], v[36:39]
	v_mfma_f32_16x16x32_bf16 v[32:35], v[152:155], v[168:171], v[32:35]
	v_mfma_f32_16x16x32_bf16 v[32:35], v[156:159], v[172:175], v[32:35]
	v_mfma_f32_16x16x32_bf16 v[20:23], v[144:147], v[176:179], v[20:23]
	v_mfma_f32_16x16x32_bf16 v[20:23], v[148:151], v[180:183], v[20:23]
	v_mfma_f32_16x16x32_bf16 v[16:19], v[152:155], v[176:179], v[16:19]
	v_mfma_f32_16x16x32_bf16 v[16:19], v[156:159], v[180:183], v[16:19]
	v_mfma_f32_16x16x32_bf16 v[4:7], v[144:147], v[184:187], v[4:7]
	v_mfma_f32_16x16x32_bf16 v[4:7], v[148:151], v[188:191], v[4:7]
	s_setprio 3
	s_barrier
	v_mfma_f32_16x16x32_bf16 v[0:3], v[152:155], v[184:187], v[0:3]
	v_mfma_f32_16x16x32_bf16 v[0:3], v[156:159], v[188:191], v[0:3]
	s_setprio 0
	s_add_i32 s59, s59, 2
	s_add_u32 s76, s76, 0x100
	s_addc_u32 s77, s77, 0
	s_add_u32 s55, s55, 0x100
	s_addc_u32 s58, s58, 0
	s_cmp_gt_u32 s59, 41
	s_cbranch_scc0 .LBB0_1299
	s_and_b64 vcc, exec, s[50:51]
	s_cbranch_vccz .LBB0_1302
	s_barrier

.LBB0_1760:
	ds_read_b128 v[128:131], v181
	ds_read_b128 v[132:135], v181 offset:1024
	ds_read_b128 v[136:139], v181 offset:2048
	ds_read_b128 v[160:163], v181 offset:3072
	ds_read_b128 v[164:167], v182
	ds_read_b128 v[168:171], v182 offset:1024
	ds_read_b128 v[186:189], v182 offset:2048
	ds_read_b128 v[190:193], v182 offset:3072
	s_add_u32 s69, s78, 0xfffc0080
	s_addc_u32 s73, s79, -1
	s_cmp_eq_u32 s68, 12
	s_cselect_b32 s83, s49, s73
	s_cselect_b32 s82, s54, s69
	s_cselect_b32 s81, s47, s67
	s_cselect_b32 s80, s55, s66
	v_lshl_add_u64 v[172:173], s[78:79], 0, v[152:153]
	s_add_i32 m0, s18, 0xc000
	ds_read_b128 v[194:197], v183
	ds_read_b128 v[198:201], v183 offset:1024
	ds_read_b128 v[202:205], v183 offset:2048
	ds_read_b128 v[206:209], v183 offset:3072
	ds_read_b128 v[210:213], v183 offset:4096
	ds_read_b128 v[214:217], v183 offset:5120
	ds_read_b128 v[218:221], v183 offset:6144
	ds_read_b128 v[222:225], v183 offset:7168
	global_load_lds_dwordx4 v[172:173], off
	v_lshl_add_u64 v[172:173], s[78:79], 0, v[154:155]
	s_add_i32 m0, s18, 0xe000
	s_nop 0
	global_load_lds_dwordx4 v[172:173], off
	s_waitcnt vmcnt(8)
	s_waitcnt lgkmcnt(0)
	s_barrier
	s_setprio 1
	v_mfma_f32_16x16x32_bf16 v[124:127], v[128:131], v[194:197], v[124:127]
	v_mfma_f32_16x16x32_bf16 v[124:127], v[132:135], v[198:201], v[124:127]
	v_mfma_f32_16x16x32_bf16 v[120:123], v[136:139], v[194:197], v[120:123]
	v_mfma_f32_16x16x32_bf16 v[120:123], v[160:163], v[198:201], v[120:123]
	v_mfma_f32_16x16x32_bf16 v[108:111], v[128:131], v[202:205], v[108:111]
	v_mfma_f32_16x16x32_bf16 v[108:111], v[132:135], v[206:209], v[108:111]
	v_mfma_f32_16x16x32_bf16 v[104:107], v[136:139], v[202:205], v[104:107]
	v_mfma_f32_16x16x32_bf16 v[104:107], v[160:163], v[206:209], v[104:107]
	v_mfma_f32_16x16x32_bf16 v[92:95], v[128:131], v[210:213], v[92:95]
	v_mfma_f32_16x16x32_bf16 v[92:95], v[132:135], v[214:217], v[92:95]
	v_mfma_f32_16x16x32_bf16 v[88:91], v[136:139], v[210:213], v[88:91]
	v_mfma_f32_16x16x32_bf16 v[88:91], v[160:163], v[214:217], v[88:91]
	v_mfma_f32_16x16x32_bf16 v[76:79], v[128:131], v[218:221], v[76:79]
	v_mfma_f32_16x16x32_bf16 v[76:79], v[132:135], v[222:225], v[76:79]
	v_mfma_f32_16x16x32_bf16 v[72:75], v[136:139], v[218:221], v[72:75]
	v_mfma_f32_16x16x32_bf16 v[72:75], v[160:163], v[222:225], v[72:75]
	v_mfma_f32_16x16x32_bf16 v[116:119], v[164:167], v[194:197], v[116:119]
	v_mfma_f32_16x16x32_bf16 v[116:119], v[168:171], v[198:201], v[116:119]
	v_mfma_f32_16x16x32_bf16 v[112:115], v[186:189], v[194:197], v[112:115]
	v_mfma_f32_16x16x32_bf16 v[112:115], v[190:193], v[198:201], v[112:115]
	v_mfma_f32_16x16x32_bf16 v[100:103], v[164:167], v[202:205], v[100:103]
	v_mfma_f32_16x16x32_bf16 v[100:103], v[168:171], v[206:209], v[100:103]
	v_mfma_f32_16x16x32_bf16 v[96:99], v[186:189], v[202:205], v[96:99]
	v_mfma_f32_16x16x32_bf16 v[96:99], v[190:193], v[206:209], v[96:99]
	v_mfma_f32_16x16x32_bf16 v[84:87], v[164:167], v[210:213], v[84:87]
	v_mfma_f32_16x16x32_bf16 v[84:87], v[168:171], v[214:217], v[84:87]
	v_mfma_f32_16x16x32_bf16 v[80:83], v[186:189], v[210:213], v[80:83]
	v_mfma_f32_16x16x32_bf16 v[80:83], v[190:193], v[214:217], v[80:83]
	v_mfma_f32_16x16x32_bf16 v[68:71], v[164:167], v[218:221], v[68:71]
	v_mfma_f32_16x16x32_bf16 v[68:71], v[168:171], v[222:225], v[68:71]
	s_setprio 3
	s_barrier
	v_mfma_f32_16x16x32_bf16 v[64:67], v[186:189], v[218:221], v[64:67]
	v_mfma_f32_16x16x32_bf16 v[64:67], v[190:193], v[222:225], v[64:67]
	s_setprio 0
	s_add_i32 s69, s25, s17
	v_lshl_add_u64 v[172:173], s[80:81], 0, v[142:143]
	s_mov_b32 m0, s69
	ds_read_b128 v[194:197], v183 offset:16384
	ds_read_b128 v[198:201], v183 offset:17408
	ds_read_b128 v[202:205], v183 offset:18432
	ds_read_b128 v[206:209], v183 offset:19456
	ds_read_b128 v[210:213], v183 offset:20480
	ds_read_b128 v[214:217], v183 offset:21504
	ds_read_b128 v[218:221], v183 offset:22528
	ds_read_b128 v[222:225], v183 offset:23552
	global_load_lds_dwordx4 v[172:173], off
	s_add_i32 m0, s69, 0x2000
	s_add_u32 s84, s80, 0x40000
	v_lshl_add_u64 v[226:227], s[80:81], 0, v[146:147]
	s_addc_u32 s85, s81, 0
	s_add_i32 s69, s26, s17
	global_load_lds_dwordx4 v[226:227], off
	v_lshl_add_u64 v[228:229], s[84:85], 0, v[142:143]
	s_mov_b32 m0, s69
	v_lshl_add_u64 v[230:231], s[82:83], 0, v[144:145]
	global_load_lds_dwordx4 v[228:229], off
	v_lshl_add_u64 v[228:229], s[84:85], 0, v[146:147]
	s_add_i32 m0, s69, 0x2000
	s_nop 0
	global_load_lds_dwordx4 v[228:229], off
	v_lshl_add_u64 v[228:229], s[82:83], 0, v[140:141]
	s_mov_b32 m0, s18
	s_nop 0
	global_load_lds_dwordx4 v[228:229], off
	s_mov_b32 m0, s19
	s_nop 0
	global_load_lds_dwordx4 v[230:231], off
	s_waitcnt vmcnt(8)
	s_waitcnt lgkmcnt(0)
	s_barrier
	s_setprio 1
	v_mfma_f32_16x16x32_bf16 v[60:63], v[128:131], v[194:197], v[60:63]
	v_mfma_f32_16x16x32_bf16 v[60:63], v[132:135], v[198:201], v[60:63]
	v_mfma_f32_16x16x32_bf16 v[56:59], v[136:139], v[194:197], v[56:59]
	v_mfma_f32_16x16x32_bf16 v[56:59], v[160:163], v[198:201], v[56:59]
	v_mfma_f32_16x16x32_bf16 v[44:47], v[128:131], v[202:205], v[44:47]
	v_mfma_f32_16x16x32_bf16 v[44:47], v[132:135], v[206:209], v[44:47]
	v_mfma_f32_16x16x32_bf16 v[40:43], v[136:139], v[202:205], v[40:43]
	v_mfma_f32_16x16x32_bf16 v[40:43], v[160:163], v[206:209], v[40:43]
	v_mfma_f32_16x16x32_bf16 v[28:31], v[128:131], v[210:213], v[28:31]
	v_mfma_f32_16x16x32_bf16 v[28:31], v[132:135], v[214:217], v[28:31]
	v_mfma_f32_16x16x32_bf16 v[24:27], v[136:139], v[210:213], v[24:27]
	v_mfma_f32_16x16x32_bf16 v[24:27], v[160:163], v[214:217], v[24:27]
	v_mfma_f32_16x16x32_bf16 v[12:15], v[128:131], v[218:221], v[12:15]
	v_mfma_f32_16x16x32_bf16 v[12:15], v[132:135], v[222:225], v[12:15]
	v_mfma_f32_16x16x32_bf16 v[8:11], v[136:139], v[218:221], v[8:11]
	v_mfma_f32_16x16x32_bf16 v[8:11], v[160:163], v[222:225], v[8:11]
	v_mfma_f32_16x16x32_bf16 v[52:55], v[164:167], v[194:197], v[52:55]
	v_mfma_f32_16x16x32_bf16 v[52:55], v[168:171], v[198:201], v[52:55]
	v_mfma_f32_16x16x32_bf16 v[48:51], v[186:189], v[194:197], v[48:51]
	v_mfma_f32_16x16x32_bf16 v[48:51], v[190:193], v[198:201], v[48:51]
	v_mfma_f32_16x16x32_bf16 v[36:39], v[164:167], v[202:205], v[36:39]
	v_mfma_f32_16x16x32_bf16 v[36:39], v[168:171], v[206:209], v[36:39]
	v_mfma_f32_16x16x32_bf16 v[32:35], v[186:189], v[202:205], v[32:35]
	v_mfma_f32_16x16x32_bf16 v[32:35], v[190:193], v[206:209], v[32:35]
	v_mfma_f32_16x16x32_bf16 v[20:23], v[164:167], v[210:213], v[20:23]
	v_mfma_f32_16x16x32_bf16 v[20:23], v[168:171], v[214:217], v[20:23]
	v_mfma_f32_16x16x32_bf16 v[16:19], v[186:189], v[210:213], v[16:19]
	v_mfma_f32_16x16x32_bf16 v[16:19], v[190:193], v[214:217], v[16:19]
	v_mfma_f32_16x16x32_bf16 v[4:7], v[164:167], v[218:221], v[4:7]
	v_mfma_f32_16x16x32_bf16 v[4:7], v[168:171], v[222:225], v[4:7]
	s_setprio 3
	s_barrier
	v_mfma_f32_16x16x32_bf16 v[0:3], v[186:189], v[218:221], v[0:3]
	v_mfma_f32_16x16x32_bf16 v[0:3], v[190:193], v[222:225], v[0:3]
	s_setprio 0
	s_add_i32 s69, 0, 0x18000
	v_add_u32_e32 v148, s69, v177
	s_add_i32 s73, 0, 0x1c000
	ds_read_b128 v[128:131], v148
	ds_read_b128 v[132:135], v148 offset:1024
	ds_read_b128 v[136:139], v148 offset:2048
	ds_read_b128 v[160:163], v148 offset:3072
	v_add_u32_e32 v148, s73, v177
	ds_read_b128 v[164:167], v148
	ds_read_b128 v[168:171], v148 offset:1024
	ds_read_b128 v[186:189], v148 offset:2048
	ds_read_b128 v[190:193], v148 offset:3072
	s_add_u32 s82, s82, 0x40000
	s_addc_u32 s83, s83, 0
	s_mov_b32 m0, s20
	v_lshl_add_u64 v[232:233], s[82:83], 0, v[140:141]
	ds_read_b128 v[194:197], v183 offset:32768
	ds_read_b128 v[198:201], v183 offset:33792
	ds_read_b128 v[202:205], v183 offset:34816
	ds_read_b128 v[206:209], v183 offset:35840
	ds_read_b128 v[210:213], v183 offset:36864
	ds_read_b128 v[214:217], v183 offset:37888
	ds_read_b128 v[218:221], v183 offset:38912
	ds_read_b128 v[222:225], v183 offset:39936
	global_load_lds_dwordx4 v[232:233], off
	v_lshl_add_u64 v[232:233], s[82:83], 0, v[144:145]
	s_mov_b32 m0, s21
	s_nop 0
	global_load_lds_dwordx4 v[232:233], off
	s_waitcnt vmcnt(8)
	s_waitcnt lgkmcnt(0)
	s_barrier
	s_setprio 1
	v_mfma_f32_16x16x32_bf16 v[124:127], v[128:131], v[194:197], v[124:127]
	v_mfma_f32_16x16x32_bf16 v[124:127], v[132:135], v[198:201], v[124:127]
	v_mfma_f32_16x16x32_bf16 v[120:123], v[136:139], v[194:197], v[120:123]
	v_mfma_f32_16x16x32_bf16 v[120:123], v[160:163], v[198:201], v[120:123]
	v_mfma_f32_16x16x32_bf16 v[108:111], v[128:131], v[202:205], v[108:111]
	v_mfma_f32_16x16x32_bf16 v[108:111], v[132:135], v[206:209], v[108:111]
	v_mfma_f32_16x16x32_bf16 v[104:107], v[136:139], v[202:205], v[104:107]
	v_mfma_f32_16x16x32_bf16 v[104:107], v[160:163], v[206:209], v[104:107]
	v_mfma_f32_16x16x32_bf16 v[92:95], v[128:131], v[210:213], v[92:95]
	v_mfma_f32_16x16x32_bf16 v[92:95], v[132:135], v[214:217], v[92:95]
	v_mfma_f32_16x16x32_bf16 v[88:91], v[136:139], v[210:213], v[88:91]
	v_mfma_f32_16x16x32_bf16 v[88:91], v[160:163], v[214:217], v[88:91]
	v_mfma_f32_16x16x32_bf16 v[76:79], v[128:131], v[218:221], v[76:79]
	v_mfma_f32_16x16x32_bf16 v[76:79], v[132:135], v[222:225], v[76:79]
	v_mfma_f32_16x16x32_bf16 v[72:75], v[136:139], v[218:221], v[72:75]
	v_mfma_f32_16x16x32_bf16 v[72:75], v[160:163], v[222:225], v[72:75]
	v_mfma_f32_16x16x32_bf16 v[116:119], v[164:167], v[194:197], v[116:119]
	v_mfma_f32_16x16x32_bf16 v[116:119], v[168:171], v[198:201], v[116:119]
	v_mfma_f32_16x16x32_bf16 v[112:115], v[186:189], v[194:197], v[112:115]
	v_mfma_f32_16x16x32_bf16 v[112:115], v[190:193], v[198:201], v[112:115]
	v_mfma_f32_16x16x32_bf16 v[100:103], v[164:167], v[202:205], v[100:103]
	v_mfma_f32_16x16x32_bf16 v[100:103], v[168:171], v[206:209], v[100:103]
	v_mfma_f32_16x16x32_bf16 v[96:99], v[186:189], v[202:205], v[96:99]
	v_mfma_f32_16x16x32_bf16 v[96:99], v[190:193], v[206:209], v[96:99]
	v_mfma_f32_16x16x32_bf16 v[84:87], v[164:167], v[210:213], v[84:87]
	v_mfma_f32_16x16x32_bf16 v[84:87], v[168:171], v[214:217], v[84:87]
	v_mfma_f32_16x16x32_bf16 v[80:83], v[186:189], v[210:213], v[80:83]
	v_mfma_f32_16x16x32_bf16 v[80:83], v[190:193], v[214:217], v[80:83]
	v_mfma_f32_16x16x32_bf16 v[68:71], v[164:167], v[218:221], v[68:71]
	v_mfma_f32_16x16x32_bf16 v[68:71], v[168:171], v[222:225], v[68:71]
	s_setprio 3
	s_barrier
	v_mfma_f32_16x16x32_bf16 v[64:67], v[186:189], v[218:221], v[64:67]
	v_mfma_f32_16x16x32_bf16 v[64:67], v[190:193], v[222:225], v[64:67]
	s_setprio 0
	s_add_i32 s69, s69, s17
	v_lshl_add_u64 v[172:173], v[172:173], 0, s[10:11]
	s_mov_b32 m0, s69
	ds_read_b128 v[194:197], v183 offset:49152
	ds_read_b128 v[198:201], v183 offset:50176
	ds_read_b128 v[202:205], v183 offset:51200
	ds_read_b128 v[206:209], v183 offset:52224
	ds_read_b128 v[210:213], v183 offset:53248
	ds_read_b128 v[214:217], v183 offset:54272
	ds_read_b128 v[218:221], v183 offset:55296
	ds_read_b128 v[222:225], v183 offset:56320
	global_load_lds_dwordx4 v[172:173], off
	s_add_i32 m0, s69, 0x2000
	s_add_u32 s80, s80, 0x40080
	v_lshl_add_u64 v[172:173], v[226:227], 0, s[10:11]
	s_addc_u32 s81, s81, 0
	s_add_i32 s69, s73, s17
	global_load_lds_dwordx4 v[172:173], off
	v_lshl_add_u64 v[172:173], s[80:81], 0, v[142:143]
	s_mov_b32 m0, s69
	s_nop 0
	global_load_lds_dwordx4 v[172:173], off
	v_lshl_add_u64 v[172:173], s[80:81], 0, v[146:147]
	s_add_i32 m0, s69, 0x2000
	s_nop 0
	global_load_lds_dwordx4 v[172:173], off
	v_lshl_add_u64 v[172:173], v[228:229], 0, s[10:11]
	s_mov_b32 m0, s23
	s_nop 0
	global_load_lds_dwordx4 v[172:173], off
	v_lshl_add_u64 v[172:173], v[230:231], 0, s[10:11]
	s_mov_b32 m0, s24
	s_nop 0
	global_load_lds_dwordx4 v[172:173], off
	s_waitcnt vmcnt(8)
	s_waitcnt lgkmcnt(0)
	s_barrier
	s_setprio 1
	v_mfma_f32_16x16x32_bf16 v[60:63], v[128:131], v[194:197], v[60:63]
	v_mfma_f32_16x16x32_bf16 v[60:63], v[132:135], v[198:201], v[60:63]
	v_mfma_f32_16x16x32_bf16 v[56:59], v[136:139], v[194:197], v[56:59]
	v_mfma_f32_16x16x32_bf16 v[56:59], v[160:163], v[198:201], v[56:59]
	v_mfma_f32_16x16x32_bf16 v[44:47], v[128:131], v[202:205], v[44:47]
	v_mfma_f32_16x16x32_bf16 v[44:47], v[132:135], v[206:209], v[44:47]
	v_mfma_f32_16x16x32_bf16 v[40:43], v[136:139], v[202:205], v[40:43]
	v_mfma_f32_16x16x32_bf16 v[40:43], v[160:163], v[206:209], v[40:43]
	v_mfma_f32_16x16x32_bf16 v[28:31], v[128:131], v[210:213], v[28:31]
	v_mfma_f32_16x16x32_bf16 v[28:31], v[132:135], v[214:217], v[28:31]
	v_mfma_f32_16x16x32_bf16 v[24:27], v[136:139], v[210:213], v[24:27]
	v_mfma_f32_16x16x32_bf16 v[24:27], v[160:163], v[214:217], v[24:27]
	v_mfma_f32_16x16x32_bf16 v[12:15], v[128:131], v[218:221], v[12:15]
	v_mfma_f32_16x16x32_bf16 v[12:15], v[132:135], v[222:225], v[12:15]
	v_mfma_f32_16x16x32_bf16 v[8:11], v[136:139], v[218:221], v[8:11]
	v_mfma_f32_16x16x32_bf16 v[8:11], v[160:163], v[222:225], v[8:11]
	v_mfma_f32_16x16x32_bf16 v[52:55], v[164:167], v[194:197], v[52:55]
	v_mfma_f32_16x16x32_bf16 v[52:55], v[168:171], v[198:201], v[52:55]
	v_mfma_f32_16x16x32_bf16 v[48:51], v[186:189], v[194:197], v[48:51]
	v_mfma_f32_16x16x32_bf16 v[48:51], v[190:193], v[198:201], v[48:51]
	v_mfma_f32_16x16x32_bf16 v[36:39], v[164:167], v[202:205], v[36:39]
	v_mfma_f32_16x16x32_bf16 v[36:39], v[168:171], v[206:209], v[36:39]
	v_mfma_f32_16x16x32_bf16 v[32:35], v[186:189], v[202:205], v[32:35]
	v_mfma_f32_16x16x32_bf16 v[32:35], v[190:193], v[206:209], v[32:35]
	v_mfma_f32_16x16x32_bf16 v[20:23], v[164:167], v[210:213], v[20:23]
	v_mfma_f32_16x16x32_bf16 v[20:23], v[168:171], v[214:217], v[20:23]
	v_mfma_f32_16x16x32_bf16 v[16:19], v[186:189], v[210:213], v[16:19]
	v_mfma_f32_16x16x32_bf16 v[16:19], v[190:193], v[214:217], v[16:19]
	v_mfma_f32_16x16x32_bf16 v[4:7], v[164:167], v[218:221], v[4:7]
	v_mfma_f32_16x16x32_bf16 v[4:7], v[168:171], v[222:225], v[4:7]
	s_setprio 3
	s_barrier
	v_mfma_f32_16x16x32_bf16 v[0:3], v[186:189], v[218:221], v[0:3]
	v_mfma_f32_16x16x32_bf16 v[0:3], v[190:193], v[222:225], v[0:3]
	s_setprio 0
	s_add_i32 s68, s68, 2
	s_add_u32 s78, s78, 0x100
	s_addc_u32 s79, s79, 0
	s_add_u32 s66, s66, 0x100
	s_addc_u32 s67, s67, 0
	s_cmp_gt_u32 s68, 13
	s_cbranch_scc0 .LBB0_1760
	s_and_b64 vcc, exec, s[44:45]
	s_cbranch_vccz .LBB0_1763
	s_barrier

.LBB0_2037:
	ds_read_b128 v[120:123], v245
	ds_read_b128 v[124:127], v245 offset:1024
	ds_read_b128 v[128:131], v245 offset:2048
	ds_read_b128 v[132:135], v245 offset:3072
	ds_read_b128 v[144:147], v246
	ds_read_b128 v[148:151], v246 offset:1024
	ds_read_b128 v[152:155], v246 offset:2048
	ds_read_b128 v[156:159], v246 offset:3072
	s_add_u32 s67, s76, 0xfffc0080
	s_addc_u32 s68, s77, -1
	s_cmp_eq_u32 s66, 12
	s_cselect_b32 s81, s53, s68
	s_cselect_b32 s80, s54, s67
	s_cselect_b32 s79, s51, s57
	s_cselect_b32 s78, s55, s56
	v_lshl_add_u64 v[204:205], s[76:77], 0, v[200:201]
	s_add_i32 m0, s16, 0xc000
	ds_read_b128 v[160:163], v247
	ds_read_b128 v[164:167], v247 offset:1024
	ds_read_b128 v[168:171], v247 offset:2048
	ds_read_b128 v[172:175], v247 offset:3072
	ds_read_b128 v[176:179], v247 offset:4096
	ds_read_b128 v[180:183], v247 offset:5120
	ds_read_b128 v[184:187], v247 offset:6144
	ds_read_b128 v[188:191], v247 offset:7168
	global_load_lds_dwordx4 v[204:205], off
	v_lshl_add_u64 v[204:205], s[76:77], 0, v[202:203]
	s_add_i32 m0, s16, 0xe000
	s_nop 0
	global_load_lds_dwordx4 v[204:205], off
	s_waitcnt vmcnt(8)
	s_waitcnt lgkmcnt(0)
	s_barrier
	s_setprio 1
	v_mfma_f32_16x16x32_bf16 v[140:143], v[120:123], v[160:163], v[140:143]
	v_mfma_f32_16x16x32_bf16 v[140:143], v[124:127], v[164:167], v[140:143]
	v_mfma_f32_16x16x32_bf16 v[136:139], v[128:131], v[160:163], v[136:139]
	v_mfma_f32_16x16x32_bf16 v[136:139], v[132:135], v[164:167], v[136:139]
	v_mfma_f32_16x16x32_bf16 v[108:111], v[120:123], v[168:171], v[108:111]
	v_mfma_f32_16x16x32_bf16 v[108:111], v[124:127], v[172:175], v[108:111]
	v_mfma_f32_16x16x32_bf16 v[104:107], v[128:131], v[168:171], v[104:107]
	v_mfma_f32_16x16x32_bf16 v[104:107], v[132:135], v[172:175], v[104:107]
	v_mfma_f32_16x16x32_bf16 v[92:95], v[120:123], v[176:179], v[92:95]
	v_mfma_f32_16x16x32_bf16 v[92:95], v[124:127], v[180:183], v[92:95]
	v_mfma_f32_16x16x32_bf16 v[88:91], v[128:131], v[176:179], v[88:91]
	v_mfma_f32_16x16x32_bf16 v[88:91], v[132:135], v[180:183], v[88:91]
	v_mfma_f32_16x16x32_bf16 v[76:79], v[120:123], v[184:187], v[76:79]
	v_mfma_f32_16x16x32_bf16 v[76:79], v[124:127], v[188:191], v[76:79]
	v_mfma_f32_16x16x32_bf16 v[72:75], v[128:131], v[184:187], v[72:75]
	v_mfma_f32_16x16x32_bf16 v[72:75], v[132:135], v[188:191], v[72:75]
	v_mfma_f32_16x16x32_bf16 v[116:119], v[144:147], v[160:163], v[116:119]
	v_mfma_f32_16x16x32_bf16 v[116:119], v[148:151], v[164:167], v[116:119]
	v_mfma_f32_16x16x32_bf16 v[112:115], v[152:155], v[160:163], v[112:115]
	v_mfma_f32_16x16x32_bf16 v[112:115], v[156:159], v[164:167], v[112:115]
	v_mfma_f32_16x16x32_bf16 v[100:103], v[144:147], v[168:171], v[100:103]
	v_mfma_f32_16x16x32_bf16 v[100:103], v[148:151], v[172:175], v[100:103]
	v_mfma_f32_16x16x32_bf16 v[96:99], v[152:155], v[168:171], v[96:99]
	v_mfma_f32_16x16x32_bf16 v[96:99], v[156:159], v[172:175], v[96:99]
	v_mfma_f32_16x16x32_bf16 v[84:87], v[144:147], v[176:179], v[84:87]
	v_mfma_f32_16x16x32_bf16 v[84:87], v[148:151], v[180:183], v[84:87]
	v_mfma_f32_16x16x32_bf16 v[80:83], v[152:155], v[176:179], v[80:83]
	v_mfma_f32_16x16x32_bf16 v[80:83], v[156:159], v[180:183], v[80:83]
	v_mfma_f32_16x16x32_bf16 v[68:71], v[144:147], v[184:187], v[68:71]
	v_mfma_f32_16x16x32_bf16 v[68:71], v[148:151], v[188:191], v[68:71]
	s_setprio 3
	s_barrier
	v_mfma_f32_16x16x32_bf16 v[64:67], v[152:155], v[184:187], v[64:67]
	v_mfma_f32_16x16x32_bf16 v[64:67], v[156:159], v[188:191], v[64:67]
	s_setprio 0
	s_add_i32 s67, s26, s15
	v_lshl_add_u64 v[204:205], s[78:79], 0, v[194:195]
	s_mov_b32 m0, s67
	ds_read_b128 v[160:163], v247 offset:16384
	ds_read_b128 v[164:167], v247 offset:17408
	ds_read_b128 v[168:171], v247 offset:18432
	ds_read_b128 v[172:175], v247 offset:19456
	ds_read_b128 v[176:179], v247 offset:20480
	ds_read_b128 v[180:183], v247 offset:21504
	ds_read_b128 v[184:187], v247 offset:22528
	ds_read_b128 v[188:191], v247 offset:23552
	global_load_lds_dwordx4 v[204:205], off
	s_add_i32 m0, s67, 0x2000
	s_add_u32 s68, s78, 0x40000
	v_lshl_add_u64 v[206:207], s[78:79], 0, v[198:199]
	s_addc_u32 s69, s79, 0
	s_add_i32 s67, s27, s15
	global_load_lds_dwordx4 v[206:207], off
	v_lshl_add_u64 v[208:209], s[68:69], 0, v[194:195]
	s_mov_b32 m0, s67
	v_lshl_add_u64 v[210:211], s[80:81], 0, v[196:197]
	global_load_lds_dwordx4 v[208:209], off
	v_lshl_add_u64 v[208:209], s[68:69], 0, v[198:199]
	s_add_i32 m0, s67, 0x2000
	s_nop 0
	global_load_lds_dwordx4 v[208:209], off
	v_lshl_add_u64 v[208:209], s[80:81], 0, v[192:193]
	s_mov_b32 m0, s16
	s_nop 0
	global_load_lds_dwordx4 v[208:209], off
	s_mov_b32 m0, s17
	s_nop 0
	global_load_lds_dwordx4 v[210:211], off
	s_waitcnt vmcnt(8)
	s_waitcnt lgkmcnt(0)
	s_barrier
	s_setprio 1
	v_mfma_f32_16x16x32_bf16 v[60:63], v[120:123], v[160:163], v[60:63]
	v_mfma_f32_16x16x32_bf16 v[60:63], v[124:127], v[164:167], v[60:63]
	v_mfma_f32_16x16x32_bf16 v[56:59], v[128:131], v[160:163], v[56:59]
	v_mfma_f32_16x16x32_bf16 v[56:59], v[132:135], v[164:167], v[56:59]
	v_mfma_f32_16x16x32_bf16 v[44:47], v[120:123], v[168:171], v[44:47]
	v_mfma_f32_16x16x32_bf16 v[44:47], v[124:127], v[172:175], v[44:47]
	v_mfma_f32_16x16x32_bf16 v[40:43], v[128:131], v[168:171], v[40:43]
	v_mfma_f32_16x16x32_bf16 v[40:43], v[132:135], v[172:175], v[40:43]
	v_mfma_f32_16x16x32_bf16 v[28:31], v[120:123], v[176:179], v[28:31]
	v_mfma_f32_16x16x32_bf16 v[28:31], v[124:127], v[180:183], v[28:31]
	v_mfma_f32_16x16x32_bf16 v[24:27], v[128:131], v[176:179], v[24:27]
	v_mfma_f32_16x16x32_bf16 v[24:27], v[132:135], v[180:183], v[24:27]
	v_mfma_f32_16x16x32_bf16 v[12:15], v[120:123], v[184:187], v[12:15]
	v_mfma_f32_16x16x32_bf16 v[12:15], v[124:127], v[188:191], v[12:15]
	v_mfma_f32_16x16x32_bf16 v[8:11], v[128:131], v[184:187], v[8:11]
	v_mfma_f32_16x16x32_bf16 v[8:11], v[132:135], v[188:191], v[8:11]
	v_mfma_f32_16x16x32_bf16 v[52:55], v[144:147], v[160:163], v[52:55]
	v_mfma_f32_16x16x32_bf16 v[52:55], v[148:151], v[164:167], v[52:55]
	v_mfma_f32_16x16x32_bf16 v[48:51], v[152:155], v[160:163], v[48:51]
	v_mfma_f32_16x16x32_bf16 v[48:51], v[156:159], v[164:167], v[48:51]
	v_mfma_f32_16x16x32_bf16 v[36:39], v[144:147], v[168:171], v[36:39]
	v_mfma_f32_16x16x32_bf16 v[36:39], v[148:151], v[172:175], v[36:39]
	v_mfma_f32_16x16x32_bf16 v[32:35], v[152:155], v[168:171], v[32:35]
	v_mfma_f32_16x16x32_bf16 v[32:35], v[156:159], v[172:175], v[32:35]
	v_mfma_f32_16x16x32_bf16 v[20:23], v[144:147], v[176:179], v[20:23]
	v_mfma_f32_16x16x32_bf16 v[20:23], v[148:151], v[180:183], v[20:23]
	v_mfma_f32_16x16x32_bf16 v[16:19], v[152:155], v[176:179], v[16:19]
	v_mfma_f32_16x16x32_bf16 v[16:19], v[156:159], v[180:183], v[16:19]
	v_mfma_f32_16x16x32_bf16 v[4:7], v[144:147], v[184:187], v[4:7]
	v_mfma_f32_16x16x32_bf16 v[4:7], v[148:151], v[188:191], v[4:7]
	s_setprio 3
	s_barrier
	v_mfma_f32_16x16x32_bf16 v[0:3], v[152:155], v[184:187], v[0:3]
	v_mfma_f32_16x16x32_bf16 v[0:3], v[156:159], v[188:191], v[0:3]
	s_setprio 0
	s_add_i32 s67, 0, 0x18000
	s_add_i32 s75, 0, 0x1c000
	v_add_u32_e32 v132, s67, v243
	v_add_u32_e32 v156, s75, v243
	ds_read_b128 v[120:123], v132
	ds_read_b128 v[124:127], v132 offset:1024
	ds_read_b128 v[128:131], v132 offset:2048
	ds_read_b128 v[132:135], v132 offset:3072
	ds_read_b128 v[144:147], v156
	ds_read_b128 v[148:151], v156 offset:1024
	ds_read_b128 v[152:155], v156 offset:2048
	ds_read_b128 v[156:159], v156 offset:3072
	s_add_u32 s68, s80, 0x40000
	s_addc_u32 s69, s81, 0
	s_mov_b32 m0, s18
	v_lshl_add_u64 v[212:213], s[68:69], 0, v[192:193]
	ds_read_b128 v[160:163], v247 offset:32768
	ds_read_b128 v[164:167], v247 offset:33792
	ds_read_b128 v[168:171], v247 offset:34816
	ds_read_b128 v[172:175], v247 offset:35840
	ds_read_b128 v[176:179], v247 offset:36864
	ds_read_b128 v[180:183], v247 offset:37888
	ds_read_b128 v[184:187], v247 offset:38912
	ds_read_b128 v[188:191], v247 offset:39936
	global_load_lds_dwordx4 v[212:213], off
	v_lshl_add_u64 v[212:213], s[68:69], 0, v[196:197]
	s_mov_b32 m0, s19
	s_nop 0
	global_load_lds_dwordx4 v[212:213], off
	s_waitcnt vmcnt(8)
	s_waitcnt lgkmcnt(0)
	s_barrier
	s_setprio 1
	v_mfma_f32_16x16x32_bf16 v[140:143], v[120:123], v[160:163], v[140:143]
	v_mfma_f32_16x16x32_bf16 v[140:143], v[124:127], v[164:167], v[140:143]
	v_mfma_f32_16x16x32_bf16 v[136:139], v[128:131], v[160:163], v[136:139]
	v_mfma_f32_16x16x32_bf16 v[136:139], v[132:135], v[164:167], v[136:139]
	v_mfma_f32_16x16x32_bf16 v[108:111], v[120:123], v[168:171], v[108:111]
	v_mfma_f32_16x16x32_bf16 v[108:111], v[124:127], v[172:175], v[108:111]
	v_mfma_f32_16x16x32_bf16 v[104:107], v[128:131], v[168:171], v[104:107]
	v_mfma_f32_16x16x32_bf16 v[104:107], v[132:135], v[172:175], v[104:107]
	v_mfma_f32_16x16x32_bf16 v[92:95], v[120:123], v[176:179], v[92:95]
	v_mfma_f32_16x16x32_bf16 v[92:95], v[124:127], v[180:183], v[92:95]
	v_mfma_f32_16x16x32_bf16 v[88:91], v[128:131], v[176:179], v[88:91]
	v_mfma_f32_16x16x32_bf16 v[88:91], v[132:135], v[180:183], v[88:91]
	v_mfma_f32_16x16x32_bf16 v[76:79], v[120:123], v[184:187], v[76:79]
	v_mfma_f32_16x16x32_bf16 v[76:79], v[124:127], v[188:191], v[76:79]
	v_mfma_f32_16x16x32_bf16 v[72:75], v[128:131], v[184:187], v[72:75]
	v_mfma_f32_16x16x32_bf16 v[72:75], v[132:135], v[188:191], v[72:75]
	v_mfma_f32_16x16x32_bf16 v[116:119], v[144:147], v[160:163], v[116:119]
	v_mfma_f32_16x16x32_bf16 v[116:119], v[148:151], v[164:167], v[116:119]
	v_mfma_f32_16x16x32_bf16 v[112:115], v[152:155], v[160:163], v[112:115]
	v_mfma_f32_16x16x32_bf16 v[112:115], v[156:159], v[164:167], v[112:115]
	v_mfma_f32_16x16x32_bf16 v[100:103], v[144:147], v[168:171], v[100:103]
	v_mfma_f32_16x16x32_bf16 v[100:103], v[148:151], v[172:175], v[100:103]
	v_mfma_f32_16x16x32_bf16 v[96:99], v[152:155], v[168:171], v[96:99]
	v_mfma_f32_16x16x32_bf16 v[96:99], v[156:159], v[172:175], v[96:99]
	v_mfma_f32_16x16x32_bf16 v[84:87], v[144:147], v[176:179], v[84:87]
	v_mfma_f32_16x16x32_bf16 v[84:87], v[148:151], v[180:183], v[84:87]
	v_mfma_f32_16x16x32_bf16 v[80:83], v[152:155], v[176:179], v[80:83]
	v_mfma_f32_16x16x32_bf16 v[80:83], v[156:159], v[180:183], v[80:83]
	v_mfma_f32_16x16x32_bf16 v[68:71], v[144:147], v[184:187], v[68:71]
	v_mfma_f32_16x16x32_bf16 v[68:71], v[148:151], v[188:191], v[68:71]
	s_setprio 3
	s_barrier
	v_mfma_f32_16x16x32_bf16 v[64:67], v[152:155], v[184:187], v[64:67]
	v_mfma_f32_16x16x32_bf16 v[64:67], v[156:159], v[188:191], v[64:67]
	s_setprio 0
	s_add_i32 s67, s67, s15
	v_lshl_add_u64 v[204:205], v[204:205], 0, s[46:47]
	s_mov_b32 m0, s67
	ds_read_b128 v[160:163], v247 offset:49152
	ds_read_b128 v[164:167], v247 offset:50176
	ds_read_b128 v[168:171], v247 offset:51200
	ds_read_b128 v[172:175], v247 offset:52224
	ds_read_b128 v[176:179], v247 offset:53248
	ds_read_b128 v[180:183], v247 offset:54272
	ds_read_b128 v[184:187], v247 offset:55296
	ds_read_b128 v[188:191], v247 offset:56320
	global_load_lds_dwordx4 v[204:205], off
	s_add_i32 m0, s67, 0x2000
	s_add_u32 s68, s78, 0x40080
	v_lshl_add_u64 v[204:205], v[206:207], 0, s[46:47]
	s_addc_u32 s69, s79, 0
	s_add_i32 s67, s75, s15
	global_load_lds_dwordx4 v[204:205], off
	v_lshl_add_u64 v[204:205], s[68:69], 0, v[194:195]
	s_mov_b32 m0, s67
	s_nop 0
	global_load_lds_dwordx4 v[204:205], off
	v_lshl_add_u64 v[204:205], s[68:69], 0, v[198:199]
	s_add_i32 m0, s67, 0x2000
	s_nop 0
	global_load_lds_dwordx4 v[204:205], off
	v_lshl_add_u64 v[204:205], v[208:209], 0, s[46:47]
	s_mov_b32 m0, s21
	s_nop 0
	global_load_lds_dwordx4 v[204:205], off
	v_lshl_add_u64 v[204:205], v[210:211], 0, s[46:47]
	s_mov_b32 m0, s22
	s_nop 0
	global_load_lds_dwordx4 v[204:205], off
	s_waitcnt vmcnt(8)
	s_waitcnt lgkmcnt(0)
	s_barrier
	s_setprio 1
	v_mfma_f32_16x16x32_bf16 v[60:63], v[120:123], v[160:163], v[60:63]
	v_mfma_f32_16x16x32_bf16 v[60:63], v[124:127], v[164:167], v[60:63]
	v_mfma_f32_16x16x32_bf16 v[56:59], v[128:131], v[160:163], v[56:59]
	v_mfma_f32_16x16x32_bf16 v[56:59], v[132:135], v[164:167], v[56:59]
	v_mfma_f32_16x16x32_bf16 v[44:47], v[120:123], v[168:171], v[44:47]
	v_mfma_f32_16x16x32_bf16 v[44:47], v[124:127], v[172:175], v[44:47]
	v_mfma_f32_16x16x32_bf16 v[40:43], v[128:131], v[168:171], v[40:43]
	v_mfma_f32_16x16x32_bf16 v[40:43], v[132:135], v[172:175], v[40:43]
	v_mfma_f32_16x16x32_bf16 v[28:31], v[120:123], v[176:179], v[28:31]
	v_mfma_f32_16x16x32_bf16 v[28:31], v[124:127], v[180:183], v[28:31]
	v_mfma_f32_16x16x32_bf16 v[24:27], v[128:131], v[176:179], v[24:27]
	v_mfma_f32_16x16x32_bf16 v[24:27], v[132:135], v[180:183], v[24:27]
	v_mfma_f32_16x16x32_bf16 v[12:15], v[120:123], v[184:187], v[12:15]
	v_mfma_f32_16x16x32_bf16 v[12:15], v[124:127], v[188:191], v[12:15]
	v_mfma_f32_16x16x32_bf16 v[8:11], v[128:131], v[184:187], v[8:11]
	v_mfma_f32_16x16x32_bf16 v[8:11], v[132:135], v[188:191], v[8:11]
	v_mfma_f32_16x16x32_bf16 v[52:55], v[144:147], v[160:163], v[52:55]
	v_mfma_f32_16x16x32_bf16 v[52:55], v[148:151], v[164:167], v[52:55]
	v_mfma_f32_16x16x32_bf16 v[48:51], v[152:155], v[160:163], v[48:51]
	v_mfma_f32_16x16x32_bf16 v[48:51], v[156:159], v[164:167], v[48:51]
	v_mfma_f32_16x16x32_bf16 v[36:39], v[144:147], v[168:171], v[36:39]
	v_mfma_f32_16x16x32_bf16 v[36:39], v[148:151], v[172:175], v[36:39]
	v_mfma_f32_16x16x32_bf16 v[32:35], v[152:155], v[168:171], v[32:35]
	v_mfma_f32_16x16x32_bf16 v[32:35], v[156:159], v[172:175], v[32:35]
	v_mfma_f32_16x16x32_bf16 v[20:23], v[144:147], v[176:179], v[20:23]
	v_mfma_f32_16x16x32_bf16 v[20:23], v[148:151], v[180:183], v[20:23]
	v_mfma_f32_16x16x32_bf16 v[16:19], v[152:155], v[176:179], v[16:19]
	v_mfma_f32_16x16x32_bf16 v[16:19], v[156:159], v[180:183], v[16:19]
	v_mfma_f32_16x16x32_bf16 v[4:7], v[144:147], v[184:187], v[4:7]
	v_mfma_f32_16x16x32_bf16 v[4:7], v[148:151], v[188:191], v[4:7]
	s_setprio 3
	s_barrier
	v_mfma_f32_16x16x32_bf16 v[0:3], v[152:155], v[184:187], v[0:3]
	v_mfma_f32_16x16x32_bf16 v[0:3], v[156:159], v[188:191], v[0:3]
	s_setprio 0
	s_add_i32 s66, s66, 2
	s_add_u32 s76, s76, 0x100
	s_addc_u32 s77, s77, 0
	s_add_u32 s56, s56, 0x100
	s_addc_u32 s57, s57, 0
	s_cmp_gt_u32 s66, 13
	s_cbranch_scc0 .LBB0_2037
	s_and_b64 vcc, exec, s[48:49]
	s_cbranch_vccz .LBB0_2040
	s_barrier

.LBB0_2192:
	ds_read_b128 v[146:149], v174
	ds_read_b128 v[150:153], v174 offset:1024
	ds_read_b128 v[154:157], v174 offset:2048
	ds_read_b128 v[158:161], v174 offset:3072
	ds_read_b128 v[162:165], v175
	ds_read_b128 v[178:181], v175 offset:1024
	ds_read_b128 v[182:185], v175 offset:2048
	ds_read_b128 v[186:189], v175 offset:3072
	s_add_u32 s70, s58, 0xfffc0080
	s_addc_u32 s71, s59, -1
	s_cmp_eq_u32 s69, 12
	s_cselect_b32 s73, s47, s71
	s_cselect_b32 s72, s53, s70
	s_cselect_b32 s71, s45, s68
	s_cselect_b32 s70, s66, s67
	v_lshl_add_u64 v[166:167], s[58:59], 0, v[136:137]
	s_add_i32 m0, s17, 0xc000
	ds_read_b128 v[190:193], v176
	ds_read_b128 v[194:197], v176 offset:1024
	ds_read_b128 v[198:201], v176 offset:2048
	ds_read_b128 v[202:205], v176 offset:3072
	ds_read_b128 v[206:209], v176 offset:4096
	ds_read_b128 v[210:213], v176 offset:5120
	ds_read_b128 v[214:217], v176 offset:6144
	ds_read_b128 v[218:221], v176 offset:7168
	global_load_lds_dwordx4 v[166:167], off
	v_lshl_add_u64 v[166:167], s[58:59], 0, v[140:141]
	s_add_i32 m0, s17, 0xe000
	s_nop 0
	global_load_lds_dwordx4 v[166:167], off
	s_waitcnt vmcnt(8)
	s_waitcnt lgkmcnt(0)
	s_barrier
	s_setprio 1
	v_mfma_f32_16x16x32_bf16 v[124:127], v[146:149], v[190:193], v[124:127]
	v_mfma_f32_16x16x32_bf16 v[124:127], v[150:153], v[194:197], v[124:127]
	v_mfma_f32_16x16x32_bf16 v[116:119], v[154:157], v[190:193], v[116:119]
	v_mfma_f32_16x16x32_bf16 v[116:119], v[158:161], v[194:197], v[116:119]
	v_mfma_f32_16x16x32_bf16 v[108:111], v[146:149], v[198:201], v[108:111]
	v_mfma_f32_16x16x32_bf16 v[108:111], v[150:153], v[202:205], v[108:111]
	v_mfma_f32_16x16x32_bf16 v[100:103], v[154:157], v[198:201], v[100:103]
	v_mfma_f32_16x16x32_bf16 v[100:103], v[158:161], v[202:205], v[100:103]
	v_mfma_f32_16x16x32_bf16 v[92:95], v[146:149], v[206:209], v[92:95]
	v_mfma_f32_16x16x32_bf16 v[92:95], v[150:153], v[210:213], v[92:95]
	v_mfma_f32_16x16x32_bf16 v[84:87], v[154:157], v[206:209], v[84:87]
	v_mfma_f32_16x16x32_bf16 v[84:87], v[158:161], v[210:213], v[84:87]
	v_mfma_f32_16x16x32_bf16 v[76:79], v[146:149], v[214:217], v[76:79]
	v_mfma_f32_16x16x32_bf16 v[76:79], v[150:153], v[218:221], v[76:79]
	v_mfma_f32_16x16x32_bf16 v[68:71], v[154:157], v[214:217], v[68:71]
	v_mfma_f32_16x16x32_bf16 v[68:71], v[158:161], v[218:221], v[68:71]
	v_mfma_f32_16x16x32_bf16 v[120:123], v[162:165], v[190:193], v[120:123]
	v_mfma_f32_16x16x32_bf16 v[120:123], v[178:181], v[194:197], v[120:123]
	v_mfma_f32_16x16x32_bf16 v[112:115], v[182:185], v[190:193], v[112:115]
	v_mfma_f32_16x16x32_bf16 v[112:115], v[186:189], v[194:197], v[112:115]
	v_mfma_f32_16x16x32_bf16 v[104:107], v[162:165], v[198:201], v[104:107]
	v_mfma_f32_16x16x32_bf16 v[104:107], v[178:181], v[202:205], v[104:107]
	v_mfma_f32_16x16x32_bf16 v[96:99], v[182:185], v[198:201], v[96:99]
	v_mfma_f32_16x16x32_bf16 v[96:99], v[186:189], v[202:205], v[96:99]
	v_mfma_f32_16x16x32_bf16 v[88:91], v[162:165], v[206:209], v[88:91]
	v_mfma_f32_16x16x32_bf16 v[88:91], v[178:181], v[210:213], v[88:91]
	v_mfma_f32_16x16x32_bf16 v[80:83], v[182:185], v[206:209], v[80:83]
	v_mfma_f32_16x16x32_bf16 v[80:83], v[186:189], v[210:213], v[80:83]
	v_mfma_f32_16x16x32_bf16 v[72:75], v[162:165], v[214:217], v[72:75]
	v_mfma_f32_16x16x32_bf16 v[72:75], v[178:181], v[218:221], v[72:75]
	s_setprio 3
	s_barrier
	v_mfma_f32_16x16x32_bf16 v[64:67], v[182:185], v[214:217], v[64:67]
	v_mfma_f32_16x16x32_bf16 v[64:67], v[186:189], v[218:221], v[64:67]
	s_setprio 0
	s_add_i32 s74, s26, s16
	v_lshl_add_u64 v[166:167], s[70:71], 0, v[132:133]
	s_mov_b32 m0, s74
	ds_read_b128 v[190:193], v176 offset:16384
	ds_read_b128 v[194:197], v176 offset:17408
	ds_read_b128 v[198:201], v176 offset:18432
	ds_read_b128 v[202:205], v176 offset:19456
	ds_read_b128 v[206:209], v176 offset:20480
	ds_read_b128 v[210:213], v176 offset:21504
	ds_read_b128 v[214:217], v176 offset:22528
	ds_read_b128 v[218:221], v176 offset:23552
	global_load_lds_dwordx4 v[166:167], off
	s_add_i32 m0, s74, 0x2000
	s_add_u32 s74, s70, 0x40000
	v_lshl_add_u64 v[222:223], s[70:71], 0, v[128:129]
	s_addc_u32 s75, s71, 0
	s_add_i32 s76, s27, s16
	global_load_lds_dwordx4 v[222:223], off
	v_lshl_add_u64 v[224:225], s[74:75], 0, v[132:133]
	s_mov_b32 m0, s76
	v_lshl_add_u64 v[226:227], s[72:73], 0, v[130:131]
	global_load_lds_dwordx4 v[224:225], off
	v_lshl_add_u64 v[224:225], s[74:75], 0, v[128:129]
	s_add_i32 m0, s76, 0x2000
	s_nop 0
	global_load_lds_dwordx4 v[224:225], off
	v_lshl_add_u64 v[224:225], s[72:73], 0, v[134:135]
	s_mov_b32 m0, s17
	s_nop 0
	global_load_lds_dwordx4 v[224:225], off
	s_mov_b32 m0, s18
	s_nop 0
	global_load_lds_dwordx4 v[226:227], off
	s_waitcnt vmcnt(8)
	s_waitcnt lgkmcnt(0)
	s_barrier
	s_setprio 1
	v_mfma_f32_16x16x32_bf16 v[60:63], v[146:149], v[190:193], v[60:63]
	v_mfma_f32_16x16x32_bf16 v[60:63], v[150:153], v[194:197], v[60:63]
	v_mfma_f32_16x16x32_bf16 v[52:55], v[154:157], v[190:193], v[52:55]
	v_mfma_f32_16x16x32_bf16 v[52:55], v[158:161], v[194:197], v[52:55]
	v_mfma_f32_16x16x32_bf16 v[44:47], v[146:149], v[198:201], v[44:47]
	v_mfma_f32_16x16x32_bf16 v[44:47], v[150:153], v[202:205], v[44:47]
	v_mfma_f32_16x16x32_bf16 v[36:39], v[154:157], v[198:201], v[36:39]
	v_mfma_f32_16x16x32_bf16 v[36:39], v[158:161], v[202:205], v[36:39]
	v_mfma_f32_16x16x32_bf16 v[28:31], v[146:149], v[206:209], v[28:31]
	v_mfma_f32_16x16x32_bf16 v[28:31], v[150:153], v[210:213], v[28:31]
	v_mfma_f32_16x16x32_bf16 v[20:23], v[154:157], v[206:209], v[20:23]
	v_mfma_f32_16x16x32_bf16 v[20:23], v[158:161], v[210:213], v[20:23]
	v_mfma_f32_16x16x32_bf16 v[12:15], v[146:149], v[214:217], v[12:15]
	v_mfma_f32_16x16x32_bf16 v[12:15], v[150:153], v[218:221], v[12:15]
	v_mfma_f32_16x16x32_bf16 v[4:7], v[154:157], v[214:217], v[4:7]
	v_mfma_f32_16x16x32_bf16 v[4:7], v[158:161], v[218:221], v[4:7]
	v_mfma_f32_16x16x32_bf16 v[56:59], v[162:165], v[190:193], v[56:59]
	v_mfma_f32_16x16x32_bf16 v[56:59], v[178:181], v[194:197], v[56:59]
	v_mfma_f32_16x16x32_bf16 v[48:51], v[182:185], v[190:193], v[48:51]
	v_mfma_f32_16x16x32_bf16 v[48:51], v[186:189], v[194:197], v[48:51]
	v_mfma_f32_16x16x32_bf16 v[40:43], v[162:165], v[198:201], v[40:43]
	v_mfma_f32_16x16x32_bf16 v[40:43], v[178:181], v[202:205], v[40:43]
	v_mfma_f32_16x16x32_bf16 v[32:35], v[182:185], v[198:201], v[32:35]
	v_mfma_f32_16x16x32_bf16 v[32:35], v[186:189], v[202:205], v[32:35]
	v_mfma_f32_16x16x32_bf16 v[24:27], v[162:165], v[206:209], v[24:27]
	v_mfma_f32_16x16x32_bf16 v[24:27], v[178:181], v[210:213], v[24:27]
	v_mfma_f32_16x16x32_bf16 v[16:19], v[182:185], v[206:209], v[16:19]
	v_mfma_f32_16x16x32_bf16 v[16:19], v[186:189], v[210:213], v[16:19]
	v_mfma_f32_16x16x32_bf16 v[8:11], v[162:165], v[214:217], v[8:11]
	v_mfma_f32_16x16x32_bf16 v[8:11], v[178:181], v[218:221], v[8:11]
	s_setprio 3
	s_barrier
	v_mfma_f32_16x16x32_bf16 v[0:3], v[182:185], v[214:217], v[0:3]
	v_mfma_f32_16x16x32_bf16 v[0:3], v[186:189], v[218:221], v[0:3]
	s_setprio 0
	s_add_i32 s74, 0, 0x18000
	s_add_i32 s75, 0, 0x1c000
	v_add_u32_e32 v158, s74, v171
	v_add_u32_e32 v186, s75, v171
	ds_read_b128 v[146:149], v158
	ds_read_b128 v[150:153], v158 offset:1024
	ds_read_b128 v[154:157], v158 offset:2048
	ds_read_b128 v[158:161], v158 offset:3072
	ds_read_b128 v[162:165], v186
	ds_read_b128 v[178:181], v186 offset:1024
	ds_read_b128 v[182:185], v186 offset:2048
	ds_read_b128 v[186:189], v186 offset:3072
	s_add_u32 s72, s72, 0x40000
	s_addc_u32 s73, s73, 0
	s_mov_b32 m0, s19
	v_lshl_add_u64 v[228:229], s[72:73], 0, v[134:135]
	ds_read_b128 v[190:193], v176 offset:32768
	ds_read_b128 v[194:197], v176 offset:33792
	ds_read_b128 v[198:201], v176 offset:34816
	ds_read_b128 v[202:205], v176 offset:35840
	ds_read_b128 v[206:209], v176 offset:36864
	ds_read_b128 v[210:213], v176 offset:37888
	ds_read_b128 v[214:217], v176 offset:38912
	ds_read_b128 v[218:221], v176 offset:39936
	global_load_lds_dwordx4 v[228:229], off
	v_lshl_add_u64 v[228:229], s[72:73], 0, v[130:131]
	s_mov_b32 m0, s20
	s_nop 0
	global_load_lds_dwordx4 v[228:229], off
	s_waitcnt vmcnt(8)
	s_waitcnt lgkmcnt(0)
	s_barrier
	s_setprio 1
	v_mfma_f32_16x16x32_bf16 v[124:127], v[146:149], v[190:193], v[124:127]
	v_mfma_f32_16x16x32_bf16 v[124:127], v[150:153], v[194:197], v[124:127]
	v_mfma_f32_16x16x32_bf16 v[116:119], v[154:157], v[190:193], v[116:119]
	v_mfma_f32_16x16x32_bf16 v[116:119], v[158:161], v[194:197], v[116:119]
	v_mfma_f32_16x16x32_bf16 v[108:111], v[146:149], v[198:201], v[108:111]
	v_mfma_f32_16x16x32_bf16 v[108:111], v[150:153], v[202:205], v[108:111]
	v_mfma_f32_16x16x32_bf16 v[100:103], v[154:157], v[198:201], v[100:103]
	v_mfma_f32_16x16x32_bf16 v[100:103], v[158:161], v[202:205], v[100:103]
	v_mfma_f32_16x16x32_bf16 v[92:95], v[146:149], v[206:209], v[92:95]
	v_mfma_f32_16x16x32_bf16 v[92:95], v[150:153], v[210:213], v[92:95]
	v_mfma_f32_16x16x32_bf16 v[84:87], v[154:157], v[206:209], v[84:87]
	v_mfma_f32_16x16x32_bf16 v[84:87], v[158:161], v[210:213], v[84:87]
	v_mfma_f32_16x16x32_bf16 v[76:79], v[146:149], v[214:217], v[76:79]
	v_mfma_f32_16x16x32_bf16 v[76:79], v[150:153], v[218:221], v[76:79]
	v_mfma_f32_16x16x32_bf16 v[68:71], v[154:157], v[214:217], v[68:71]
	v_mfma_f32_16x16x32_bf16 v[68:71], v[158:161], v[218:221], v[68:71]
	v_mfma_f32_16x16x32_bf16 v[120:123], v[162:165], v[190:193], v[120:123]
	v_mfma_f32_16x16x32_bf16 v[120:123], v[178:181], v[194:197], v[120:123]
	v_mfma_f32_16x16x32_bf16 v[112:115], v[182:185], v[190:193], v[112:115]
	v_mfma_f32_16x16x32_bf16 v[112:115], v[186:189], v[194:197], v[112:115]
	v_mfma_f32_16x16x32_bf16 v[104:107], v[162:165], v[198:201], v[104:107]
	v_mfma_f32_16x16x32_bf16 v[104:107], v[178:181], v[202:205], v[104:107]
	v_mfma_f32_16x16x32_bf16 v[96:99], v[182:185], v[198:201], v[96:99]
	v_mfma_f32_16x16x32_bf16 v[96:99], v[186:189], v[202:205], v[96:99]
	v_mfma_f32_16x16x32_bf16 v[88:91], v[162:165], v[206:209], v[88:91]
	v_mfma_f32_16x16x32_bf16 v[88:91], v[178:181], v[210:213], v[88:91]
	v_mfma_f32_16x16x32_bf16 v[80:83], v[182:185], v[206:209], v[80:83]
	v_mfma_f32_16x16x32_bf16 v[80:83], v[186:189], v[210:213], v[80:83]
	v_mfma_f32_16x16x32_bf16 v[72:75], v[162:165], v[214:217], v[72:75]
	v_mfma_f32_16x16x32_bf16 v[72:75], v[178:181], v[218:221], v[72:75]
	s_setprio 3
	s_barrier
	v_mfma_f32_16x16x32_bf16 v[64:67], v[182:185], v[214:217], v[64:67]
	v_mfma_f32_16x16x32_bf16 v[64:67], v[186:189], v[218:221], v[64:67]
	s_setprio 0
	s_add_i32 s72, s74, s16
	v_lshl_add_u64 v[166:167], v[166:167], 0, s[10:11]
	s_mov_b32 m0, s72
	ds_read_b128 v[190:193], v176 offset:49152
	ds_read_b128 v[194:197], v176 offset:50176
	ds_read_b128 v[198:201], v176 offset:51200
	ds_read_b128 v[202:205], v176 offset:52224
	ds_read_b128 v[206:209], v176 offset:53248
	ds_read_b128 v[210:213], v176 offset:54272
	ds_read_b128 v[214:217], v176 offset:55296
	ds_read_b128 v[218:221], v176 offset:56320
	global_load_lds_dwordx4 v[166:167], off
	s_add_i32 m0, s72, 0x2000
	s_add_u32 s70, s70, 0x40080
	v_lshl_add_u64 v[166:167], v[222:223], 0, s[10:11]
	s_addc_u32 s71, s71, 0
	s_add_i32 s72, s75, s16
	global_load_lds_dwordx4 v[166:167], off
	v_lshl_add_u64 v[166:167], s[70:71], 0, v[132:133]
	s_mov_b32 m0, s72
	s_nop 0
	global_load_lds_dwordx4 v[166:167], off
	v_lshl_add_u64 v[166:167], s[70:71], 0, v[128:129]
	s_add_i32 m0, s72, 0x2000
	s_nop 0
	global_load_lds_dwordx4 v[166:167], off
	v_lshl_add_u64 v[166:167], v[224:225], 0, s[10:11]
	s_mov_b32 m0, s23
	s_nop 0
	global_load_lds_dwordx4 v[166:167], off
	v_lshl_add_u64 v[166:167], v[226:227], 0, s[10:11]
	s_mov_b32 m0, s24
	s_nop 0
	global_load_lds_dwordx4 v[166:167], off
	s_waitcnt vmcnt(8)
	s_waitcnt lgkmcnt(0)
	s_barrier
	s_setprio 1
	v_mfma_f32_16x16x32_bf16 v[60:63], v[146:149], v[190:193], v[60:63]
	v_mfma_f32_16x16x32_bf16 v[60:63], v[150:153], v[194:197], v[60:63]
	v_mfma_f32_16x16x32_bf16 v[52:55], v[154:157], v[190:193], v[52:55]
	v_mfma_f32_16x16x32_bf16 v[52:55], v[158:161], v[194:197], v[52:55]
	v_mfma_f32_16x16x32_bf16 v[44:47], v[146:149], v[198:201], v[44:47]
	v_mfma_f32_16x16x32_bf16 v[44:47], v[150:153], v[202:205], v[44:47]
	v_mfma_f32_16x16x32_bf16 v[36:39], v[154:157], v[198:201], v[36:39]
	v_mfma_f32_16x16x32_bf16 v[36:39], v[158:161], v[202:205], v[36:39]
	v_mfma_f32_16x16x32_bf16 v[28:31], v[146:149], v[206:209], v[28:31]
	v_mfma_f32_16x16x32_bf16 v[28:31], v[150:153], v[210:213], v[28:31]
	v_mfma_f32_16x16x32_bf16 v[20:23], v[154:157], v[206:209], v[20:23]
	v_mfma_f32_16x16x32_bf16 v[20:23], v[158:161], v[210:213], v[20:23]
	v_mfma_f32_16x16x32_bf16 v[12:15], v[146:149], v[214:217], v[12:15]
	v_mfma_f32_16x16x32_bf16 v[12:15], v[150:153], v[218:221], v[12:15]
	v_mfma_f32_16x16x32_bf16 v[4:7], v[154:157], v[214:217], v[4:7]
	v_mfma_f32_16x16x32_bf16 v[4:7], v[158:161], v[218:221], v[4:7]
	v_mfma_f32_16x16x32_bf16 v[56:59], v[162:165], v[190:193], v[56:59]
	v_mfma_f32_16x16x32_bf16 v[56:59], v[178:181], v[194:197], v[56:59]
	v_mfma_f32_16x16x32_bf16 v[48:51], v[182:185], v[190:193], v[48:51]
	v_mfma_f32_16x16x32_bf16 v[48:51], v[186:189], v[194:197], v[48:51]
	v_mfma_f32_16x16x32_bf16 v[40:43], v[162:165], v[198:201], v[40:43]
	v_mfma_f32_16x16x32_bf16 v[40:43], v[178:181], v[202:205], v[40:43]
	v_mfma_f32_16x16x32_bf16 v[32:35], v[182:185], v[198:201], v[32:35]
	v_mfma_f32_16x16x32_bf16 v[32:35], v[186:189], v[202:205], v[32:35]
	v_mfma_f32_16x16x32_bf16 v[24:27], v[162:165], v[206:209], v[24:27]
	v_mfma_f32_16x16x32_bf16 v[24:27], v[178:181], v[210:213], v[24:27]
	v_mfma_f32_16x16x32_bf16 v[16:19], v[182:185], v[206:209], v[16:19]
	v_mfma_f32_16x16x32_bf16 v[16:19], v[186:189], v[210:213], v[16:19]
	v_mfma_f32_16x16x32_bf16 v[8:11], v[162:165], v[214:217], v[8:11]
	v_mfma_f32_16x16x32_bf16 v[8:11], v[178:181], v[218:221], v[8:11]
	s_setprio 3
	s_barrier
	v_mfma_f32_16x16x32_bf16 v[0:3], v[182:185], v[214:217], v[0:3]
	v_mfma_f32_16x16x32_bf16 v[0:3], v[186:189], v[218:221], v[0:3]
	s_setprio 0
	s_add_i32 s69, s69, 2
	s_add_u32 s58, s58, 0x100
	s_addc_u32 s59, s59, 0
	s_add_u32 s67, s67, 0x100
	s_addc_u32 s68, s68, 0
	s_cmp_gt_u32 s69, 13
	s_cbranch_scc0 .LBB0_2192
	s_and_b64 vcc, exec, s[42:43]
	s_cbranch_vccz .LBB0_2195
	s_barrier

.LBB0_2341:
	ds_read_b128 v[128:131], v197
	ds_read_b128 v[132:135], v197 offset:1024
	ds_read_b128 v[136:139], v197 offset:2048
	ds_read_b128 v[140:143], v197 offset:3072
	ds_read_b128 v[144:147], v198
	ds_read_b128 v[148:151], v198 offset:1024
	ds_read_b128 v[152:155], v198 offset:2048
	ds_read_b128 v[156:159], v198 offset:3072
	s_add_u32 s18, s16, 0xfff50080
	s_addc_u32 s19, s17, -1
	s_cmp_eq_u32 s45, 40
	s_cselect_b32 s21, s5, s19
	s_cselect_b32 s20, s4, s18
	s_cselect_b32 s19, s15, s44
	s_cselect_b32 s18, s14, s43
	v_lshl_add_u64 v[192:193], s[16:17], 0, v[172:173]
	s_add_i32 m0, s25, 0xc000
	ds_read_b128 v[160:163], v199
	ds_read_b128 v[180:183], v199 offset:1024
	ds_read_b128 v[184:187], v199 offset:2048
	ds_read_b128 v[188:191], v199 offset:3072
	ds_read_b128 v[200:203], v199 offset:4096
	ds_read_b128 v[204:207], v199 offset:5120
	ds_read_b128 v[208:211], v199 offset:6144
	ds_read_b128 v[212:215], v199 offset:7168
	global_load_lds_dwordx4 v[192:193], off
	v_lshl_add_u64 v[192:193], s[16:17], 0, v[174:175]
	s_add_i32 m0, s25, 0xe000
	s_nop 0
	global_load_lds_dwordx4 v[192:193], off
	s_waitcnt vmcnt(8)
	s_waitcnt lgkmcnt(0)
	s_barrier
	s_setprio 1
	v_mfma_f32_16x16x32_bf16 v[124:127], v[128:131], v[160:163], v[124:127]
	v_mfma_f32_16x16x32_bf16 v[124:127], v[132:135], v[180:183], v[124:127]
	v_mfma_f32_16x16x32_bf16 v[120:123], v[136:139], v[160:163], v[120:123]
	v_mfma_f32_16x16x32_bf16 v[120:123], v[140:143], v[180:183], v[120:123]
	v_mfma_f32_16x16x32_bf16 v[108:111], v[128:131], v[184:187], v[108:111]
	v_mfma_f32_16x16x32_bf16 v[108:111], v[132:135], v[188:191], v[108:111]
	v_mfma_f32_16x16x32_bf16 v[104:107], v[136:139], v[184:187], v[104:107]
	v_mfma_f32_16x16x32_bf16 v[104:107], v[140:143], v[188:191], v[104:107]
	v_mfma_f32_16x16x32_bf16 v[96:99], v[128:131], v[200:203], v[96:99]
	v_mfma_f32_16x16x32_bf16 v[96:99], v[132:135], v[204:207], v[96:99]
	v_mfma_f32_16x16x32_bf16 v[88:91], v[136:139], v[200:203], v[88:91]
	v_mfma_f32_16x16x32_bf16 v[88:91], v[140:143], v[204:207], v[88:91]
	v_mfma_f32_16x16x32_bf16 v[80:83], v[128:131], v[208:211], v[80:83]
	v_mfma_f32_16x16x32_bf16 v[80:83], v[132:135], v[212:215], v[80:83]
	v_mfma_f32_16x16x32_bf16 v[72:75], v[136:139], v[208:211], v[72:75]
	v_mfma_f32_16x16x32_bf16 v[72:75], v[140:143], v[212:215], v[72:75]
	v_mfma_f32_16x16x32_bf16 v[116:119], v[144:147], v[160:163], v[116:119]
	v_mfma_f32_16x16x32_bf16 v[116:119], v[148:151], v[180:183], v[116:119]
	v_mfma_f32_16x16x32_bf16 v[112:115], v[152:155], v[160:163], v[112:115]
	v_mfma_f32_16x16x32_bf16 v[112:115], v[156:159], v[180:183], v[112:115]
	v_mfma_f32_16x16x32_bf16 v[100:103], v[144:147], v[184:187], v[100:103]
	v_mfma_f32_16x16x32_bf16 v[100:103], v[148:151], v[188:191], v[100:103]
	v_mfma_f32_16x16x32_bf16 v[92:95], v[152:155], v[184:187], v[92:95]
	v_mfma_f32_16x16x32_bf16 v[92:95], v[156:159], v[188:191], v[92:95]
	v_mfma_f32_16x16x32_bf16 v[84:87], v[144:147], v[200:203], v[84:87]
	v_mfma_f32_16x16x32_bf16 v[84:87], v[148:151], v[204:207], v[84:87]
	v_mfma_f32_16x16x32_bf16 v[76:79], v[152:155], v[200:203], v[76:79]
	v_mfma_f32_16x16x32_bf16 v[76:79], v[156:159], v[204:207], v[76:79]
	v_mfma_f32_16x16x32_bf16 v[68:71], v[144:147], v[208:211], v[68:71]
	v_mfma_f32_16x16x32_bf16 v[68:71], v[148:151], v[212:215], v[68:71]
	s_setprio 3
	s_barrier
	v_mfma_f32_16x16x32_bf16 v[64:67], v[152:155], v[208:211], v[64:67]
	v_mfma_f32_16x16x32_bf16 v[64:67], v[156:159], v[212:215], v[64:67]
	s_setprio 0
	s_add_i32 s46, s37, s24
	v_lshl_add_u64 v[192:193], s[18:19], 0, v[166:167]
	s_mov_b32 m0, s46
	ds_read_b128 v[160:163], v199 offset:16384
	ds_read_b128 v[180:183], v199 offset:17408
	ds_read_b128 v[184:187], v199 offset:18432
	ds_read_b128 v[188:191], v199 offset:19456
	ds_read_b128 v[200:203], v199 offset:20480
	ds_read_b128 v[204:207], v199 offset:21504
	ds_read_b128 v[208:211], v199 offset:22528
	ds_read_b128 v[212:215], v199 offset:23552
	global_load_lds_dwordx4 v[192:193], off
	s_add_i32 m0, s46, 0x2000
	s_add_u32 s46, s18, 0xb0000
	v_lshl_add_u64 v[216:217], s[18:19], 0, v[170:171]
	s_addc_u32 s47, s19, 0
	s_add_i32 s48, s38, s24
	global_load_lds_dwordx4 v[216:217], off
	v_lshl_add_u64 v[218:219], s[46:47], 0, v[166:167]
	s_mov_b32 m0, s48
	v_lshl_add_u64 v[220:221], s[20:21], 0, v[168:169]
	global_load_lds_dwordx4 v[218:219], off
	v_lshl_add_u64 v[218:219], s[46:47], 0, v[170:171]
	s_add_i32 m0, s48, 0x2000
	s_nop 0
	global_load_lds_dwordx4 v[218:219], off
	v_lshl_add_u64 v[218:219], s[20:21], 0, v[164:165]
	s_mov_b32 m0, s25
	s_nop 0
	global_load_lds_dwordx4 v[218:219], off
	s_mov_b32 m0, s26
	s_nop 0
	global_load_lds_dwordx4 v[220:221], off
	s_waitcnt vmcnt(8)
	s_waitcnt lgkmcnt(0)
	s_barrier
	s_setprio 1
	v_mfma_f32_16x16x32_bf16 v[60:63], v[128:131], v[160:163], v[60:63]
	v_mfma_f32_16x16x32_bf16 v[60:63], v[132:135], v[180:183], v[60:63]
	v_mfma_f32_16x16x32_bf16 v[56:59], v[136:139], v[160:163], v[56:59]
	v_mfma_f32_16x16x32_bf16 v[56:59], v[140:143], v[180:183], v[56:59]
	v_mfma_f32_16x16x32_bf16 v[48:51], v[128:131], v[184:187], v[48:51]
	v_mfma_f32_16x16x32_bf16 v[48:51], v[132:135], v[188:191], v[48:51]
	v_mfma_f32_16x16x32_bf16 v[40:43], v[136:139], v[184:187], v[40:43]
	v_mfma_f32_16x16x32_bf16 v[40:43], v[140:143], v[188:191], v[40:43]
	v_mfma_f32_16x16x32_bf16 v[32:35], v[128:131], v[200:203], v[32:35]
	v_mfma_f32_16x16x32_bf16 v[32:35], v[132:135], v[204:207], v[32:35]
	v_mfma_f32_16x16x32_bf16 v[24:27], v[136:139], v[200:203], v[24:27]
	v_mfma_f32_16x16x32_bf16 v[24:27], v[140:143], v[204:207], v[24:27]
	v_mfma_f32_16x16x32_bf16 v[16:19], v[128:131], v[208:211], v[16:19]
	v_mfma_f32_16x16x32_bf16 v[16:19], v[132:135], v[212:215], v[16:19]
	v_mfma_f32_16x16x32_bf16 v[8:11], v[136:139], v[208:211], v[8:11]
	v_mfma_f32_16x16x32_bf16 v[8:11], v[140:143], v[212:215], v[8:11]
	v_mfma_f32_16x16x32_bf16 v[52:55], v[144:147], v[160:163], v[52:55]
	v_mfma_f32_16x16x32_bf16 v[52:55], v[148:151], v[180:183], v[52:55]
	v_mfma_f32_16x16x32_bf16 v[44:47], v[152:155], v[160:163], v[44:47]
	v_mfma_f32_16x16x32_bf16 v[44:47], v[156:159], v[180:183], v[44:47]
	v_mfma_f32_16x16x32_bf16 v[36:39], v[144:147], v[184:187], v[36:39]
	v_mfma_f32_16x16x32_bf16 v[36:39], v[148:151], v[188:191], v[36:39]
	v_mfma_f32_16x16x32_bf16 v[28:31], v[152:155], v[184:187], v[28:31]
	v_mfma_f32_16x16x32_bf16 v[28:31], v[156:159], v[188:191], v[28:31]
	v_mfma_f32_16x16x32_bf16 v[20:23], v[144:147], v[200:203], v[20:23]
	v_mfma_f32_16x16x32_bf16 v[20:23], v[148:151], v[204:207], v[20:23]
	v_mfma_f32_16x16x32_bf16 v[12:15], v[152:155], v[200:203], v[12:15]
	v_mfma_f32_16x16x32_bf16 v[12:15], v[156:159], v[204:207], v[12:15]
	v_mfma_f32_16x16x32_bf16 v[4:7], v[144:147], v[208:211], v[4:7]
	v_mfma_f32_16x16x32_bf16 v[4:7], v[148:151], v[212:215], v[4:7]
	s_setprio 3
	s_barrier
	v_mfma_f32_16x16x32_bf16 v[0:3], v[152:155], v[208:211], v[0:3]
	v_mfma_f32_16x16x32_bf16 v[0:3], v[156:159], v[212:215], v[0:3]
	s_setprio 0
	s_add_i32 s46, 0, 0x18000
	s_add_i32 s47, 0, 0x1c000
	v_add_u32_e32 v140, s46, v195
	v_add_u32_e32 v156, s47, v195
	ds_read_b128 v[128:131], v140
	ds_read_b128 v[132:135], v140 offset:1024
	ds_read_b128 v[136:139], v140 offset:2048
	ds_read_b128 v[140:143], v140 offset:3072
	ds_read_b128 v[144:147], v156
	ds_read_b128 v[148:151], v156 offset:1024
	ds_read_b128 v[152:155], v156 offset:2048
	ds_read_b128 v[156:159], v156 offset:3072
	s_add_u32 s20, s20, 0xb0000
	s_addc_u32 s21, s21, 0
	s_mov_b32 m0, s27
	v_lshl_add_u64 v[222:223], s[20:21], 0, v[164:165]
	ds_read_b128 v[160:163], v199 offset:32768
	ds_read_b128 v[180:183], v199 offset:33792
	ds_read_b128 v[184:187], v199 offset:34816
	ds_read_b128 v[188:191], v199 offset:35840
	ds_read_b128 v[200:203], v199 offset:36864
	ds_read_b128 v[204:207], v199 offset:37888
	ds_read_b128 v[208:211], v199 offset:38912
	ds_read_b128 v[212:215], v199 offset:39936
	global_load_lds_dwordx4 v[222:223], off
	v_lshl_add_u64 v[222:223], s[20:21], 0, v[168:169]
	s_mov_b32 m0, s28
	s_nop 0
	global_load_lds_dwordx4 v[222:223], off
	s_waitcnt vmcnt(8)
	s_waitcnt lgkmcnt(0)
	s_barrier
	s_setprio 1
	v_mfma_f32_16x16x32_bf16 v[124:127], v[128:131], v[160:163], v[124:127]
	v_mfma_f32_16x16x32_bf16 v[124:127], v[132:135], v[180:183], v[124:127]
	v_mfma_f32_16x16x32_bf16 v[120:123], v[136:139], v[160:163], v[120:123]
	v_mfma_f32_16x16x32_bf16 v[120:123], v[140:143], v[180:183], v[120:123]
	v_mfma_f32_16x16x32_bf16 v[108:111], v[128:131], v[184:187], v[108:111]
	v_mfma_f32_16x16x32_bf16 v[108:111], v[132:135], v[188:191], v[108:111]
	v_mfma_f32_16x16x32_bf16 v[104:107], v[136:139], v[184:187], v[104:107]
	v_mfma_f32_16x16x32_bf16 v[104:107], v[140:143], v[188:191], v[104:107]
	v_mfma_f32_16x16x32_bf16 v[96:99], v[128:131], v[200:203], v[96:99]
	v_mfma_f32_16x16x32_bf16 v[96:99], v[132:135], v[204:207], v[96:99]
	v_mfma_f32_16x16x32_bf16 v[88:91], v[136:139], v[200:203], v[88:91]
	v_mfma_f32_16x16x32_bf16 v[88:91], v[140:143], v[204:207], v[88:91]
	v_mfma_f32_16x16x32_bf16 v[80:83], v[128:131], v[208:211], v[80:83]
	v_mfma_f32_16x16x32_bf16 v[80:83], v[132:135], v[212:215], v[80:83]
	v_mfma_f32_16x16x32_bf16 v[72:75], v[136:139], v[208:211], v[72:75]
	v_mfma_f32_16x16x32_bf16 v[72:75], v[140:143], v[212:215], v[72:75]
	v_mfma_f32_16x16x32_bf16 v[116:119], v[144:147], v[160:163], v[116:119]
	v_mfma_f32_16x16x32_bf16 v[116:119], v[148:151], v[180:183], v[116:119]
	v_mfma_f32_16x16x32_bf16 v[112:115], v[152:155], v[160:163], v[112:115]
	v_mfma_f32_16x16x32_bf16 v[112:115], v[156:159], v[180:183], v[112:115]
	v_mfma_f32_16x16x32_bf16 v[100:103], v[144:147], v[184:187], v[100:103]
	v_mfma_f32_16x16x32_bf16 v[100:103], v[148:151], v[188:191], v[100:103]
	v_mfma_f32_16x16x32_bf16 v[92:95], v[152:155], v[184:187], v[92:95]
	v_mfma_f32_16x16x32_bf16 v[92:95], v[156:159], v[188:191], v[92:95]
	v_mfma_f32_16x16x32_bf16 v[84:87], v[144:147], v[200:203], v[84:87]
	v_mfma_f32_16x16x32_bf16 v[84:87], v[148:151], v[204:207], v[84:87]
	v_mfma_f32_16x16x32_bf16 v[76:79], v[152:155], v[200:203], v[76:79]
	v_mfma_f32_16x16x32_bf16 v[76:79], v[156:159], v[204:207], v[76:79]
	v_mfma_f32_16x16x32_bf16 v[68:71], v[144:147], v[208:211], v[68:71]
	v_mfma_f32_16x16x32_bf16 v[68:71], v[148:151], v[212:215], v[68:71]
	s_setprio 3
	s_barrier
	v_mfma_f32_16x16x32_bf16 v[64:67], v[152:155], v[208:211], v[64:67]
	v_mfma_f32_16x16x32_bf16 v[64:67], v[156:159], v[212:215], v[64:67]
	s_setprio 0
	s_add_i32 s20, s46, s24
	v_lshl_add_u64 v[192:193], v[192:193], 0, s[8:9]
	s_mov_b32 m0, s20
	ds_read_b128 v[160:163], v199 offset:49152
	ds_read_b128 v[180:183], v199 offset:50176
	ds_read_b128 v[184:187], v199 offset:51200
	ds_read_b128 v[188:191], v199 offset:52224
	ds_read_b128 v[200:203], v199 offset:53248
	ds_read_b128 v[204:207], v199 offset:54272
	ds_read_b128 v[208:211], v199 offset:55296
	ds_read_b128 v[212:215], v199 offset:56320
	global_load_lds_dwordx4 v[192:193], off
	s_add_i32 m0, s20, 0x2000
	s_add_u32 s18, s18, 0xb0080
	v_lshl_add_u64 v[192:193], v[216:217], 0, s[8:9]
	s_addc_u32 s19, s19, 0
	s_add_i32 s20, s47, s24
	global_load_lds_dwordx4 v[192:193], off
	v_lshl_add_u64 v[192:193], s[18:19], 0, v[166:167]
	s_mov_b32 m0, s20
	s_nop 0
	global_load_lds_dwordx4 v[192:193], off
	v_lshl_add_u64 v[192:193], s[18:19], 0, v[170:171]
	s_add_i32 m0, s20, 0x2000
	s_nop 0
	global_load_lds_dwordx4 v[192:193], off
	v_lshl_add_u64 v[192:193], v[218:219], 0, s[8:9]
	s_mov_b32 m0, s33
	s_nop 0
	global_load_lds_dwordx4 v[192:193], off
	v_lshl_add_u64 v[192:193], v[220:221], 0, s[8:9]
	s_mov_b32 m0, s35
	s_nop 0
	global_load_lds_dwordx4 v[192:193], off
	s_waitcnt vmcnt(8)
	s_waitcnt lgkmcnt(0)
	s_barrier
	s_setprio 1
	v_mfma_f32_16x16x32_bf16 v[60:63], v[128:131], v[160:163], v[60:63]
	v_mfma_f32_16x16x32_bf16 v[60:63], v[132:135], v[180:183], v[60:63]
	v_mfma_f32_16x16x32_bf16 v[56:59], v[136:139], v[160:163], v[56:59]
	v_mfma_f32_16x16x32_bf16 v[56:59], v[140:143], v[180:183], v[56:59]
	v_mfma_f32_16x16x32_bf16 v[48:51], v[128:131], v[184:187], v[48:51]
	v_mfma_f32_16x16x32_bf16 v[48:51], v[132:135], v[188:191], v[48:51]
	v_mfma_f32_16x16x32_bf16 v[40:43], v[136:139], v[184:187], v[40:43]
	v_mfma_f32_16x16x32_bf16 v[40:43], v[140:143], v[188:191], v[40:43]
	v_mfma_f32_16x16x32_bf16 v[32:35], v[128:131], v[200:203], v[32:35]
	v_mfma_f32_16x16x32_bf16 v[32:35], v[132:135], v[204:207], v[32:35]
	v_mfma_f32_16x16x32_bf16 v[24:27], v[136:139], v[200:203], v[24:27]
	v_mfma_f32_16x16x32_bf16 v[24:27], v[140:143], v[204:207], v[24:27]
	v_mfma_f32_16x16x32_bf16 v[16:19], v[128:131], v[208:211], v[16:19]
	v_mfma_f32_16x16x32_bf16 v[16:19], v[132:135], v[212:215], v[16:19]
	v_mfma_f32_16x16x32_bf16 v[8:11], v[136:139], v[208:211], v[8:11]
	v_mfma_f32_16x16x32_bf16 v[8:11], v[140:143], v[212:215], v[8:11]
	v_mfma_f32_16x16x32_bf16 v[52:55], v[144:147], v[160:163], v[52:55]
	v_mfma_f32_16x16x32_bf16 v[52:55], v[148:151], v[180:183], v[52:55]
	v_mfma_f32_16x16x32_bf16 v[44:47], v[152:155], v[160:163], v[44:47]
	v_mfma_f32_16x16x32_bf16 v[44:47], v[156:159], v[180:183], v[44:47]
	v_mfma_f32_16x16x32_bf16 v[36:39], v[144:147], v[184:187], v[36:39]
	v_mfma_f32_16x16x32_bf16 v[36:39], v[148:151], v[188:191], v[36:39]
	v_mfma_f32_16x16x32_bf16 v[28:31], v[152:155], v[184:187], v[28:31]
	v_mfma_f32_16x16x32_bf16 v[28:31], v[156:159], v[188:191], v[28:31]
	v_mfma_f32_16x16x32_bf16 v[20:23], v[144:147], v[200:203], v[20:23]
	v_mfma_f32_16x16x32_bf16 v[20:23], v[148:151], v[204:207], v[20:23]
	v_mfma_f32_16x16x32_bf16 v[12:15], v[152:155], v[200:203], v[12:15]
	v_mfma_f32_16x16x32_bf16 v[12:15], v[156:159], v[204:207], v[12:15]
	v_mfma_f32_16x16x32_bf16 v[4:7], v[144:147], v[208:211], v[4:7]
	v_mfma_f32_16x16x32_bf16 v[4:7], v[148:151], v[212:215], v[4:7]
	s_setprio 3
	s_barrier
	v_mfma_f32_16x16x32_bf16 v[0:3], v[152:155], v[208:211], v[0:3]
	v_mfma_f32_16x16x32_bf16 v[0:3], v[156:159], v[212:215], v[0:3]
	s_setprio 0
	s_add_i32 s45, s45, 2
	s_add_u32 s16, s16, 0x100
	s_addc_u32 s17, s17, 0
	s_add_u32 s43, s43, 0x100
	s_addc_u32 s44, s44, 0
	s_cmp_gt_u32 s45, 41
	s_cbranch_scc0 .LBB0_2341
	s_and_b64 vcc, exec, s[10:11]
	s_cbranch_vccz .LBB0_2344
	s_barrier
